# rec_in / att_in / glu GEMM cores switched to the 8-phase ping-pong K-loop (32x32x16 MFMA, same epilogues; buffer-1 B pieces held back over the epilogue staging)
# speedup vs baseline: 1.0425x; 1.0058x over previous
; DI f32x16 zero16() { f32x16 z; for (int i = 0; i < 16; ++i) z[i] = 0.f; return z; }
; DI int opqv(int x) { asm volatile("" : "+v"(x)); return x; }
;   const int tid = opqv(threadIdx.x), lane = tid & 63, w = tid >> 6, wm = w >> 2, wn = w & 3, l32 = lane & 31, hf = lane >> 5;
;   f32x16 acc[2][2][2];
; #pragma unroll
;   for (int h = 0; h < 2; ++h)
; #pragma unroll
;     for (int i = 0; i < 2; ++i)
; #pragma unroll
;       for (int j = 0; j < 2; ++j) acc[h][i][j] = zero16();
;   const int nk = nk1 + nk2;
;   const int drow = lane >> 3, dslot = lane & 7, x7 = (l32 >> 1) & 7;
; DI void att_in_phase(const Params& p, int j, char* smem) {
;     ...
;   for (int lt = blockIdx.x >> 3; lt < 16 * nN; lt += gridDim.x >> 3) {
;     int mt, nt; tile_map(lt, 16, nN, 16, 2, mt, nt);
;     const int m0 = mt * 256, n0 = nt * 256;
;     gemm_tile(A + (size_t)m0 * LDH, LDH, 16, nullptr, 0, 0, Wt + (size_t)n0 * LDW1, LDW1, smem, [&](f32x16(&acc)[2][2], int moff) {
.LBB0_649:
	v_readlane_b32 s4, v251, 54
	v_readlane_b32 s0, v251, 13
	v_readlane_b32 s5, v251, 55
	v_mov_b32_e32 v0, v182
	v_readlane_b32 s1, v251, 14
	s_andn2_b64 vcc, exec, s[4:5]
	s_cbranch_vccnz .LBB0_709
	s_mov_b64 s[70:71], s[62:63]
	v_readlane_b32 s28, v253, 48
	v_readlane_b32 s30, v253, 50
	s_cmp_ge_u32 s28, 0x60
	s_cbranch_scc1 .LBB0_708
	s_add_u32 s4, s0, 0x8c04100
	s_addc_u32 s5, s1, 0
	v_readlane_b32 s6, v254, 25
	v_readlane_b32 s31, v251, 0
	s_mul_i32 s6, s6, 0x330000
	s_add_u32 s6, s0, s6
	s_addc_u32 s7, s1, 0
	s_add_u32 s6, s6, 0x10c4100
	s_addc_u32 s7, s7, 0
	s_and_b32 s31, s31, 7
	s_lshl_b32 s31, s31, 4
	s_lshr_b32 s8, s28, 1
	s_add_u32 s31, s31, s8
	s_mul_i32 s8, s31, 0x88000
	s_add_u32 s34, s4, s8
	s_addc_u32 s35, s5, 0
	v_lshrrev_b32_e32 v228, 6, v182
	v_and_b32_e32 v229, 63, v182
	v_readfirstlane_b32 s15, v228
	v_and_b32_e32 v230, 31, v229
	v_lshrrev_b32_e32 v231, 5, v229
	v_lshrrev_b32_e32 v232, 3, v229
	v_and_b32_e32 v233, 7, v229
	s_lshr_b32 s8, s15, 2
	s_lshl_b32 s8, s8, 7
	s_and_b32 s9, s15, 3
	s_lshl_b32 s9, s9, 4
	s_add_u32 s10, s8, s9
	v_lshrrev_b32_e32 v234, 1, v232
	v_xor_b32_e32 v234, v233, v234
	v_lshlrev_b32_e32 v234, 4, v234
	s_add_u32 s11, s10, 0
	v_add_u32_e32 v235, s11, v232
	s_movk_i32 s11, 0x880
	v_mad_u32_u24 v220, v235, s11, v234
	v_lshrrev_b32_e32 v234, 1, v232
	v_add_u32_e32 v234, 4, v234
	v_xor_b32_e32 v234, v233, v234
	v_lshlrev_b32_e32 v234, 4, v234
	s_add_u32 s11, s10, 8
	v_add_u32_e32 v235, s11, v232
	s_movk_i32 s11, 0x880
	v_mad_u32_u24 v221, v235, s11, v234
	v_lshrrev_b32_e32 v234, 1, v232
	v_xor_b32_e32 v234, v233, v234
	v_lshlrev_b32_e32 v234, 4, v234
	s_add_u32 s11, s10, 64
	v_add_u32_e32 v235, s11, v232
	s_movk_i32 s11, 0x880
	v_mad_u32_u24 v222, v235, s11, v234
	v_lshrrev_b32_e32 v234, 1, v232
	v_add_u32_e32 v234, 4, v234
	v_xor_b32_e32 v234, v233, v234
	v_lshlrev_b32_e32 v234, 4, v234
	s_add_u32 s11, s10, 72
	v_add_u32_e32 v235, s11, v232
	s_movk_i32 s11, 0x880
	v_mad_u32_u24 v223, v235, s11, v234
	v_and_b32_e32 v244, 63, v182
	v_lshrrev_b32_e32 v245, 3, v244
	v_and_b32_e32 v246, 7, v244
	s_lshr_b32 s8, s15, 2
	s_lshl_b32 s8, s8, 1
	s_bfe_u32 s9, s15, 0x10001
	s_add_u32 s8, s8, s9
	s_lshl_b32 s8, s8, 6
	s_and_b32 s9, s15, 1
	s_lshl_b32 s9, s9, 4
	s_add_u32 s8, s8, s9
	v_lshrrev_b32_e32 v247, 1, v245
	v_xor_b32_e32 v247, v246, v247
	v_lshlrev_b32_e32 v247, 4, v247
	s_add_u32 s9, s8, 0
	v_add_u32_e32 v244, s9, v245
	s_movk_i32 s9, 0x880
	v_mad_u32_u24 v240, v244, s9, v247
	v_lshrrev_b32_e32 v247, 1, v245
	v_add_u32_e32 v247, 4, v247
	v_xor_b32_e32 v247, v246, v247
	v_lshlrev_b32_e32 v247, 4, v247
	s_add_u32 s9, s8, 8
	v_add_u32_e32 v244, s9, v245
	s_movk_i32 s9, 0x880
	v_mad_u32_u24 v241, v244, s9, v247
	v_lshrrev_b32_e32 v247, 1, v245
	v_xor_b32_e32 v247, v246, v247
	v_lshlrev_b32_e32 v247, 4, v247
	s_add_u32 s9, s8, 32
	v_add_u32_e32 v244, s9, v245
	s_movk_i32 s9, 0x880
	v_mad_u32_u24 v242, v244, s9, v247
	v_lshrrev_b32_e32 v247, 1, v245
	v_add_u32_e32 v247, 4, v247
	v_xor_b32_e32 v247, v246, v247
	v_lshlrev_b32_e32 v247, 4, v247
	s_add_u32 s9, s8, 40
	v_add_u32_e32 v244, s9, v245
	s_movk_i32 s9, 0x880
	v_mad_u32_u24 v243, v244, s9, v247
	v_lshrrev_b32_e32 v236, 1, v230
	v_and_b32_e32 v236, 7, v236
	s_lshr_b32 s8, s15, 2
	s_and_b32 s9, s15, 3
	s_lshl_b32 s10, s8, 14
	s_add_u32 s10, s10, 32
	s_lshr_b32 s11, s9, 1
	s_lshl_b32 s11, s11, 14
	s_add_u32 s11, s11, 0x8020
	v_lshlrev_b32_e32 v237, 7, v230
	v_add_u32_e32 v238, s11, v237
	s_and_b32 s11, s9, 1
	s_lshl_b32 s11, s11, 12
	v_add_u32_e32 v238, s11, v238
	v_add_u32_e32 v237, s10, v237
	v_add_u32_e32 v239, 0, v231
	v_xor_b32_e32 v239, v239, v236
	v_lshlrev_b32_e32 v239, 4, v239
	v_add_u32_e32 v204, v237, v239
	v_add_u32_e32 v212, v238, v239
	v_add_u32_e32 v208, 0x10000, v204
	v_add_u32_e32 v216, 0x10000, v212
	v_add_u32_e32 v239, 2, v231
	v_xor_b32_e32 v239, v239, v236
	v_lshlrev_b32_e32 v239, 4, v239
	v_add_u32_e32 v205, v237, v239
	v_add_u32_e32 v213, v238, v239
	v_add_u32_e32 v209, 0x10000, v205
	v_add_u32_e32 v217, 0x10000, v213
	v_add_u32_e32 v239, 4, v231
	v_xor_b32_e32 v239, v239, v236
	v_lshlrev_b32_e32 v239, 4, v239
	v_add_u32_e32 v206, v237, v239
	v_add_u32_e32 v214, v238, v239
	v_add_u32_e32 v210, 0x10000, v206
	v_add_u32_e32 v218, 0x10000, v214
	v_add_u32_e32 v239, 6, v231
	v_xor_b32_e32 v239, v239, v236
	v_lshlrev_b32_e32 v239, 4, v239
	v_add_u32_e32 v207, v237, v239
	v_add_u32_e32 v215, v238, v239
	v_add_u32_e32 v211, 0x10000, v207
	v_add_u32_e32 v219, 0x10000, v215
	s_lshl_b32 s10, s15, 12
	s_add_u32 s10, s10, 0x18020
	v_lshlrev_b32_e32 v234, 7, v230
	v_lshlrev_b32_e32 v235, 3, v231
	v_add3_u32 v234, v234, v235, s10
	v_and_b32_e32 v235, 7, v230
	v_mov_b32_e32 v178, v235
	v_xor_b32_e32 v179, 1, v235
	v_xor_b32_e32 v180, 2, v235
	v_xor_b32_e32 v181, 3, v235
	v_xor_b32_e32 v188, 4, v235
	v_xor_b32_e32 v189, 5, v235
	v_xor_b32_e32 v190, 6, v235
	v_xor_b32_e32 v191, 7, v235
	v_lshl_add_u32 v178, v178, 4, v234
	v_lshl_add_u32 v179, v179, 4, v234
	v_lshl_add_u32 v180, v180, 4, v234
	v_lshl_add_u32 v181, v181, 4, v234
	v_lshl_add_u32 v188, v188, 4, v234
	v_lshl_add_u32 v189, v189, 4, v234
	v_lshl_add_u32 v190, v190, 4, v234
	v_lshl_add_u32 v191, v191, 4, v234
	v_xor_b32_e32 v194, v232, v233
	v_lshlrev_b32_e32 v194, 4, v194
	v_lshl_add_u32 v194, v232, 7, v194
	v_add_u32_e32 v194, s10, v194
	s_lshl_b32 s14, s8, 14
	s_lshl_b32 s10, s9, 11
	s_add_u32 s14, s14, s10
	s_add_u32 s14, s14, 32
	s_lshl_b32 s12, s8, 7
	s_mov_b32 s13, s9
	v_lshlrev_b32_e32 v195, 4, v233
	s_movk_i32 s10, 0x500
	v_mad_u32_u24 v195, v232, s10, v195
	v_lshlrev_b32_e32 v196, 4, v233
	s_movk_i32 s10, 0x400
	v_mad_u32_u24 v196, v232, s10, v196
	v_lshlrev_b32_e32 v197, 4, v233
	s_movk_i32 s10, 0x100
	v_mad_u32_u24 v197, v232, s10, v197
	v_lshlrev_b32_e32 v160, 8, v230
	v_lshl_add_u32 v160, v231, 5, v160
	s_lshl_b32 s10, s31, 8
	s_add_u32 s10, s10, s12
	s_mov_b32 s52, s10
	s_and_b32 s10, s10, 0x3fff
	s_mov_b32 s53, s10
	s_lshl_b32 s10, s10, 8
	s_add_u32 s36, s0, s10
	s_addc_u32 s37, s1, 0
	s_add_u32 s36, s36, 0x234100
	s_addc_u32 s37, s37, 0
	s_mov_b32 s27, s28
	s_mov_b32 s26, 0
	s_lshr_b32 s8, s27, 5
	s_lshl_b32 s8, s8, 1
	s_and_b32 s9, s27, 1
	s_add_u32 s8, s8, s9
	s_mul_i32 s8, s8, 0x88000
	s_add_u32 s24, s6, s8
	s_addc_u32 s25, s7, 0
	s_mov_b64 s[22:23], s[34:35]
	s_add_u32 m0, s14, 0x8000
	s_nop 0
	global_load_lds_dwordx4 v240, s[24:25]
	s_add_u32 m0, s14, 0x8400
	s_nop 0
	global_load_lds_dwordx4 v241, s[24:25]
	s_add_u32 m0, s14, 0x0
	s_nop 0
	global_load_lds_dwordx4 v220, s[22:23]
	s_add_u32 m0, s14, 0x400
	s_nop 0
	global_load_lds_dwordx4 v221, s[22:23]
	s_add_u32 m0, s14, 0xa000
	s_nop 0
	global_load_lds_dwordx4 v242, s[24:25]
	s_add_u32 m0, s14, 0xa400
	s_nop 0
	global_load_lds_dwordx4 v243, s[24:25]
	s_add_u32 m0, s14, 0x2000
	s_nop 0
	global_load_lds_dwordx4 v222, s[22:23]
	s_add_u32 m0, s14, 0x2400
	s_nop 0
	global_load_lds_dwordx4 v223, s[22:23]
	s_add_u32 s22, s22, 0x80
	s_addc_u32 s23, s23, 0
	s_add_u32 s24, s24, 0x80
	s_addc_u32 s25, s25, 0
	s_add_u32 s26, s26, 1
	s_cmp_eq_u32 s26, 16
	s_cbranch_scc0 .Lai1_cadv_done
; #define RAWBAR() { asm volatile("s_waitcnt vmcnt(0) lgkmcnt(0)" ::: "memory"); __builtin_amdgcn_s_barrier(); }
;     ...
;   if (V != 1) GLDS(0, 0);
;   RAWBAR();
;   for (int kt = 0; kt < nk; kt += 2) {
;     if (V != 1) GLDS(kt + 1, 1);
	s_mov_b32 s26, 0
	s_add_u32 s27, s27, s30
	s_cmp_lt_u32 s27, 0x60
	s_cbranch_scc1 .Lai1_cadv_new
	s_sub_u32 s22, s22, 0x800
	s_subb_u32 s23, s23, 0
	s_sub_u32 s24, s24, 0x800
	s_subb_u32 s25, s25, 0
	s_branch .Lai1_cadv_done
.Lai1_cadv_new:
	s_lshr_b32 s8, s27, 5
	s_lshl_b32 s8, s8, 1
	s_and_b32 s9, s27, 1
	s_add_u32 s8, s8, s9
	s_mul_i32 s8, s8, 0x88000
	s_add_u32 s24, s6, s8
	s_addc_u32 s25, s7, 0
	s_mov_b64 s[22:23], s[34:35]
.Lai1_cadv_done:
	s_cmp_lt_u32 s15, 4
	s_cbranch_scc1 .Lai_pp_lead
	s_barrier
.Lai_pp_lead:
	s_waitcnt vmcnt(4)
	s_barrier
	s_add_u32 m0, s14, 0x10000
	s_nop 0
	global_load_lds_dwordx4 v220, s[22:23]
	s_add_u32 m0, s14, 0x10400
	s_nop 0
	global_load_lds_dwordx4 v221, s[22:23]
	s_waitcnt vmcnt(2)
	s_barrier
.Lai_tile:
	v_and_b32_e32 v244, 63, v182
	v_lshrrev_b32_e32 v245, 3, v244
	v_and_b32_e32 v246, 7, v244
	s_lshr_b32 s8, s15, 2
	s_lshl_b32 s8, s8, 1
	s_bfe_u32 s9, s15, 0x10001
	s_add_u32 s8, s8, s9
	s_lshl_b32 s8, s8, 6
	s_and_b32 s9, s15, 1
	s_lshl_b32 s9, s9, 4
	s_add_u32 s8, s8, s9
	v_lshrrev_b32_e32 v247, 1, v245
	v_xor_b32_e32 v247, v246, v247
	v_lshlrev_b32_e32 v247, 4, v247
	s_add_u32 s9, s8, 0
	v_add_u32_e32 v244, s9, v245
	s_movk_i32 s9, 0x880
	v_mad_u32_u24 v240, v244, s9, v247
	v_lshrrev_b32_e32 v247, 1, v245
	v_add_u32_e32 v247, 4, v247
	v_xor_b32_e32 v247, v246, v247
	v_lshlrev_b32_e32 v247, 4, v247
	s_add_u32 s9, s8, 8
	v_add_u32_e32 v244, s9, v245
	s_movk_i32 s9, 0x880
	v_mad_u32_u24 v241, v244, s9, v247
	v_lshrrev_b32_e32 v247, 1, v245
	v_xor_b32_e32 v247, v246, v247
	v_lshlrev_b32_e32 v247, 4, v247
	s_add_u32 s9, s8, 32
	v_add_u32_e32 v244, s9, v245
	s_movk_i32 s9, 0x880
	v_mad_u32_u24 v242, v244, s9, v247
	v_lshrrev_b32_e32 v247, 1, v245
	v_add_u32_e32 v247, 4, v247
	v_xor_b32_e32 v247, v246, v247
	v_lshlrev_b32_e32 v247, 4, v247
	s_add_u32 s9, s8, 40
	v_add_u32_e32 v244, s9, v245
	s_movk_i32 s9, 0x880
	v_mad_u32_u24 v243, v244, s9, v247
	s_add_u32 m0, s14, 0x12000
	ds_read_b128 v[162:165], v212
	ds_read_b128 v[166:169], v213
	ds_read_b128 v[170:173], v214
	ds_read_b128 v[174:177], v215
	global_load_lds_dwordx4 v222, s[22:23]
	s_add_u32 m0, s14, 0x12400
	ds_read_b128 v[128:131], v204
	ds_read_b128 v[132:135], v205
	ds_read_b128 v[136:139], v206
	ds_read_b128 v[140:143], v207
	global_load_lds_dwordx4 v223, s[22:23]
	ds_read_b128 v[144:147], v204 offset:4096
	ds_read_b128 v[148:151], v205 offset:4096
	ds_read_b128 v[152:155], v206 offset:4096
	ds_read_b128 v[156:159], v207 offset:4096
	s_add_u32 s22, s22, 0x80
	s_addc_u32 s23, s23, 0
	s_add_u32 s24, s24, 0x80
	s_addc_u32 s25, s25, 0
	s_add_u32 s26, s26, 1
	s_cmp_eq_u32 s26, 16
	s_cbranch_scc0 .Lai2_cadv_done
	s_mov_b32 s26, 0
	s_add_u32 s27, s27, s30
	s_cmp_lt_u32 s27, 0x60
	s_cbranch_scc1 .Lai2_cadv_new
	s_sub_u32 s22, s22, 0x800
	s_subb_u32 s23, s23, 0
	s_sub_u32 s24, s24, 0x800
	s_subb_u32 s25, s25, 0
	s_branch .Lai2_cadv_done

; #define RAWBAR() { asm volatile("s_waitcnt vmcnt(0) lgkmcnt(0)" ::: "memory"); __builtin_amdgcn_s_barrier(); }
;     ...
;   for (int kt = 0; kt < nk; kt += 2) {
;     if (V != 1) GLDS(kt + 1, 1);
;     if (V != 2) COMPUTE(0);
;     RAWBAR();
;     if (V != 1) if (kt + 2 < nk) GLDS(kt + 2, 0);
;     if (V != 2) COMPUTE(1);
;     RAWBAR();
.Lai2_cadv_done:
	s_waitcnt lgkmcnt(8)
	s_barrier
	s_waitcnt lgkmcnt(0)
	s_setprio 1
	v_mfma_f32_32x32x16_bf16 v[0:15], v[162:165], v[128:131], 0
	v_mfma_f32_32x32x16_bf16 v[32:47], v[162:165], v[144:147], 0
	v_mfma_f32_32x32x16_bf16 v[0:15], v[166:169], v[132:135], v[0:15]
	v_mfma_f32_32x32x16_bf16 v[32:47], v[166:169], v[148:151], v[32:47]
	v_mfma_f32_32x32x16_bf16 v[0:15], v[170:173], v[136:139], v[0:15]
	v_mfma_f32_32x32x16_bf16 v[32:47], v[170:173], v[152:155], v[32:47]
	v_mfma_f32_32x32x16_bf16 v[0:15], v[174:177], v[140:143], v[0:15]
	v_mfma_f32_32x32x16_bf16 v[32:47], v[174:177], v[156:159], v[32:47]
	s_setprio 0
	s_barrier
	s_add_u32 m0, s14, 0x18080
	ds_read_b128 v[224:227], v212 offset:8192
	global_load_lds_dwordx4 v240, s[24:25] offset:-128
	s_add_u32 m0, s14, 0x18480
	ds_read_b128 v[228:231], v213 offset:8192
	global_load_lds_dwordx4 v241, s[24:25] offset:-128
	s_add_u32 m0, s14, 0x1a080
	ds_read_b128 v[232:235], v214 offset:8192
	global_load_lds_dwordx4 v242, s[24:25] offset:-128
	s_add_u32 m0, s14, 0x1a480
	ds_read_b128 v[236:239], v215 offset:8192
	global_load_lds_dwordx4 v243, s[24:25] offset:-128
	s_add_u32 m0, s14, 0x8000
	s_nop 0
	global_load_lds_dwordx4 v240, s[24:25]
	s_add_u32 m0, s14, 0x8400
	s_nop 0
	global_load_lds_dwordx4 v241, s[24:25]
	s_barrier
	s_waitcnt lgkmcnt(0)
	s_setprio 1
	v_mfma_f32_32x32x16_bf16 v[16:31], v[224:227], v[128:131], 0
	v_mfma_f32_32x32x16_bf16 v[48:63], v[224:227], v[144:147], 0
	v_mfma_f32_32x32x16_bf16 v[16:31], v[228:231], v[132:135], v[16:31]
	v_mfma_f32_32x32x16_bf16 v[48:63], v[228:231], v[148:151], v[48:63]
	v_mfma_f32_32x32x16_bf16 v[16:31], v[232:235], v[136:139], v[16:31]
	v_mfma_f32_32x32x16_bf16 v[48:63], v[232:235], v[152:155], v[48:63]
	v_mfma_f32_32x32x16_bf16 v[16:31], v[236:239], v[140:143], v[16:31]
	v_mfma_f32_32x32x16_bf16 v[48:63], v[236:239], v[156:159], v[48:63]
	s_setprio 0
	s_barrier
	s_add_u32 m0, s14, 0x0
	ds_read_b128 v[128:131], v204 offset:8192
	ds_read_b128 v[132:135], v205 offset:8192
	global_load_lds_dwordx4 v220, s[22:23]
	s_add_u32 m0, s14, 0x400
	ds_read_b128 v[136:139], v206 offset:8192
	ds_read_b128 v[140:143], v207 offset:8192
	global_load_lds_dwordx4 v221, s[22:23]
	ds_read_b128 v[144:147], v204 offset:12288
	ds_read_b128 v[148:151], v205 offset:12288
	ds_read_b128 v[152:155], v206 offset:12288
	ds_read_b128 v[156:159], v207 offset:12288
	s_barrier
	s_waitcnt lgkmcnt(0)
	s_setprio 1
	v_mfma_f32_32x32x16_bf16 v[64:79], v[162:165], v[128:131], 0
	v_mfma_f32_32x32x16_bf16 v[96:111], v[162:165], v[144:147], 0
	v_mfma_f32_32x32x16_bf16 v[64:79], v[166:169], v[132:135], v[64:79]
	v_mfma_f32_32x32x16_bf16 v[96:111], v[166:169], v[148:151], v[96:111]
	v_mfma_f32_32x32x16_bf16 v[64:79], v[170:173], v[136:139], v[64:79]
	v_mfma_f32_32x32x16_bf16 v[96:111], v[170:173], v[152:155], v[96:111]
	v_mfma_f32_32x32x16_bf16 v[64:79], v[174:177], v[140:143], v[64:79]
	v_mfma_f32_32x32x16_bf16 v[96:111], v[174:177], v[156:159], v[96:111]
	s_setprio 0
	s_barrier
	s_add_u32 m0, s14, 0xa000
	s_nop 0
	global_load_lds_dwordx4 v242, s[24:25]
	s_add_u32 m0, s14, 0xa400
	s_nop 0
	global_load_lds_dwordx4 v243, s[24:25]
	s_waitcnt vmcnt(6)
	s_barrier
	s_setprio 1
	v_mfma_f32_32x32x16_bf16 v[80:95], v[224:227], v[128:131], 0
	v_mfma_f32_32x32x16_bf16 v[112:127], v[224:227], v[144:147], 0
	v_mfma_f32_32x32x16_bf16 v[80:95], v[228:231], v[132:135], v[80:95]
	v_mfma_f32_32x32x16_bf16 v[112:127], v[228:231], v[148:151], v[112:127]
	v_mfma_f32_32x32x16_bf16 v[80:95], v[232:235], v[136:139], v[80:95]
	v_mfma_f32_32x32x16_bf16 v[112:127], v[232:235], v[152:155], v[112:127]
	v_mfma_f32_32x32x16_bf16 v[80:95], v[236:239], v[140:143], v[80:95]
	v_mfma_f32_32x32x16_bf16 v[112:127], v[236:239], v[156:159], v[112:127]
	s_setprio 0
	s_barrier
	s_add_u32 m0, s14, 0x2000
	ds_read_b128 v[162:165], v216
	ds_read_b128 v[166:169], v217
	ds_read_b128 v[170:173], v218
	ds_read_b128 v[174:177], v219
	global_load_lds_dwordx4 v222, s[22:23]
	s_add_u32 m0, s14, 0x2400
	ds_read_b128 v[128:131], v208
	ds_read_b128 v[132:135], v209
	ds_read_b128 v[136:139], v210
	ds_read_b128 v[140:143], v211
	global_load_lds_dwordx4 v223, s[22:23]
	ds_read_b128 v[144:147], v208 offset:4096
	ds_read_b128 v[148:151], v209 offset:4096
	ds_read_b128 v[152:155], v210 offset:4096
	ds_read_b128 v[156:159], v211 offset:4096
	s_add_u32 s22, s22, 0x80
	s_addc_u32 s23, s23, 0
	s_add_u32 s24, s24, 0x80
	s_addc_u32 s25, s25, 0
	s_add_u32 s26, s26, 1
	s_cmp_eq_u32 s26, 16
	s_cbranch_scc0 .Lai3_cadv_done
	s_mov_b32 s26, 0
	s_add_u32 s27, s27, s30
	s_cmp_lt_u32 s27, 0x60
	s_cbranch_scc1 .Lai3_cadv_new
	s_sub_u32 s22, s22, 0x800
	s_subb_u32 s23, s23, 0
	s_sub_u32 s24, s24, 0x800
	s_subb_u32 s25, s25, 0
	s_branch .Lai3_cadv_done

; #define RAWBAR() { asm volatile("s_waitcnt vmcnt(0) lgkmcnt(0)" ::: "memory"); __builtin_amdgcn_s_barrier(); }
;     ...
;   for (int kt = 0; kt < nk; kt += 2) {
;     if (V != 1) GLDS(kt + 1, 1);
;     if (V != 2) COMPUTE(0);
;     RAWBAR();
;     if (V != 1) if (kt + 2 < nk) GLDS(kt + 2, 0);
;     if (V != 2) COMPUTE(1);
;     RAWBAR();
.Lai3_cadv_done:
	s_waitcnt lgkmcnt(8)
	s_barrier
	s_waitcnt lgkmcnt(0)
	s_setprio 1
	v_mfma_f32_32x32x16_bf16 v[0:15], v[162:165], v[128:131], v[0:15]
	v_mfma_f32_32x32x16_bf16 v[32:47], v[162:165], v[144:147], v[32:47]
	v_mfma_f32_32x32x16_bf16 v[0:15], v[166:169], v[132:135], v[0:15]
	v_mfma_f32_32x32x16_bf16 v[32:47], v[166:169], v[148:151], v[32:47]
	v_mfma_f32_32x32x16_bf16 v[0:15], v[170:173], v[136:139], v[0:15]
	v_mfma_f32_32x32x16_bf16 v[32:47], v[170:173], v[152:155], v[32:47]
	v_mfma_f32_32x32x16_bf16 v[0:15], v[174:177], v[140:143], v[0:15]
	v_mfma_f32_32x32x16_bf16 v[32:47], v[174:177], v[156:159], v[32:47]
	s_setprio 0
	s_barrier
	s_add_u32 m0, s14, 0x18000
	ds_read_b128 v[224:227], v216 offset:8192
	global_load_lds_dwordx4 v240, s[24:25]
	s_add_u32 m0, s14, 0x18400
	ds_read_b128 v[228:231], v217 offset:8192
	global_load_lds_dwordx4 v241, s[24:25]
	ds_read_b128 v[232:235], v218 offset:8192
	ds_read_b128 v[236:239], v219 offset:8192
	s_barrier
	s_waitcnt lgkmcnt(0)
	s_setprio 1
	v_mfma_f32_32x32x16_bf16 v[16:31], v[224:227], v[128:131], v[16:31]
	v_mfma_f32_32x32x16_bf16 v[48:63], v[224:227], v[144:147], v[48:63]
	v_mfma_f32_32x32x16_bf16 v[16:31], v[228:231], v[132:135], v[16:31]
	v_mfma_f32_32x32x16_bf16 v[48:63], v[228:231], v[148:151], v[48:63]
	v_mfma_f32_32x32x16_bf16 v[16:31], v[232:235], v[136:139], v[16:31]
	v_mfma_f32_32x32x16_bf16 v[48:63], v[232:235], v[152:155], v[48:63]
	v_mfma_f32_32x32x16_bf16 v[16:31], v[236:239], v[140:143], v[16:31]
	v_mfma_f32_32x32x16_bf16 v[48:63], v[236:239], v[156:159], v[48:63]
	s_setprio 0
	s_barrier
	s_add_u32 m0, s14, 0x10000
	ds_read_b128 v[128:131], v208 offset:8192
	ds_read_b128 v[132:135], v209 offset:8192
	global_load_lds_dwordx4 v220, s[22:23]
	s_add_u32 m0, s14, 0x10400
	ds_read_b128 v[136:139], v210 offset:8192
	ds_read_b128 v[140:143], v211 offset:8192
	global_load_lds_dwordx4 v221, s[22:23]
	ds_read_b128 v[144:147], v208 offset:12288
	ds_read_b128 v[148:151], v209 offset:12288
	ds_read_b128 v[152:155], v210 offset:12288
	ds_read_b128 v[156:159], v211 offset:12288
	s_barrier
	s_waitcnt lgkmcnt(0)
	s_setprio 1
	v_mfma_f32_32x32x16_bf16 v[64:79], v[162:165], v[128:131], v[64:79]
	v_mfma_f32_32x32x16_bf16 v[96:111], v[162:165], v[144:147], v[96:111]
	v_mfma_f32_32x32x16_bf16 v[64:79], v[166:169], v[132:135], v[64:79]
	v_mfma_f32_32x32x16_bf16 v[96:111], v[166:169], v[148:151], v[96:111]
	v_mfma_f32_32x32x16_bf16 v[64:79], v[170:173], v[136:139], v[64:79]
	v_mfma_f32_32x32x16_bf16 v[96:111], v[170:173], v[152:155], v[96:111]
	v_mfma_f32_32x32x16_bf16 v[64:79], v[174:177], v[140:143], v[64:79]
	v_mfma_f32_32x32x16_bf16 v[96:111], v[174:177], v[156:159], v[96:111]
	s_setprio 0
	s_barrier
	s_add_u32 m0, s14, 0x1a000
	s_nop 0
	global_load_lds_dwordx4 v242, s[24:25]
	s_add_u32 m0, s14, 0x1a400
	s_nop 0
	global_load_lds_dwordx4 v243, s[24:25]
	s_waitcnt vmcnt(6)
	s_barrier
	s_setprio 1
	v_mfma_f32_32x32x16_bf16 v[80:95], v[224:227], v[128:131], v[80:95]
	v_mfma_f32_32x32x16_bf16 v[112:127], v[224:227], v[144:147], v[112:127]
	v_mfma_f32_32x32x16_bf16 v[80:95], v[228:231], v[132:135], v[80:95]
	v_mfma_f32_32x32x16_bf16 v[112:127], v[228:231], v[148:151], v[112:127]
	v_mfma_f32_32x32x16_bf16 v[80:95], v[232:235], v[136:139], v[80:95]
	v_mfma_f32_32x32x16_bf16 v[112:127], v[232:235], v[152:155], v[112:127]
	v_mfma_f32_32x32x16_bf16 v[80:95], v[236:239], v[140:143], v[80:95]
	v_mfma_f32_32x32x16_bf16 v[112:127], v[236:239], v[156:159], v[112:127]
	s_setprio 0
	s_barrier
	s_mov_b32 s29, 6
	s_cmp_eq_u32 s29, 0
	s_cbranch_scc1 .Lai_pairs_done
.Lai_pair:
	s_add_u32 m0, s14, 0x12000
	ds_read_b128 v[162:165], v212
	ds_read_b128 v[166:169], v213
	ds_read_b128 v[170:173], v214
	ds_read_b128 v[174:177], v215
	global_load_lds_dwordx4 v222, s[22:23]
	s_add_u32 m0, s14, 0x12400
	ds_read_b128 v[128:131], v204
	ds_read_b128 v[132:135], v205
	ds_read_b128 v[136:139], v206
	ds_read_b128 v[140:143], v207
	global_load_lds_dwordx4 v223, s[22:23]
	ds_read_b128 v[144:147], v204 offset:4096
	ds_read_b128 v[148:151], v205 offset:4096
	ds_read_b128 v[152:155], v206 offset:4096
	ds_read_b128 v[156:159], v207 offset:4096
	s_add_u32 s22, s22, 0x80
	s_addc_u32 s23, s23, 0
	s_add_u32 s24, s24, 0x80
	s_addc_u32 s25, s25, 0
	s_add_u32 s26, s26, 1
	s_cmp_eq_u32 s26, 16
	s_cbranch_scc0 .Lai4_cadv_done
	s_mov_b32 s26, 0
	s_add_u32 s27, s27, s30
	s_cmp_lt_u32 s27, 0x60
	s_cbranch_scc1 .Lai4_cadv_new
	s_sub_u32 s22, s22, 0x800
	s_subb_u32 s23, s23, 0
	s_sub_u32 s24, s24, 0x800
	s_subb_u32 s25, s25, 0
	s_branch .Lai4_cadv_done

; #define RAWBAR() { asm volatile("s_waitcnt vmcnt(0) lgkmcnt(0)" ::: "memory"); __builtin_amdgcn_s_barrier(); }
;     ...
;   for (int kt = 0; kt < nk; kt += 2) {
;     if (V != 1) GLDS(kt + 1, 1);
;     if (V != 2) COMPUTE(0);
;     RAWBAR();
;     if (V != 1) if (kt + 2 < nk) GLDS(kt + 2, 0);
;     if (V != 2) COMPUTE(1);
;     RAWBAR();
.Lai4_cadv_done:
	s_waitcnt lgkmcnt(8)
	s_barrier
	s_waitcnt lgkmcnt(0)
	s_setprio 1
	v_mfma_f32_32x32x16_bf16 v[0:15], v[162:165], v[128:131], v[0:15]
	v_mfma_f32_32x32x16_bf16 v[32:47], v[162:165], v[144:147], v[32:47]
	v_mfma_f32_32x32x16_bf16 v[0:15], v[166:169], v[132:135], v[0:15]
	v_mfma_f32_32x32x16_bf16 v[32:47], v[166:169], v[148:151], v[32:47]
	v_mfma_f32_32x32x16_bf16 v[0:15], v[170:173], v[136:139], v[0:15]
	v_mfma_f32_32x32x16_bf16 v[32:47], v[170:173], v[152:155], v[32:47]
	v_mfma_f32_32x32x16_bf16 v[0:15], v[174:177], v[140:143], v[0:15]
	v_mfma_f32_32x32x16_bf16 v[32:47], v[174:177], v[156:159], v[32:47]
	s_setprio 0
	s_barrier
	s_add_u32 m0, s14, 0x8000
	ds_read_b128 v[224:227], v212 offset:8192
	global_load_lds_dwordx4 v240, s[24:25]
	s_add_u32 m0, s14, 0x8400
	ds_read_b128 v[228:231], v213 offset:8192
	global_load_lds_dwordx4 v241, s[24:25]
	ds_read_b128 v[232:235], v214 offset:8192
	ds_read_b128 v[236:239], v215 offset:8192
	s_barrier
	s_waitcnt lgkmcnt(0)
	s_setprio 1
	v_mfma_f32_32x32x16_bf16 v[16:31], v[224:227], v[128:131], v[16:31]
	v_mfma_f32_32x32x16_bf16 v[48:63], v[224:227], v[144:147], v[48:63]
	v_mfma_f32_32x32x16_bf16 v[16:31], v[228:231], v[132:135], v[16:31]
	v_mfma_f32_32x32x16_bf16 v[48:63], v[228:231], v[148:151], v[48:63]
	v_mfma_f32_32x32x16_bf16 v[16:31], v[232:235], v[136:139], v[16:31]
	v_mfma_f32_32x32x16_bf16 v[48:63], v[232:235], v[152:155], v[48:63]
	v_mfma_f32_32x32x16_bf16 v[16:31], v[236:239], v[140:143], v[16:31]
	v_mfma_f32_32x32x16_bf16 v[48:63], v[236:239], v[156:159], v[48:63]
	s_setprio 0
	s_barrier
	s_add_u32 m0, s14, 0x0
	ds_read_b128 v[128:131], v204 offset:8192
	ds_read_b128 v[132:135], v205 offset:8192
	global_load_lds_dwordx4 v220, s[22:23]
	s_add_u32 m0, s14, 0x400
	ds_read_b128 v[136:139], v206 offset:8192
	ds_read_b128 v[140:143], v207 offset:8192
	global_load_lds_dwordx4 v221, s[22:23]
	ds_read_b128 v[144:147], v204 offset:12288
	ds_read_b128 v[148:151], v205 offset:12288
	ds_read_b128 v[152:155], v206 offset:12288
	ds_read_b128 v[156:159], v207 offset:12288
	s_barrier
	s_waitcnt lgkmcnt(0)
	s_setprio 1
	v_mfma_f32_32x32x16_bf16 v[64:79], v[162:165], v[128:131], v[64:79]
	v_mfma_f32_32x32x16_bf16 v[96:111], v[162:165], v[144:147], v[96:111]
	v_mfma_f32_32x32x16_bf16 v[64:79], v[166:169], v[132:135], v[64:79]
	v_mfma_f32_32x32x16_bf16 v[96:111], v[166:169], v[148:151], v[96:111]
	v_mfma_f32_32x32x16_bf16 v[64:79], v[170:173], v[136:139], v[64:79]
	v_mfma_f32_32x32x16_bf16 v[96:111], v[170:173], v[152:155], v[96:111]
	v_mfma_f32_32x32x16_bf16 v[64:79], v[174:177], v[140:143], v[64:79]
	v_mfma_f32_32x32x16_bf16 v[96:111], v[174:177], v[156:159], v[96:111]
	s_setprio 0
	s_barrier
	s_add_u32 m0, s14, 0xa000
	s_nop 0
	global_load_lds_dwordx4 v242, s[24:25]
	s_add_u32 m0, s14, 0xa400
	s_nop 0
	global_load_lds_dwordx4 v243, s[24:25]
	s_waitcnt vmcnt(6)
	s_barrier
	s_setprio 1
	v_mfma_f32_32x32x16_bf16 v[80:95], v[224:227], v[128:131], v[80:95]
	v_mfma_f32_32x32x16_bf16 v[112:127], v[224:227], v[144:147], v[112:127]
	v_mfma_f32_32x32x16_bf16 v[80:95], v[228:231], v[132:135], v[80:95]
	v_mfma_f32_32x32x16_bf16 v[112:127], v[228:231], v[148:151], v[112:127]
	v_mfma_f32_32x32x16_bf16 v[80:95], v[232:235], v[136:139], v[80:95]
	v_mfma_f32_32x32x16_bf16 v[112:127], v[232:235], v[152:155], v[112:127]
	v_mfma_f32_32x32x16_bf16 v[80:95], v[236:239], v[140:143], v[80:95]
	v_mfma_f32_32x32x16_bf16 v[112:127], v[236:239], v[156:159], v[112:127]
	s_setprio 0
	s_barrier
	s_add_u32 m0, s14, 0x2000
	ds_read_b128 v[162:165], v216
	ds_read_b128 v[166:169], v217
	ds_read_b128 v[170:173], v218
	ds_read_b128 v[174:177], v219
	global_load_lds_dwordx4 v222, s[22:23]
	s_add_u32 m0, s14, 0x2400
	ds_read_b128 v[128:131], v208
	ds_read_b128 v[132:135], v209
	ds_read_b128 v[136:139], v210
	ds_read_b128 v[140:143], v211
	global_load_lds_dwordx4 v223, s[22:23]
	ds_read_b128 v[144:147], v208 offset:4096
	ds_read_b128 v[148:151], v209 offset:4096
	ds_read_b128 v[152:155], v210 offset:4096
	ds_read_b128 v[156:159], v211 offset:4096
	s_add_u32 s22, s22, 0x80
	s_addc_u32 s23, s23, 0
	s_add_u32 s24, s24, 0x80
	s_addc_u32 s25, s25, 0
	s_add_u32 s26, s26, 1
	s_cmp_eq_u32 s26, 16
	s_cbranch_scc0 .Lai5_cadv_done
	s_mov_b32 s26, 0
	s_add_u32 s27, s27, s30
	s_cmp_lt_u32 s27, 0x60
	s_cbranch_scc1 .Lai5_cadv_new
	s_sub_u32 s22, s22, 0x800
	s_subb_u32 s23, s23, 0
	s_sub_u32 s24, s24, 0x800
	s_subb_u32 s25, s25, 0
	s_branch .Lai5_cadv_done

; #define RAWBAR() { asm volatile("s_waitcnt vmcnt(0) lgkmcnt(0)" ::: "memory"); __builtin_amdgcn_s_barrier(); }
;     ...
;   if (V != 1) GLDS(0, 0);
;   RAWBAR();
;   for (int kt = 0; kt < nk; kt += 2) {
;     if (V != 1) GLDS(kt + 1, 1);
;     if (V != 2) COMPUTE(0);
;     RAWBAR();
;     if (V != 1) if (kt + 2 < nk) GLDS(kt + 2, 0);
;     if (V != 2) COMPUTE(1);
;     RAWBAR();
.Lai5_cadv_done:
	s_waitcnt lgkmcnt(8)
	s_barrier
	s_waitcnt lgkmcnt(0)
	s_setprio 1
	v_mfma_f32_32x32x16_bf16 v[0:15], v[162:165], v[128:131], v[0:15]
	v_mfma_f32_32x32x16_bf16 v[32:47], v[162:165], v[144:147], v[32:47]
	v_mfma_f32_32x32x16_bf16 v[0:15], v[166:169], v[132:135], v[0:15]
	v_mfma_f32_32x32x16_bf16 v[32:47], v[166:169], v[148:151], v[32:47]
	v_mfma_f32_32x32x16_bf16 v[0:15], v[170:173], v[136:139], v[0:15]
	v_mfma_f32_32x32x16_bf16 v[32:47], v[170:173], v[152:155], v[32:47]
	v_mfma_f32_32x32x16_bf16 v[0:15], v[174:177], v[140:143], v[0:15]
	v_mfma_f32_32x32x16_bf16 v[32:47], v[174:177], v[156:159], v[32:47]
	s_setprio 0
	s_barrier
	s_add_u32 m0, s14, 0x18000
	ds_read_b128 v[224:227], v216 offset:8192
	global_load_lds_dwordx4 v240, s[24:25]
	s_add_u32 m0, s14, 0x18400
	ds_read_b128 v[228:231], v217 offset:8192
	global_load_lds_dwordx4 v241, s[24:25]
	ds_read_b128 v[232:235], v218 offset:8192
	ds_read_b128 v[236:239], v219 offset:8192
	s_barrier
	s_waitcnt lgkmcnt(0)
	s_setprio 1
	v_mfma_f32_32x32x16_bf16 v[16:31], v[224:227], v[128:131], v[16:31]
	v_mfma_f32_32x32x16_bf16 v[48:63], v[224:227], v[144:147], v[48:63]
	v_mfma_f32_32x32x16_bf16 v[16:31], v[228:231], v[132:135], v[16:31]
	v_mfma_f32_32x32x16_bf16 v[48:63], v[228:231], v[148:151], v[48:63]
	v_mfma_f32_32x32x16_bf16 v[16:31], v[232:235], v[136:139], v[16:31]
	v_mfma_f32_32x32x16_bf16 v[48:63], v[232:235], v[152:155], v[48:63]
	v_mfma_f32_32x32x16_bf16 v[16:31], v[236:239], v[140:143], v[16:31]
	v_mfma_f32_32x32x16_bf16 v[48:63], v[236:239], v[156:159], v[48:63]
	s_setprio 0
	s_barrier
	s_add_u32 m0, s14, 0x10000
	ds_read_b128 v[128:131], v208 offset:8192
	ds_read_b128 v[132:135], v209 offset:8192
	global_load_lds_dwordx4 v220, s[22:23]
	s_add_u32 m0, s14, 0x10400
	ds_read_b128 v[136:139], v210 offset:8192
	ds_read_b128 v[140:143], v211 offset:8192
	global_load_lds_dwordx4 v221, s[22:23]
	ds_read_b128 v[144:147], v208 offset:12288
	ds_read_b128 v[148:151], v209 offset:12288
	ds_read_b128 v[152:155], v210 offset:12288
	ds_read_b128 v[156:159], v211 offset:12288
	s_barrier
	s_waitcnt lgkmcnt(0)
	s_setprio 1
	v_mfma_f32_32x32x16_bf16 v[64:79], v[162:165], v[128:131], v[64:79]
	v_mfma_f32_32x32x16_bf16 v[96:111], v[162:165], v[144:147], v[96:111]
	v_mfma_f32_32x32x16_bf16 v[64:79], v[166:169], v[132:135], v[64:79]
	v_mfma_f32_32x32x16_bf16 v[96:111], v[166:169], v[148:151], v[96:111]
	v_mfma_f32_32x32x16_bf16 v[64:79], v[170:173], v[136:139], v[64:79]
	v_mfma_f32_32x32x16_bf16 v[96:111], v[170:173], v[152:155], v[96:111]
	v_mfma_f32_32x32x16_bf16 v[64:79], v[174:177], v[140:143], v[64:79]
	v_mfma_f32_32x32x16_bf16 v[96:111], v[174:177], v[156:159], v[96:111]
	s_setprio 0
	s_barrier
	s_add_u32 m0, s14, 0x1a000
	s_nop 0
	global_load_lds_dwordx4 v242, s[24:25]
	s_add_u32 m0, s14, 0x1a400
	s_nop 0
	global_load_lds_dwordx4 v243, s[24:25]
	s_waitcnt vmcnt(6)
	s_barrier
	s_setprio 1
	v_mfma_f32_32x32x16_bf16 v[80:95], v[224:227], v[128:131], v[80:95]
	v_mfma_f32_32x32x16_bf16 v[112:127], v[224:227], v[144:147], v[112:127]
	v_mfma_f32_32x32x16_bf16 v[80:95], v[228:231], v[132:135], v[80:95]
	v_mfma_f32_32x32x16_bf16 v[112:127], v[228:231], v[148:151], v[112:127]
	v_mfma_f32_32x32x16_bf16 v[80:95], v[232:235], v[136:139], v[80:95]
	v_mfma_f32_32x32x16_bf16 v[112:127], v[232:235], v[152:155], v[112:127]
	v_mfma_f32_32x32x16_bf16 v[80:95], v[236:239], v[140:143], v[80:95]
	v_mfma_f32_32x32x16_bf16 v[112:127], v[236:239], v[156:159], v[112:127]
	s_setprio 0
	s_barrier
	s_sub_u32 s29, s29, 1
	s_cmp_lg_u32 s29, 0
	s_cbranch_scc1 .Lai_pair

; DI int crow(int r, int hf) { return (r & 3) + 8 * (r >> 2) + 4 * hf; }
; #define RAWBAR() { asm volatile("s_waitcnt vmcnt(0) lgkmcnt(0)" ::: "memory"); __builtin_amdgcn_s_barrier(); }
;     ...
;   for (int kt = 0; kt < nk; kt += 2) {
;     if (V != 1) GLDS(kt + 1, 1);
;     if (V != 2) COMPUTE(0);
;     RAWBAR();
;     if (V != 1) if (kt + 2 < nk) GLDS(kt + 2, 0);
;     if (V != 2) COMPUTE(1);
;     RAWBAR();
; DI void att_in_phase(const Params& p, int j, char* smem) {
;     ...
;         if (C64 < 640) {
; #pragma unroll
;           for (int jn = 0; jn < 2; ++jn)
; #pragma unroll
;             for (int r = 0; r < 16; ++r) zc[(size_t)(rb + crow(r, hf_)) * 640 + C64 + jn * 32 + l32_] = f2bf(acc[i][jn][r]);
;         } else if (C64 < 1280) {
;           const bool isq = C64 < 1152;
;           u16* dst = isq ? SQ : SK; const int pitch = isq ? 512 : 128; const int cb = isq ? (C64 - 640) : (C64 - 1152);
;           const float sc = isq ? SWA_QSCALE : 1.f;
; #pragma unroll
;           for (int r = 0; r < 16; ++r) {
;             const int t = rb + crow(r, hf_), pos = t & (S_ - 1);
;             const float2 cs = rt64[pos * 32 + l32_];
;             const float x1 = acc[i][0][r], x2 = acc[i][1][r];
;             dst[(size_t)t * pitch + cb + l32_] = f2bf((x1 * cs.x - x2 * cs.y) * sc);
;             dst[(size_t)t * pitch + cb + 32 + l32_] = f2bf((x2 * cs.x + x1 * cs.y) * sc);
;           }
;         } else if (C64 < 1408) {
; #pragma unroll
;           for (int jn = 0; jn < 2; ++jn)
; #pragma unroll
;             for (int r = 0; r < 16; ++r) SV[(size_t)(rb + crow(r, hf_)) * 128 + (C64 - 1280) + jn * 32 + l32_] = f2bf(acc[i][jn][r]);
;         } else if (C64 == 1408) {
.Lai7_cadv_done:
	s_waitcnt lgkmcnt(8)
	s_barrier
	s_waitcnt lgkmcnt(0)
	s_setprio 1
	v_mfma_f32_32x32x16_bf16 v[0:15], v[162:165], v[128:131], v[0:15]
	v_mfma_f32_32x32x16_bf16 v[32:47], v[162:165], v[144:147], v[32:47]
	v_mfma_f32_32x32x16_bf16 v[0:15], v[166:169], v[132:135], v[0:15]
	v_mfma_f32_32x32x16_bf16 v[32:47], v[166:169], v[148:151], v[32:47]
	v_mfma_f32_32x32x16_bf16 v[0:15], v[170:173], v[136:139], v[0:15]
	v_mfma_f32_32x32x16_bf16 v[32:47], v[170:173], v[152:155], v[32:47]
	v_mfma_f32_32x32x16_bf16 v[0:15], v[174:177], v[140:143], v[0:15]
	v_mfma_f32_32x32x16_bf16 v[32:47], v[174:177], v[156:159], v[32:47]
	s_setprio 0
	s_barrier
	ds_read_b128 v[224:227], v216 offset:8192
	ds_read_b128 v[228:231], v217 offset:8192
	ds_read_b128 v[232:235], v218 offset:8192
	ds_read_b128 v[236:239], v219 offset:8192
	s_barrier
	s_waitcnt lgkmcnt(0)
	s_setprio 1
	v_mfma_f32_32x32x16_bf16 v[16:31], v[224:227], v[128:131], v[16:31]
	v_mfma_f32_32x32x16_bf16 v[48:63], v[224:227], v[144:147], v[48:63]
	v_mfma_f32_32x32x16_bf16 v[16:31], v[228:231], v[132:135], v[16:31]
	v_mfma_f32_32x32x16_bf16 v[48:63], v[228:231], v[148:151], v[48:63]
	v_mfma_f32_32x32x16_bf16 v[16:31], v[232:235], v[136:139], v[16:31]
	v_mfma_f32_32x32x16_bf16 v[48:63], v[232:235], v[152:155], v[48:63]
	v_mfma_f32_32x32x16_bf16 v[16:31], v[236:239], v[140:143], v[16:31]
	v_mfma_f32_32x32x16_bf16 v[48:63], v[236:239], v[156:159], v[48:63]
	s_setprio 0
	s_barrier
	s_add_u32 m0, s14, 0x10000
	ds_read_b128 v[128:131], v208 offset:8192
	ds_read_b128 v[132:135], v209 offset:8192
	global_load_lds_dwordx4 v220, s[22:23]
	s_add_u32 m0, s14, 0x10400
	ds_read_b128 v[136:139], v210 offset:8192
	ds_read_b128 v[140:143], v211 offset:8192
	global_load_lds_dwordx4 v221, s[22:23]
	ds_read_b128 v[144:147], v208 offset:12288
	ds_read_b128 v[148:151], v209 offset:12288
	ds_read_b128 v[152:155], v210 offset:12288
	ds_read_b128 v[156:159], v211 offset:12288
	s_barrier
	s_waitcnt lgkmcnt(0)
	s_setprio 1
	v_mfma_f32_32x32x16_bf16 v[64:79], v[162:165], v[128:131], v[64:79]
	v_mfma_f32_32x32x16_bf16 v[96:111], v[162:165], v[144:147], v[96:111]
	v_mfma_f32_32x32x16_bf16 v[64:79], v[166:169], v[132:135], v[64:79]
	v_mfma_f32_32x32x16_bf16 v[96:111], v[166:169], v[148:151], v[96:111]
	v_mfma_f32_32x32x16_bf16 v[64:79], v[170:173], v[136:139], v[64:79]
	v_mfma_f32_32x32x16_bf16 v[96:111], v[170:173], v[152:155], v[96:111]
	v_mfma_f32_32x32x16_bf16 v[64:79], v[174:177], v[140:143], v[64:79]
	v_mfma_f32_32x32x16_bf16 v[96:111], v[174:177], v[156:159], v[96:111]
	s_setprio 0
	s_barrier
	s_waitcnt vmcnt(2)
	s_barrier
	s_setprio 1
	v_mfma_f32_32x32x16_bf16 v[80:95], v[224:227], v[128:131], v[80:95]
	v_mfma_f32_32x32x16_bf16 v[112:127], v[224:227], v[144:147], v[112:127]
	v_mfma_f32_32x32x16_bf16 v[80:95], v[228:231], v[132:135], v[80:95]
	v_mfma_f32_32x32x16_bf16 v[112:127], v[228:231], v[148:151], v[112:127]
	v_mfma_f32_32x32x16_bf16 v[80:95], v[232:235], v[136:139], v[80:95]
	v_mfma_f32_32x32x16_bf16 v[112:127], v[232:235], v[152:155], v[112:127]
	v_mfma_f32_32x32x16_bf16 v[80:95], v[236:239], v[140:143], v[80:95]
	v_mfma_f32_32x32x16_bf16 v[112:127], v[236:239], v[156:159], v[112:127]
	s_setprio 0
	s_barrier
	s_lshr_b32 s20, s28, 5
	s_lshl_b32 s20, s20, 1
	s_and_b32 s8, s28, 1
	s_add_u32 s20, s20, s8
	s_lshl_b32 s20, s20, 2
	s_add_u32 s20, s20, s13
	s_cmp_lt_u32 s20, 10
	s_cbranch_scc1 .Lai_epi_zc
	s_cmp_lt_u32 s20, 18
	s_cbranch_scc1 .Lai_epi_sq
	s_cmp_lt_u32 s20, 20
	s_cbranch_scc1 .Lai_epi_sk
	s_cmp_lt_u32 s20, 22
	s_cbranch_scc1 .Lai_epi_sv
	s_cmp_eq_u32 s20, 22
	s_cbranch_scc1 .Lai_epi_kr
	s_branch .Lai_epi_done

; DI int crow(int r, int hf) { return (r & 3) + 8 * (r >> 2) + 4 * hf; }
; DI void att_in_phase(const Params& p, int j, char* smem) {
;     ...
;         } else if (C64 == 1408) {
; #pragma unroll
;           for (int r = 0; r < 16; ++r) {
;             const int t = rb + crow(r, hf_), pos = t & (S_ - 1);
;             const float x = acc[i][0][r];
;             const float xp = __shfl_xor(x, 16);
;             const float2 cs = rt32[pos * 16 + (l32_ & 15)];
;             const float o = (l32_ < 16) ? (x * cs.x - xp * cs.y) : (x * cs.x + xp * cs.y);
;             const u16 v = f2bf(o);
; #pragma unroll
;             for (int h = 0; h < 8; ++h) Kb[(size_t)t * LDKB + h * 96 + 64 + l32_] = v;
;           }
.Lai_epi_kr:
	v_and_b32_e32 v245, 63, v182
	v_and_b32_e32 v244, 31, v245
	v_lshrrev_b32_e32 v243, 5, v245
	v_lshlrev_b32_e32 v246, 7, v244
	v_lshl_add_u32 v246, v243, 5, v246
	s_lshl_b32 s8, s53, 7
	s_add_u32 s54, s0, s8
	s_addc_u32 s55, s1, 0
	s_add_u32 s54, s54, 0x34100
	s_addc_u32 s55, s55, 0
	s_add_u32 s8, s54, 0x0
	s_addc_u32 s9, s55, 0
	global_load_dwordx4 v[128:131], v246, s[8:9]
	global_load_dwordx4 v[132:135], v246, s[8:9] offset:16
	global_load_dwordx4 v[136:139], v246, s[8:9] offset:64
	global_load_dwordx4 v[140:143], v246, s[8:9] offset:80
	s_add_u32 s8, s54, 0x1000
	s_addc_u32 s9, s55, 0
	global_load_dwordx4 v[144:147], v246, s[8:9]
	global_load_dwordx4 v[148:151], v246, s[8:9] offset:16
	global_load_dwordx4 v[152:155], v246, s[8:9] offset:64
	global_load_dwordx4 v[156:159], v246, s[8:9] offset:80
	s_add_u32 s8, s54, 0x2000
	s_addc_u32 s9, s55, 0
	global_load_dwordx4 v[162:165], v246, s[8:9]
	global_load_dwordx4 v[166:169], v246, s[8:9] offset:16
	global_load_dwordx4 v[170:173], v246, s[8:9] offset:64
	global_load_dwordx4 v[174:177], v246, s[8:9] offset:80
	s_add_u32 s8, s54, 0x3000
	s_addc_u32 s9, s55, 0
	global_load_dwordx4 v[224:227], v246, s[8:9]
	global_load_dwordx4 v[228:231], v246, s[8:9] offset:16
	global_load_dwordx4 v[232:235], v246, s[8:9] offset:64
	global_load_dwordx4 v[236:239], v246, s[8:9] offset:80
	v_lshrrev_b32_e32 v247, 2, v245
	v_and_b32_e32 v196, 7, v247
	v_and_b32_e32 v197, 3, v245
	v_xor_b32_e32 v196, v196, v197
	v_lshlrev_b32_e32 v196, 4, v196
	v_lshl_add_u32 v196, v247, 7, v196
	s_lshl_b32 s8, s15, 12
	s_add_u32 s8, s8, 0x18020
	v_add_u32_e32 v196, s8, v196
	v_lshlrev_b32_e32 v197, 4, v197
	s_movk_i32 s8, 0x680
	v_mad_u32_u24 v197, v247, s8, v197
	s_mul_i32 s8, s52, 0x680
	s_add_u32 s38, s0, s8
	s_addc_u32 s39, s1, 0
	s_add_u32 s38, s38, 0x12804180
	s_addc_u32 s39, s39, 0
	s_waitcnt vmcnt(0)
	v_mul_f32_e32 v246, v8, v129
	v_mul_f32_e32 v247, v0, v129
	v_fma_f32 v0, v0, v128, -v246
	v_fma_f32 v8, v8, v128, v247
	v_mul_f32_e32 v246, v9, v131
	v_mul_f32_e32 v247, v1, v131
	v_fma_f32 v1, v1, v130, -v246
	v_fma_f32 v9, v9, v130, v247
	v_mul_f32_e32 v246, v10, v133
	v_mul_f32_e32 v247, v2, v133
	v_fma_f32 v2, v2, v132, -v246
	v_fma_f32 v10, v10, v132, v247
	v_mul_f32_e32 v246, v11, v135
	v_mul_f32_e32 v247, v3, v135
	v_fma_f32 v3, v3, v134, -v246
	v_fma_f32 v11, v11, v134, v247
	v_mul_f32_e32 v246, v12, v137
	v_mul_f32_e32 v247, v4, v137
	v_fma_f32 v4, v4, v136, -v246
	v_fma_f32 v12, v12, v136, v247
	v_mul_f32_e32 v246, v13, v139
	v_mul_f32_e32 v247, v5, v139
	v_fma_f32 v5, v5, v138, -v246
	v_fma_f32 v13, v13, v138, v247
	v_mul_f32_e32 v246, v14, v141
	v_mul_f32_e32 v247, v6, v141
	v_fma_f32 v6, v6, v140, -v246
	v_fma_f32 v14, v14, v140, v247
	v_mul_f32_e32 v246, v15, v143
	v_mul_f32_e32 v247, v7, v143
	v_fma_f32 v7, v7, v142, -v246
	v_fma_f32 v15, v15, v142, v247
	v_cvt_pk_bf16_f32 v240, v0, v1
	v_cvt_pk_bf16_f32 v241, v2, v3
	ds_write_b64 v178, v[240:241]
	v_cvt_pk_bf16_f32 v242, v4, v5
	v_cvt_pk_bf16_f32 v243, v6, v7
	ds_write_b64 v179, v[242:243]
	v_cvt_pk_bf16_f32 v244, v8, v9
	v_cvt_pk_bf16_f32 v245, v10, v11
	ds_write_b64 v180, v[244:245]
	v_cvt_pk_bf16_f32 v240, v12, v13
	v_cvt_pk_bf16_f32 v241, v14, v15
	ds_write_b64 v181, v[240:241]
	ds_read_b128 v[16:19], v196
	ds_read_b128 v[20:23], v196 offset:2048
	s_waitcnt lgkmcnt(0)
	global_store_dwordx4 v197, v[16:19], s[38:39]
	global_store_dwordx4 v197, v[16:19], s[38:39] offset:192
	global_store_dwordx4 v197, v[16:19], s[38:39] offset:384
	global_store_dwordx4 v197, v[16:19], s[38:39] offset:576
	global_store_dwordx4 v197, v[16:19], s[38:39] offset:768
	global_store_dwordx4 v197, v[16:19], s[38:39] offset:960
	global_store_dwordx4 v197, v[16:19], s[38:39] offset:1152
	global_store_dwordx4 v197, v[16:19], s[38:39] offset:1344
	s_add_u32 s38, s38, 0x6800
	s_addc_u32 s39, s39, 0
	global_store_dwordx4 v197, v[20:23], s[38:39]
	global_store_dwordx4 v197, v[20:23], s[38:39] offset:192
	global_store_dwordx4 v197, v[20:23], s[38:39] offset:384
	global_store_dwordx4 v197, v[20:23], s[38:39] offset:576
	global_store_dwordx4 v197, v[20:23], s[38:39] offset:768
	global_store_dwordx4 v197, v[20:23], s[38:39] offset:960
	global_store_dwordx4 v197, v[20:23], s[38:39] offset:1152
	global_store_dwordx4 v197, v[20:23], s[38:39] offset:1344
	s_add_u32 s38, s38, 0x6800
	s_addc_u32 s39, s39, 0
	v_mul_f32_e32 v246, v40, v145
	v_mul_f32_e32 v247, v32, v145
	v_fma_f32 v32, v32, v144, -v246
	v_fma_f32 v40, v40, v144, v247
	v_mul_f32_e32 v246, v41, v147
	v_mul_f32_e32 v247, v33, v147
	v_fma_f32 v33, v33, v146, -v246
	v_fma_f32 v41, v41, v146, v247
	v_mul_f32_e32 v246, v42, v149
	v_mul_f32_e32 v247, v34, v149
	v_fma_f32 v34, v34, v148, -v246
	v_fma_f32 v42, v42, v148, v247
	v_mul_f32_e32 v246, v43, v151
	v_mul_f32_e32 v247, v35, v151
	v_fma_f32 v35, v35, v150, -v246
	v_fma_f32 v43, v43, v150, v247
	v_mul_f32_e32 v246, v44, v153
	v_mul_f32_e32 v247, v36, v153
	v_fma_f32 v36, v36, v152, -v246
	v_fma_f32 v44, v44, v152, v247
	v_mul_f32_e32 v246, v45, v155
	v_mul_f32_e32 v247, v37, v155
	v_fma_f32 v37, v37, v154, -v246
	v_fma_f32 v45, v45, v154, v247
	v_mul_f32_e32 v246, v46, v157
	v_mul_f32_e32 v247, v38, v157
	v_fma_f32 v38, v38, v156, -v246
	v_fma_f32 v46, v46, v156, v247
	v_mul_f32_e32 v246, v47, v159
	v_mul_f32_e32 v247, v39, v159
	v_fma_f32 v39, v39, v158, -v246
	v_fma_f32 v47, v47, v158, v247
	v_cvt_pk_bf16_f32 v242, v32, v33
	v_cvt_pk_bf16_f32 v243, v34, v35
	ds_write_b64 v178, v[242:243]
	v_cvt_pk_bf16_f32 v244, v36, v37
	v_cvt_pk_bf16_f32 v245, v38, v39
	ds_write_b64 v179, v[244:245]
	v_cvt_pk_bf16_f32 v240, v40, v41
	v_cvt_pk_bf16_f32 v241, v42, v43
	ds_write_b64 v180, v[240:241]
	v_cvt_pk_bf16_f32 v242, v44, v45
	v_cvt_pk_bf16_f32 v243, v46, v47
	ds_write_b64 v181, v[242:243]
	ds_read_b128 v[48:51], v196
	ds_read_b128 v[52:55], v196 offset:2048
	s_waitcnt lgkmcnt(0)
; DI int crow(int r, int hf) { return (r & 3) + 8 * (r >> 2) + 4 * hf; }
; DI void att_in_phase(const Params& p, int j, char* smem) {
;     ...
;         } else if (C64 == 1408) {
; #pragma unroll
;           for (int r = 0; r < 16; ++r) {
;             const int t = rb + crow(r, hf_), pos = t & (S_ - 1);
;             const float x = acc[i][0][r];
;             const float xp = __shfl_xor(x, 16);
;             const float2 cs = rt32[pos * 16 + (l32_ & 15)];
;             const float o = (l32_ < 16) ? (x * cs.x - xp * cs.y) : (x * cs.x + xp * cs.y);
;             const u16 v = f2bf(o);
; #pragma unroll
;             for (int h = 0; h < 8; ++h) Kb[(size_t)t * LDKB + h * 96 + 64 + l32_] = v;
;           }
	global_store_dwordx4 v197, v[48:51], s[38:39]
	global_store_dwordx4 v197, v[48:51], s[38:39] offset:192
	global_store_dwordx4 v197, v[48:51], s[38:39] offset:384
	global_store_dwordx4 v197, v[48:51], s[38:39] offset:576
	global_store_dwordx4 v197, v[48:51], s[38:39] offset:768
	global_store_dwordx4 v197, v[48:51], s[38:39] offset:960
	global_store_dwordx4 v197, v[48:51], s[38:39] offset:1152
	global_store_dwordx4 v197, v[48:51], s[38:39] offset:1344
	s_add_u32 s38, s38, 0x6800
	s_addc_u32 s39, s39, 0
	global_store_dwordx4 v197, v[52:55], s[38:39]
	global_store_dwordx4 v197, v[52:55], s[38:39] offset:192
	global_store_dwordx4 v197, v[52:55], s[38:39] offset:384
	global_store_dwordx4 v197, v[52:55], s[38:39] offset:576
	global_store_dwordx4 v197, v[52:55], s[38:39] offset:768
	global_store_dwordx4 v197, v[52:55], s[38:39] offset:960
	global_store_dwordx4 v197, v[52:55], s[38:39] offset:1152
	global_store_dwordx4 v197, v[52:55], s[38:39] offset:1344
	s_add_u32 s38, s38, 0x6800
	s_addc_u32 s39, s39, 0
	v_mul_f32_e32 v246, v72, v163
	v_mul_f32_e32 v247, v64, v163
	v_fma_f32 v64, v64, v162, -v246
	v_fma_f32 v72, v72, v162, v247
	v_mul_f32_e32 v246, v73, v165
	v_mul_f32_e32 v247, v65, v165
	v_fma_f32 v65, v65, v164, -v246
	v_fma_f32 v73, v73, v164, v247
	v_mul_f32_e32 v246, v74, v167
	v_mul_f32_e32 v247, v66, v167
	v_fma_f32 v66, v66, v166, -v246
	v_fma_f32 v74, v74, v166, v247
	v_mul_f32_e32 v246, v75, v169
	v_mul_f32_e32 v247, v67, v169
	v_fma_f32 v67, v67, v168, -v246
	v_fma_f32 v75, v75, v168, v247
	v_mul_f32_e32 v246, v76, v171
	v_mul_f32_e32 v247, v68, v171
	v_fma_f32 v68, v68, v170, -v246
	v_fma_f32 v76, v76, v170, v247
	v_mul_f32_e32 v246, v77, v173
	v_mul_f32_e32 v247, v69, v173
	v_fma_f32 v69, v69, v172, -v246
	v_fma_f32 v77, v77, v172, v247
	v_mul_f32_e32 v246, v78, v175
	v_mul_f32_e32 v247, v70, v175
	v_fma_f32 v70, v70, v174, -v246
	v_fma_f32 v78, v78, v174, v247
	v_mul_f32_e32 v246, v79, v177
	v_mul_f32_e32 v247, v71, v177
	v_fma_f32 v71, v71, v176, -v246
	v_fma_f32 v79, v79, v176, v247
	v_cvt_pk_bf16_f32 v244, v64, v65
	v_cvt_pk_bf16_f32 v245, v66, v67
	ds_write_b64 v178, v[244:245]
	v_cvt_pk_bf16_f32 v240, v68, v69
	v_cvt_pk_bf16_f32 v241, v70, v71
	ds_write_b64 v179, v[240:241]
	v_cvt_pk_bf16_f32 v242, v72, v73
	v_cvt_pk_bf16_f32 v243, v74, v75
	ds_write_b64 v180, v[242:243]
	v_cvt_pk_bf16_f32 v244, v76, v77
	v_cvt_pk_bf16_f32 v245, v78, v79
	ds_write_b64 v181, v[244:245]
	ds_read_b128 v[80:83], v196
	ds_read_b128 v[84:87], v196 offset:2048
	s_waitcnt lgkmcnt(0)
	global_store_dwordx4 v197, v[80:83], s[38:39]
	global_store_dwordx4 v197, v[80:83], s[38:39] offset:192
	global_store_dwordx4 v197, v[80:83], s[38:39] offset:384
	global_store_dwordx4 v197, v[80:83], s[38:39] offset:576
	global_store_dwordx4 v197, v[80:83], s[38:39] offset:768
	global_store_dwordx4 v197, v[80:83], s[38:39] offset:960
	global_store_dwordx4 v197, v[80:83], s[38:39] offset:1152
	global_store_dwordx4 v197, v[80:83], s[38:39] offset:1344
	s_add_u32 s38, s38, 0x6800
	s_addc_u32 s39, s39, 0
	global_store_dwordx4 v197, v[84:87], s[38:39]
	global_store_dwordx4 v197, v[84:87], s[38:39] offset:192
	global_store_dwordx4 v197, v[84:87], s[38:39] offset:384
	global_store_dwordx4 v197, v[84:87], s[38:39] offset:576
	global_store_dwordx4 v197, v[84:87], s[38:39] offset:768
	global_store_dwordx4 v197, v[84:87], s[38:39] offset:960
	global_store_dwordx4 v197, v[84:87], s[38:39] offset:1152
	global_store_dwordx4 v197, v[84:87], s[38:39] offset:1344
	s_add_u32 s38, s38, 0x6800
	s_addc_u32 s39, s39, 0
	v_mul_f32_e32 v246, v104, v225
	v_mul_f32_e32 v247, v96, v225
	v_fma_f32 v96, v96, v224, -v246
	v_fma_f32 v104, v104, v224, v247
	v_mul_f32_e32 v246, v105, v227
	v_mul_f32_e32 v247, v97, v227
	v_fma_f32 v97, v97, v226, -v246
	v_fma_f32 v105, v105, v226, v247
	v_mul_f32_e32 v246, v106, v229
	v_mul_f32_e32 v247, v98, v229
	v_fma_f32 v98, v98, v228, -v246
	v_fma_f32 v106, v106, v228, v247
	v_mul_f32_e32 v246, v107, v231
	v_mul_f32_e32 v247, v99, v231
	v_fma_f32 v99, v99, v230, -v246
	v_fma_f32 v107, v107, v230, v247
	v_mul_f32_e32 v246, v108, v233
	v_mul_f32_e32 v247, v100, v233
	v_fma_f32 v100, v100, v232, -v246
	v_fma_f32 v108, v108, v232, v247
	v_mul_f32_e32 v246, v109, v235
	v_mul_f32_e32 v247, v101, v235
	v_fma_f32 v101, v101, v234, -v246
	v_fma_f32 v109, v109, v234, v247
	v_mul_f32_e32 v246, v110, v237
	v_mul_f32_e32 v247, v102, v237
	v_fma_f32 v102, v102, v236, -v246
	v_fma_f32 v110, v110, v236, v247
	v_mul_f32_e32 v246, v111, v239
	v_mul_f32_e32 v247, v103, v239
	v_fma_f32 v103, v103, v238, -v246
	v_fma_f32 v111, v111, v238, v247
	v_cvt_pk_bf16_f32 v240, v96, v97
	v_cvt_pk_bf16_f32 v241, v98, v99
	ds_write_b64 v178, v[240:241]
	v_cvt_pk_bf16_f32 v242, v100, v101
	v_cvt_pk_bf16_f32 v243, v102, v103
	ds_write_b64 v179, v[242:243]
	v_cvt_pk_bf16_f32 v244, v104, v105
	v_cvt_pk_bf16_f32 v245, v106, v107
	ds_write_b64 v180, v[244:245]
	v_cvt_pk_bf16_f32 v240, v108, v109
	v_cvt_pk_bf16_f32 v241, v110, v111
	ds_write_b64 v181, v[240:241]
	ds_read_b128 v[112:115], v196
	ds_read_b128 v[116:119], v196 offset:2048
	s_waitcnt lgkmcnt(0)
	global_store_dwordx4 v197, v[112:115], s[38:39]
	global_store_dwordx4 v197, v[112:115], s[38:39] offset:192
	global_store_dwordx4 v197, v[112:115], s[38:39] offset:384
	global_store_dwordx4 v197, v[112:115], s[38:39] offset:576
	global_store_dwordx4 v197, v[112:115], s[38:39] offset:768
	global_store_dwordx4 v197, v[112:115], s[38:39] offset:960
	global_store_dwordx4 v197, v[112:115], s[38:39] offset:1152
	global_store_dwordx4 v197, v[112:115], s[38:39] offset:1344
	s_add_u32 s38, s38, 0x6800
	s_addc_u32 s39, s39, 0
	global_store_dwordx4 v197, v[116:119], s[38:39]
	global_store_dwordx4 v197, v[116:119], s[38:39] offset:192
	global_store_dwordx4 v197, v[116:119], s[38:39] offset:384
	global_store_dwordx4 v197, v[116:119], s[38:39] offset:576
	global_store_dwordx4 v197, v[116:119], s[38:39] offset:768
	global_store_dwordx4 v197, v[116:119], s[38:39] offset:960
	global_store_dwordx4 v197, v[116:119], s[38:39] offset:1152
	global_store_dwordx4 v197, v[116:119], s[38:39] offset:1344
	s_add_u32 s38, s38, 0x6800
	s_addc_u32 s39, s39, 0
	v_and_b32_e32 v245, 63, v182
	v_lshrrev_b32_e32 v244, 3, v245
	v_and_b32_e32 v243, 7, v245
	v_lshlrev_b32_e32 v196, 4, v243
	s_movk_i32 s10, 0x400
	v_mad_u32_u24 v196, v244, s10, v196
	v_lshlrev_b32_e32 v197, 4, v243
	s_movk_i32 s10, 0x100
	v_mad_u32_u24 v197, v244, s10, v197
.Lai_epi_done:
	s_waitcnt lgkmcnt(0)
	s_add_u32 s28, s28, s30
	s_cmp_lt_u32 s28, 0x60
	s_cbranch_scc1 .Lai_tile
	s_waitcnt vmcnt(0) lgkmcnt(0)
	s_cmp_lt_u32 s15, 4
	s_cbranch_scc0 .Lai_pp_trail
	s_barrier
.Lai_pp_trail:
.LBB0_708:
	v_readlane_b32 s56, v254, 14
	s_mov_b32 s59, 0x800000
	s_movk_i32 s58, 0x3000
	s_mov_b64 s[62:63], s[70:71]
	v_readlane_b32 s57, v254, 15

; DI void glu_phase(const Params& p, int j, char* smem) {
;     ...
;   for (int lt = blockIdx.x >> 3; lt < 16 * nN; lt += gridDim.x >> 3) {
; DI void run_phase(const Params& p, int ph, char* smem, int rep) {
;     ...
;   } else {
;     if (k == 0) { rec_in_phase(p, j, smem); s5_fill(p, j); }
;     else if (k == 1) rec_state_phase(p, j, smem);
;     else if (k == 2) scan_phase(p, j, smem);
;     else if (k == 3) rec_out_phase(p, j, smem);
;     else glu_phase(p, j, smem);
.LBB0_710:
	s_and_b64 vcc, exec, s[0:1]
	s_cbranch_vccz .LBB0_846
	v_readlane_b32 s0, v254, 24
	s_cmp_lt_i32 s0, 10
	s_mov_b64 s[0:1], -1
	s_cbranch_scc1 .LBB0_762
	v_readlane_b32 s0, v254, 24
	s_cmp_lt_i32 s0, 11
	s_mov_b64 s[0:1], -1
	s_cbranch_scc1 .LBB0_740
	v_readlane_b32 s0, v254, 24
	s_cmp_lg_u32 s0, 11
	s_mov_b64 s[0:1], -1
	s_cbranch_scc0 .LBB0_722
	v_readlane_b32 s4, v252, 7
	v_readlane_b32 s0, v251, 13
	v_readlane_b32 s5, v252, 8
	v_mov_b32_e32 v0, v182
	v_readlane_b32 s1, v251, 14
	s_andn2_b64 vcc, exec, s[4:5]
	s_cbranch_vccnz .LBB0_721
	v_readlane_b32 s68, v253, 62
	v_readlane_b32 s82, v254, 12
	v_readlane_b32 s83, v254, 13
	v_readlane_b32 s69, v253, 63
	v_readlane_b32 s70, v254, 0
	v_readlane_b32 s71, v254, 1
	v_readlane_b32 s72, v254, 2
	v_readlane_b32 s73, v254, 3
	v_readlane_b32 s74, v254, 4
	v_readlane_b32 s75, v254, 5
	v_readlane_b32 s76, v254, 6
	v_readlane_b32 s77, v254, 7
	v_readlane_b32 s78, v254, 8
	v_readlane_b32 s79, v254, 9
	v_readlane_b32 s80, v254, 10
	v_readlane_b32 s81, v254, 11
	v_readlane_b32 s28, v253, 48
	v_readlane_b32 s30, v253, 50
	s_cmp_ge_u32 s28, 0x20
	s_cbranch_scc1 .LBB0_721
; DI int opqv(int x) { asm volatile("" : "+v"(x)); return x; }
; DI char* opq(char* p) { asm volatile("" : "+s"(p)); return p; }
; #define RAWBAR() { asm volatile("s_waitcnt vmcnt(0) lgkmcnt(0)" ::: "memory"); __builtin_amdgcn_s_barrier(); }
;     ...
;   const int drow = lane >> 3, dslot = lane & 7, x7 = (l32 >> 1) & 7;
;     ...
;   if (V != 1) GLDS(0, 0);
;   RAWBAR();
; DI void glu_phase(const Params& p, int j, char* smem) {
;   const int tid = opqv(threadIdx.x), lane = tid & 63, w = tid >> 6, wm = w >> 2, wn = w & 3, l32 = lane & 31, hf = lane >> 5;
;   char* ws = opq(p.ws);
;   const u16* yt = (const u16*)(ws + OFF_YT);
;   const u16* Wt = (const u16*)(ws + OFF_W_GLU) + (size_t)j * 512 * LDGLU;
;   u16* o = (u16*)(ws + OFF_UO);
;   const float* gb = p.s5_glu_b + j * 512;
;   const int nN = 2;
;   for (int lt = blockIdx.x >> 3; lt < 16 * nN; lt += gridDim.x >> 3) {
;     int mt, nt; tile_map(lt, 16, nN, 16, 2, mt, nt);
;     const int m0 = mt * 256, n0 = nt * 256;
;     gemm_tile(yt + (size_t)m0 * LDYT, LDYT, 8, nullptr, 0, 0, Wt + (size_t)n0 * LDGLU, LDGLU, smem, [&](f32x16(&acc)[2][2], int moff) {
	s_add_u32 s6, s0, 0x8c04100
	s_addc_u32 s7, s1, 0
	v_readlane_b32 s10, v254, 25
	v_readlane_b32 s5, v251, 0
	s_mul_i32 s8, s10, 0x90000
	s_add_u32 s8, s0, s8
	s_addc_u32 s9, s1, 0
	s_add_u32 s8, s8, 0x2824100
	s_addc_u32 s9, s9, 0
	s_lshl_b32 s10, s10, 11
	s_add_u32 s10, s82, s10
	s_addc_u32 s11, s83, 0
	s_and_b32 s5, s5, 7
	s_lshl_b32 s5, s5, 4
	v_lshrrev_b32_e32 v228, 6, v182
	v_and_b32_e32 v229, 63, v182
	v_readfirstlane_b32 s15, v228
	v_and_b32_e32 v230, 31, v229
	v_lshrrev_b32_e32 v231, 5, v229
	v_lshrrev_b32_e32 v232, 3, v229
	v_and_b32_e32 v233, 7, v229
	s_lshr_b32 s12, s15, 2
	s_lshl_b32 s12, s12, 7
	s_and_b32 s13, s15, 3
	s_lshl_b32 s13, s13, 4
	s_add_u32 s20, s12, s13
	v_lshrrev_b32_e32 v234, 1, v232
	v_xor_b32_e32 v234, v233, v234
	v_lshlrev_b32_e32 v234, 4, v234
	s_add_u32 s29, s20, 0
	v_add_u32_e32 v235, s29, v232
	s_movk_i32 s29, 0x480
	v_mad_u32_u24 v220, v235, s29, v234
	v_lshrrev_b32_e32 v234, 1, v232
	v_add_u32_e32 v234, 4, v234
	v_xor_b32_e32 v234, v233, v234
	v_lshlrev_b32_e32 v234, 4, v234
	s_add_u32 s29, s20, 8
	v_add_u32_e32 v235, s29, v232
	s_movk_i32 s29, 0x480
	v_mad_u32_u24 v221, v235, s29, v234
	v_lshrrev_b32_e32 v234, 1, v232
	v_xor_b32_e32 v234, v233, v234
	v_lshlrev_b32_e32 v234, 4, v234
	s_add_u32 s29, s20, 64
	v_add_u32_e32 v235, s29, v232
	s_movk_i32 s29, 0x480
	v_mad_u32_u24 v222, v235, s29, v234
	v_lshrrev_b32_e32 v234, 1, v232
	v_add_u32_e32 v234, 4, v234
	v_xor_b32_e32 v234, v233, v234
	v_lshlrev_b32_e32 v234, 4, v234
	s_add_u32 s29, s20, 72
	v_add_u32_e32 v235, s29, v232
	s_movk_i32 s29, 0x480
	v_mad_u32_u24 v223, v235, s29, v234
	v_and_b32_e32 v244, 63, v182
	v_lshrrev_b32_e32 v245, 3, v244
	v_and_b32_e32 v246, 7, v244
	s_lshr_b32 s12, s15, 2
	s_lshl_b32 s12, s12, 1
	s_bfe_u32 s13, s15, 0x10001
	s_add_u32 s12, s12, s13
	s_lshl_b32 s12, s12, 6
	s_and_b32 s13, s15, 1
	s_lshl_b32 s13, s13, 4
	s_add_u32 s12, s12, s13
	v_lshrrev_b32_e32 v247, 1, v245
	v_xor_b32_e32 v247, v246, v247
	v_lshlrev_b32_e32 v247, 4, v247
	s_add_u32 s13, s12, 0
	v_add_u32_e32 v244, s13, v245
	s_movk_i32 s13, 0x480
	v_mad_u32_u24 v240, v244, s13, v247
	v_lshrrev_b32_e32 v247, 1, v245
	v_add_u32_e32 v247, 4, v247
	v_xor_b32_e32 v247, v246, v247
	v_lshlrev_b32_e32 v247, 4, v247
	s_add_u32 s13, s12, 8
	v_add_u32_e32 v244, s13, v245
	s_movk_i32 s13, 0x480
	v_mad_u32_u24 v241, v244, s13, v247
	v_lshrrev_b32_e32 v247, 1, v245
	v_xor_b32_e32 v247, v246, v247
	v_lshlrev_b32_e32 v247, 4, v247
	s_add_u32 s13, s12, 32
	v_add_u32_e32 v244, s13, v245
	s_movk_i32 s13, 0x480
	v_mad_u32_u24 v242, v244, s13, v247
	v_lshrrev_b32_e32 v247, 1, v245
	v_add_u32_e32 v247, 4, v247
	v_xor_b32_e32 v247, v246, v247
	v_lshlrev_b32_e32 v247, 4, v247
	s_add_u32 s13, s12, 40
	v_add_u32_e32 v244, s13, v245
	s_movk_i32 s13, 0x480
	v_mad_u32_u24 v243, v244, s13, v247
	v_lshrrev_b32_e32 v236, 1, v230
	v_and_b32_e32 v236, 7, v236
	s_lshr_b32 s12, s15, 2
	s_and_b32 s13, s15, 3
	s_lshl_b32 s20, s12, 14
	s_add_u32 s20, s20, 32
	s_lshr_b32 s29, s13, 1
	s_lshl_b32 s29, s29, 14
	s_add_u32 s29, s29, 0x8020
	v_lshlrev_b32_e32 v237, 7, v230
	v_add_u32_e32 v238, s29, v237
	s_and_b32 s29, s13, 1
	s_lshl_b32 s29, s29, 12
	v_add_u32_e32 v238, s29, v238
	v_add_u32_e32 v237, s20, v237
	v_add_u32_e32 v239, 0, v231
	v_xor_b32_e32 v239, v239, v236
	v_lshlrev_b32_e32 v239, 4, v239
	v_add_u32_e32 v204, v237, v239
	v_add_u32_e32 v212, v238, v239
	v_add_u32_e32 v208, 0x10000, v204
	v_add_u32_e32 v216, 0x10000, v212
	v_add_u32_e32 v239, 2, v231
	v_xor_b32_e32 v239, v239, v236
	v_lshlrev_b32_e32 v239, 4, v239
	v_add_u32_e32 v205, v237, v239
	v_add_u32_e32 v213, v238, v239
	v_add_u32_e32 v209, 0x10000, v205
	v_add_u32_e32 v217, 0x10000, v213
	v_add_u32_e32 v239, 4, v231
	v_xor_b32_e32 v239, v239, v236
	v_lshlrev_b32_e32 v239, 4, v239
	v_add_u32_e32 v206, v237, v239
	v_add_u32_e32 v214, v238, v239
	v_add_u32_e32 v210, 0x10000, v206
	v_add_u32_e32 v218, 0x10000, v214
	v_add_u32_e32 v239, 6, v231
	v_xor_b32_e32 v239, v239, v236
	v_lshlrev_b32_e32 v239, 4, v239
	v_add_u32_e32 v207, v237, v239
	v_add_u32_e32 v215, v238, v239
	v_add_u32_e32 v211, 0x10000, v207
	v_add_u32_e32 v219, 0x10000, v215
	s_lshl_b32 s20, s15, 12
	s_add_u32 s20, s20, 0x18020
	v_lshlrev_b32_e32 v234, 7, v230
	v_lshlrev_b32_e32 v235, 3, v231
	v_add3_u32 v234, v234, v235, s20
	v_and_b32_e32 v235, 7, v230
	v_mov_b32_e32 v178, v235
	v_xor_b32_e32 v179, 1, v235
	v_xor_b32_e32 v180, 2, v235
	v_xor_b32_e32 v181, 3, v235
	v_xor_b32_e32 v188, 4, v235
	v_xor_b32_e32 v189, 5, v235
	v_xor_b32_e32 v190, 6, v235
	v_xor_b32_e32 v191, 7, v235
	v_lshl_add_u32 v178, v178, 4, v234
	v_lshl_add_u32 v179, v179, 4, v234
	v_lshl_add_u32 v180, v180, 4, v234
	v_lshl_add_u32 v181, v181, 4, v234
	v_lshl_add_u32 v188, v188, 4, v234
	v_lshl_add_u32 v189, v189, 4, v234
	v_lshl_add_u32 v190, v190, 4, v234
	v_lshl_add_u32 v191, v191, 4, v234
	v_xor_b32_e32 v194, v232, v233
	v_lshlrev_b32_e32 v194, 4, v194
	v_lshl_add_u32 v194, v232, 7, v194
	v_add_u32_e32 v194, s20, v194
	s_lshl_b32 s14, s12, 14
	s_lshl_b32 s20, s13, 11
	s_add_u32 s14, s14, s20
	s_add_u32 s14, s14, 32
	v_lshlrev_b32_e32 v195, 4, v233
	s_movk_i32 s20, 0x880
	v_mad_u32_u24 v195, v232, s20, v195
	v_lshlrev_b32_e32 v196, 4, v231
	v_lshlrev_b32_e32 v197, 3, v231
	s_movk_i32 s20, 0x480
	v_mad_u32_u24 v197, v230, s20, v197
	s_mov_b32 s27, s28
	s_mov_b32 s26, 0
	s_lshr_b32 s12, s27, 1
	s_add_u32 s12, s12, s5
	s_mul_i32 s12, s12, 0x48000
	s_add_u32 s22, s6, s12
	s_addc_u32 s23, s7, 0
	s_and_b32 s12, s27, 1
	s_mul_i32 s12, s12, 0x48000
	s_add_u32 s24, s8, s12
	s_addc_u32 s25, s9, 0
	s_add_u32 m0, s14, 0x8000
	s_nop 0
	global_load_lds_dwordx4 v240, s[24:25]
	s_add_u32 m0, s14, 0x8400
	s_nop 0
	global_load_lds_dwordx4 v241, s[24:25]
	s_add_u32 m0, s14, 0x0
	s_nop 0
	global_load_lds_dwordx4 v220, s[22:23]
	s_add_u32 m0, s14, 0x400
	s_nop 0
	global_load_lds_dwordx4 v221, s[22:23]
	s_add_u32 m0, s14, 0xa000
	s_nop 0
	global_load_lds_dwordx4 v242, s[24:25]
	s_add_u32 m0, s14, 0xa400
	s_nop 0
	global_load_lds_dwordx4 v243, s[24:25]
	s_add_u32 m0, s14, 0x2000
	s_nop 0
	global_load_lds_dwordx4 v222, s[22:23]
	s_add_u32 m0, s14, 0x2400
	s_nop 0
	global_load_lds_dwordx4 v223, s[22:23]
	s_add_u32 s22, s22, 0x80
	s_addc_u32 s23, s23, 0
	s_add_u32 s24, s24, 0x80
	s_addc_u32 s25, s25, 0
	s_add_u32 s26, s26, 1
	s_cmp_eq_u32 s26, 8
	s_cbranch_scc0 .Lgl1_cadv_done
	s_mov_b32 s26, 0
	s_add_u32 s27, s27, s30
	s_cmp_lt_u32 s27, 0x20
	s_cbranch_scc1 .Lgl1_cadv_new
	s_sub_u32 s22, s22, 0x400
	s_subb_u32 s23, s23, 0
	s_sub_u32 s24, s24, 0x400
	s_subb_u32 s25, s25, 0
	s_branch .Lgl1_cadv_done
.Lgl1_cadv_new:
	s_lshr_b32 s12, s27, 1
	s_add_u32 s12, s12, s5
	s_mul_i32 s12, s12, 0x48000
	s_add_u32 s22, s6, s12
	s_addc_u32 s23, s7, 0
	s_and_b32 s12, s27, 1
	s_mul_i32 s12, s12, 0x48000
	s_add_u32 s24, s8, s12
	s_addc_u32 s25, s9, 0
.Lgl1_cadv_done:
	s_cmp_lt_u32 s15, 4
	s_cbranch_scc1 .Lgl_pp_lead
	s_barrier

; #define RAWBAR() { asm volatile("s_waitcnt vmcnt(0) lgkmcnt(0)" ::: "memory"); __builtin_amdgcn_s_barrier(); }
;     ...
;   if (V != 1) GLDS(0, 0);
;   RAWBAR();
;   for (int kt = 0; kt < nk; kt += 2) {
;     if (V != 1) GLDS(kt + 1, 1);
.Lgl_tile:
	v_and_b32_e32 v244, 63, v182
	v_lshrrev_b32_e32 v245, 3, v244
	v_and_b32_e32 v246, 7, v244
	s_lshr_b32 s12, s15, 2
	s_lshl_b32 s12, s12, 1
	s_bfe_u32 s13, s15, 0x10001
	s_add_u32 s12, s12, s13
	s_lshl_b32 s12, s12, 6
	s_and_b32 s13, s15, 1
	s_lshl_b32 s13, s13, 4
	s_add_u32 s12, s12, s13
	v_lshrrev_b32_e32 v247, 1, v245
	v_xor_b32_e32 v247, v246, v247
	v_lshlrev_b32_e32 v247, 4, v247
	s_add_u32 s13, s12, 0
	v_add_u32_e32 v244, s13, v245
	s_movk_i32 s13, 0x480
	v_mad_u32_u24 v240, v244, s13, v247
	v_lshrrev_b32_e32 v247, 1, v245
	v_add_u32_e32 v247, 4, v247
	v_xor_b32_e32 v247, v246, v247
	v_lshlrev_b32_e32 v247, 4, v247
	s_add_u32 s13, s12, 8
	v_add_u32_e32 v244, s13, v245
	s_movk_i32 s13, 0x480
	v_mad_u32_u24 v241, v244, s13, v247
	v_lshrrev_b32_e32 v247, 1, v245
	v_xor_b32_e32 v247, v246, v247
	v_lshlrev_b32_e32 v247, 4, v247
	s_add_u32 s13, s12, 32
	v_add_u32_e32 v244, s13, v245
	s_movk_i32 s13, 0x480
	v_mad_u32_u24 v242, v244, s13, v247
	v_lshrrev_b32_e32 v247, 1, v245
	v_add_u32_e32 v247, 4, v247
	v_xor_b32_e32 v247, v246, v247
	v_lshlrev_b32_e32 v247, 4, v247
	s_add_u32 s13, s12, 40
	v_add_u32_e32 v244, s13, v245
	s_movk_i32 s13, 0x480
	v_mad_u32_u24 v243, v244, s13, v247
	s_add_u32 m0, s14, 0x12000
	ds_read_b128 v[162:165], v212
	ds_read_b128 v[166:169], v213
	ds_read_b128 v[170:173], v214
	ds_read_b128 v[174:177], v215
	global_load_lds_dwordx4 v222, s[22:23]
	s_add_u32 m0, s14, 0x12400
	ds_read_b128 v[128:131], v204
	ds_read_b128 v[132:135], v205
	ds_read_b128 v[136:139], v206
	ds_read_b128 v[140:143], v207
	global_load_lds_dwordx4 v223, s[22:23]
	ds_read_b128 v[144:147], v204 offset:4096
	ds_read_b128 v[148:151], v205 offset:4096
	ds_read_b128 v[152:155], v206 offset:4096
	ds_read_b128 v[156:159], v207 offset:4096
	s_add_u32 s22, s22, 0x80
	s_addc_u32 s23, s23, 0
	s_add_u32 s24, s24, 0x80
	s_addc_u32 s25, s25, 0
	s_add_u32 s26, s26, 1
	s_cmp_eq_u32 s26, 8
	s_cbranch_scc0 .Lgl2_cadv_done
	s_mov_b32 s26, 0
	s_add_u32 s27, s27, s30
	s_cmp_lt_u32 s27, 0x20
	s_cbranch_scc1 .Lgl2_cadv_new
	s_sub_u32 s22, s22, 0x400
	s_subb_u32 s23, s23, 0
	s_sub_u32 s24, s24, 0x400
	s_subb_u32 s25, s25, 0
	s_branch .Lgl2_cadv_done

; #define RAWBAR() { asm volatile("s_waitcnt vmcnt(0) lgkmcnt(0)" ::: "memory"); __builtin_amdgcn_s_barrier(); }
;     ...
;   if (V != 1) GLDS(0, 0);
;   RAWBAR();
;   for (int kt = 0; kt < nk; kt += 2) {
;     if (V != 1) GLDS(kt + 1, 1);
;     if (V != 2) COMPUTE(0);
;     RAWBAR();
;     if (V != 1) if (kt + 2 < nk) GLDS(kt + 2, 0);
;     if (V != 2) COMPUTE(1);
;     RAWBAR();
.Lgl2_cadv_done:
	s_waitcnt lgkmcnt(8)
	s_barrier
	s_waitcnt lgkmcnt(0)
	s_setprio 1
	v_mfma_f32_32x32x16_bf16 v[0:15], v[162:165], v[128:131], 0
	v_mfma_f32_32x32x16_bf16 v[32:47], v[162:165], v[144:147], 0
	v_mfma_f32_32x32x16_bf16 v[0:15], v[166:169], v[132:135], v[0:15]
	v_mfma_f32_32x32x16_bf16 v[32:47], v[166:169], v[148:151], v[32:47]
	v_mfma_f32_32x32x16_bf16 v[0:15], v[170:173], v[136:139], v[0:15]
	v_mfma_f32_32x32x16_bf16 v[32:47], v[170:173], v[152:155], v[32:47]
	v_mfma_f32_32x32x16_bf16 v[0:15], v[174:177], v[140:143], v[0:15]
	v_mfma_f32_32x32x16_bf16 v[32:47], v[174:177], v[156:159], v[32:47]
	s_setprio 0
	s_barrier
	s_add_u32 m0, s14, 0x18080
	ds_read_b128 v[224:227], v212 offset:8192
	global_load_lds_dwordx4 v240, s[24:25] offset:-128
	s_add_u32 m0, s14, 0x18480
	ds_read_b128 v[228:231], v213 offset:8192
	global_load_lds_dwordx4 v241, s[24:25] offset:-128
	s_add_u32 m0, s14, 0x1a080
	ds_read_b128 v[232:235], v214 offset:8192
	global_load_lds_dwordx4 v242, s[24:25] offset:-128
	s_add_u32 m0, s14, 0x1a480
	ds_read_b128 v[236:239], v215 offset:8192
	global_load_lds_dwordx4 v243, s[24:25] offset:-128
	s_add_u32 m0, s14, 0x8000
	s_nop 0
	global_load_lds_dwordx4 v240, s[24:25]
	s_add_u32 m0, s14, 0x8400
	s_nop 0
	global_load_lds_dwordx4 v241, s[24:25]
	s_barrier
	s_waitcnt lgkmcnt(0)
	s_setprio 1
	v_mfma_f32_32x32x16_bf16 v[16:31], v[224:227], v[128:131], 0
	v_mfma_f32_32x32x16_bf16 v[48:63], v[224:227], v[144:147], 0
	v_mfma_f32_32x32x16_bf16 v[16:31], v[228:231], v[132:135], v[16:31]
	v_mfma_f32_32x32x16_bf16 v[48:63], v[228:231], v[148:151], v[48:63]
	v_mfma_f32_32x32x16_bf16 v[16:31], v[232:235], v[136:139], v[16:31]
	v_mfma_f32_32x32x16_bf16 v[48:63], v[232:235], v[152:155], v[48:63]
	v_mfma_f32_32x32x16_bf16 v[16:31], v[236:239], v[140:143], v[16:31]
	v_mfma_f32_32x32x16_bf16 v[48:63], v[236:239], v[156:159], v[48:63]
	s_setprio 0
	s_barrier
	s_add_u32 m0, s14, 0x0
	ds_read_b128 v[128:131], v204 offset:8192
	ds_read_b128 v[132:135], v205 offset:8192
	global_load_lds_dwordx4 v220, s[22:23]
	s_add_u32 m0, s14, 0x400
	ds_read_b128 v[136:139], v206 offset:8192
	ds_read_b128 v[140:143], v207 offset:8192
	global_load_lds_dwordx4 v221, s[22:23]
	ds_read_b128 v[144:147], v204 offset:12288
	ds_read_b128 v[148:151], v205 offset:12288
	ds_read_b128 v[152:155], v206 offset:12288
	ds_read_b128 v[156:159], v207 offset:12288
	s_barrier
	s_waitcnt lgkmcnt(0)
	s_setprio 1
	v_mfma_f32_32x32x16_bf16 v[64:79], v[162:165], v[128:131], 0
	v_mfma_f32_32x32x16_bf16 v[96:111], v[162:165], v[144:147], 0
	v_mfma_f32_32x32x16_bf16 v[64:79], v[166:169], v[132:135], v[64:79]
	v_mfma_f32_32x32x16_bf16 v[96:111], v[166:169], v[148:151], v[96:111]
	v_mfma_f32_32x32x16_bf16 v[64:79], v[170:173], v[136:139], v[64:79]
	v_mfma_f32_32x32x16_bf16 v[96:111], v[170:173], v[152:155], v[96:111]
	v_mfma_f32_32x32x16_bf16 v[64:79], v[174:177], v[140:143], v[64:79]
	v_mfma_f32_32x32x16_bf16 v[96:111], v[174:177], v[156:159], v[96:111]
	s_setprio 0
	s_barrier
	s_add_u32 m0, s14, 0xa000
	s_nop 0
	global_load_lds_dwordx4 v242, s[24:25]
	s_add_u32 m0, s14, 0xa400
	s_nop 0
	global_load_lds_dwordx4 v243, s[24:25]
	s_waitcnt vmcnt(6)
	s_barrier
	s_setprio 1
	v_mfma_f32_32x32x16_bf16 v[80:95], v[224:227], v[128:131], 0
	v_mfma_f32_32x32x16_bf16 v[112:127], v[224:227], v[144:147], 0
	v_mfma_f32_32x32x16_bf16 v[80:95], v[228:231], v[132:135], v[80:95]
	v_mfma_f32_32x32x16_bf16 v[112:127], v[228:231], v[148:151], v[112:127]
	v_mfma_f32_32x32x16_bf16 v[80:95], v[232:235], v[136:139], v[80:95]
	v_mfma_f32_32x32x16_bf16 v[112:127], v[232:235], v[152:155], v[112:127]
	v_mfma_f32_32x32x16_bf16 v[80:95], v[236:239], v[140:143], v[80:95]
	v_mfma_f32_32x32x16_bf16 v[112:127], v[236:239], v[156:159], v[112:127]
	s_setprio 0
	s_barrier
	s_add_u32 m0, s14, 0x2000
	ds_read_b128 v[162:165], v216
	ds_read_b128 v[166:169], v217
	ds_read_b128 v[170:173], v218
	ds_read_b128 v[174:177], v219
	global_load_lds_dwordx4 v222, s[22:23]
	s_add_u32 m0, s14, 0x2400
	ds_read_b128 v[128:131], v208
	ds_read_b128 v[132:135], v209
	ds_read_b128 v[136:139], v210
	ds_read_b128 v[140:143], v211
	global_load_lds_dwordx4 v223, s[22:23]
	ds_read_b128 v[144:147], v208 offset:4096
	ds_read_b128 v[148:151], v209 offset:4096
	ds_read_b128 v[152:155], v210 offset:4096
	ds_read_b128 v[156:159], v211 offset:4096
	s_add_u32 s22, s22, 0x80
	s_addc_u32 s23, s23, 0
	s_add_u32 s24, s24, 0x80
	s_addc_u32 s25, s25, 0
	s_add_u32 s26, s26, 1
	s_cmp_eq_u32 s26, 8
	s_cbranch_scc0 .Lgl3_cadv_done
	s_mov_b32 s26, 0
	s_add_u32 s27, s27, s30
	s_cmp_lt_u32 s27, 0x20
	s_cbranch_scc1 .Lgl3_cadv_new
	s_sub_u32 s22, s22, 0x400
	s_subb_u32 s23, s23, 0
	s_sub_u32 s24, s24, 0x400
	s_subb_u32 s25, s25, 0
	s_branch .Lgl3_cadv_done

; #define RAWBAR() { asm volatile("s_waitcnt vmcnt(0) lgkmcnt(0)" ::: "memory"); __builtin_amdgcn_s_barrier(); }
;     ...
;   if (V != 1) GLDS(0, 0);
;   RAWBAR();
;   for (int kt = 0; kt < nk; kt += 2) {
;     if (V != 1) GLDS(kt + 1, 1);
;     if (V != 2) COMPUTE(0);
;     RAWBAR();
;     if (V != 1) if (kt + 2 < nk) GLDS(kt + 2, 0);
;     if (V != 2) COMPUTE(1);
;     RAWBAR();
.Lgl3_cadv_done:
	s_waitcnt lgkmcnt(8)
	s_barrier
	s_waitcnt lgkmcnt(0)
	s_setprio 1
	v_mfma_f32_32x32x16_bf16 v[0:15], v[162:165], v[128:131], v[0:15]
	v_mfma_f32_32x32x16_bf16 v[32:47], v[162:165], v[144:147], v[32:47]
	v_mfma_f32_32x32x16_bf16 v[0:15], v[166:169], v[132:135], v[0:15]
	v_mfma_f32_32x32x16_bf16 v[32:47], v[166:169], v[148:151], v[32:47]
	v_mfma_f32_32x32x16_bf16 v[0:15], v[170:173], v[136:139], v[0:15]
	v_mfma_f32_32x32x16_bf16 v[32:47], v[170:173], v[152:155], v[32:47]
	v_mfma_f32_32x32x16_bf16 v[0:15], v[174:177], v[140:143], v[0:15]
	v_mfma_f32_32x32x16_bf16 v[32:47], v[174:177], v[156:159], v[32:47]
	s_setprio 0
	s_barrier
	s_add_u32 m0, s14, 0x18000
	ds_read_b128 v[224:227], v216 offset:8192
	global_load_lds_dwordx4 v240, s[24:25]
	s_add_u32 m0, s14, 0x18400
	ds_read_b128 v[228:231], v217 offset:8192
	global_load_lds_dwordx4 v241, s[24:25]
	ds_read_b128 v[232:235], v218 offset:8192
	ds_read_b128 v[236:239], v219 offset:8192
	s_barrier
	s_waitcnt lgkmcnt(0)
	s_setprio 1
	v_mfma_f32_32x32x16_bf16 v[16:31], v[224:227], v[128:131], v[16:31]
	v_mfma_f32_32x32x16_bf16 v[48:63], v[224:227], v[144:147], v[48:63]
	v_mfma_f32_32x32x16_bf16 v[16:31], v[228:231], v[132:135], v[16:31]
	v_mfma_f32_32x32x16_bf16 v[48:63], v[228:231], v[148:151], v[48:63]
	v_mfma_f32_32x32x16_bf16 v[16:31], v[232:235], v[136:139], v[16:31]
	v_mfma_f32_32x32x16_bf16 v[48:63], v[232:235], v[152:155], v[48:63]
	v_mfma_f32_32x32x16_bf16 v[16:31], v[236:239], v[140:143], v[16:31]
	v_mfma_f32_32x32x16_bf16 v[48:63], v[236:239], v[156:159], v[48:63]
	s_setprio 0
	s_barrier
	s_add_u32 m0, s14, 0x10000
	ds_read_b128 v[128:131], v208 offset:8192
	ds_read_b128 v[132:135], v209 offset:8192
	global_load_lds_dwordx4 v220, s[22:23]
	s_add_u32 m0, s14, 0x10400
	ds_read_b128 v[136:139], v210 offset:8192
	ds_read_b128 v[140:143], v211 offset:8192
	global_load_lds_dwordx4 v221, s[22:23]
	ds_read_b128 v[144:147], v208 offset:12288
	ds_read_b128 v[148:151], v209 offset:12288
	ds_read_b128 v[152:155], v210 offset:12288
	ds_read_b128 v[156:159], v211 offset:12288
	s_barrier
	s_waitcnt lgkmcnt(0)
	s_setprio 1
	v_mfma_f32_32x32x16_bf16 v[64:79], v[162:165], v[128:131], v[64:79]
	v_mfma_f32_32x32x16_bf16 v[96:111], v[162:165], v[144:147], v[96:111]
	v_mfma_f32_32x32x16_bf16 v[64:79], v[166:169], v[132:135], v[64:79]
	v_mfma_f32_32x32x16_bf16 v[96:111], v[166:169], v[148:151], v[96:111]
	v_mfma_f32_32x32x16_bf16 v[64:79], v[170:173], v[136:139], v[64:79]
	v_mfma_f32_32x32x16_bf16 v[96:111], v[170:173], v[152:155], v[96:111]
	v_mfma_f32_32x32x16_bf16 v[64:79], v[174:177], v[140:143], v[64:79]
	v_mfma_f32_32x32x16_bf16 v[96:111], v[174:177], v[156:159], v[96:111]
	s_setprio 0
	s_barrier
	s_add_u32 m0, s14, 0x1a000
	s_nop 0
	global_load_lds_dwordx4 v242, s[24:25]
	s_add_u32 m0, s14, 0x1a400
	s_nop 0
	global_load_lds_dwordx4 v243, s[24:25]
	s_waitcnt vmcnt(6)
	s_barrier
	s_setprio 1
	v_mfma_f32_32x32x16_bf16 v[80:95], v[224:227], v[128:131], v[80:95]
	v_mfma_f32_32x32x16_bf16 v[112:127], v[224:227], v[144:147], v[112:127]
	v_mfma_f32_32x32x16_bf16 v[80:95], v[228:231], v[132:135], v[80:95]
	v_mfma_f32_32x32x16_bf16 v[112:127], v[228:231], v[148:151], v[112:127]
	v_mfma_f32_32x32x16_bf16 v[80:95], v[232:235], v[136:139], v[80:95]
	v_mfma_f32_32x32x16_bf16 v[112:127], v[232:235], v[152:155], v[112:127]
	v_mfma_f32_32x32x16_bf16 v[80:95], v[236:239], v[140:143], v[80:95]
	v_mfma_f32_32x32x16_bf16 v[112:127], v[236:239], v[156:159], v[112:127]
	s_setprio 0
	s_barrier
	s_mov_b32 s31, 2
	s_cmp_eq_u32 s31, 0
	s_cbranch_scc1 .Lgl_pairs_done
.Lgl_pair:
	s_add_u32 m0, s14, 0x12000
	ds_read_b128 v[162:165], v212
	ds_read_b128 v[166:169], v213
	ds_read_b128 v[170:173], v214
	ds_read_b128 v[174:177], v215
	global_load_lds_dwordx4 v222, s[22:23]
	s_add_u32 m0, s14, 0x12400
	ds_read_b128 v[128:131], v204
	ds_read_b128 v[132:135], v205
	ds_read_b128 v[136:139], v206
	ds_read_b128 v[140:143], v207
	global_load_lds_dwordx4 v223, s[22:23]
	ds_read_b128 v[144:147], v204 offset:4096
	ds_read_b128 v[148:151], v205 offset:4096
	ds_read_b128 v[152:155], v206 offset:4096
	ds_read_b128 v[156:159], v207 offset:4096
	s_add_u32 s22, s22, 0x80
	s_addc_u32 s23, s23, 0
	s_add_u32 s24, s24, 0x80
	s_addc_u32 s25, s25, 0
	s_add_u32 s26, s26, 1
	s_cmp_eq_u32 s26, 8
	s_cbranch_scc0 .Lgl4_cadv_done
	s_mov_b32 s26, 0
	s_add_u32 s27, s27, s30
	s_cmp_lt_u32 s27, 0x20
	s_cbranch_scc1 .Lgl4_cadv_new
	s_sub_u32 s22, s22, 0x400
	s_subb_u32 s23, s23, 0
	s_sub_u32 s24, s24, 0x400
	s_subb_u32 s25, s25, 0
	s_branch .Lgl4_cadv_done

; #define RAWBAR() { asm volatile("s_waitcnt vmcnt(0) lgkmcnt(0)" ::: "memory"); __builtin_amdgcn_s_barrier(); }
;     ...
;   if (V != 1) GLDS(0, 0);
;   RAWBAR();
;   for (int kt = 0; kt < nk; kt += 2) {
;     if (V != 1) GLDS(kt + 1, 1);
;     if (V != 2) COMPUTE(0);
;     RAWBAR();
;     if (V != 1) if (kt + 2 < nk) GLDS(kt + 2, 0);
;     if (V != 2) COMPUTE(1);
;     RAWBAR();
.Lgl4_cadv_done:
	s_waitcnt lgkmcnt(8)
	s_barrier
	s_waitcnt lgkmcnt(0)
	s_setprio 1
	v_mfma_f32_32x32x16_bf16 v[0:15], v[162:165], v[128:131], v[0:15]
	v_mfma_f32_32x32x16_bf16 v[32:47], v[162:165], v[144:147], v[32:47]
	v_mfma_f32_32x32x16_bf16 v[0:15], v[166:169], v[132:135], v[0:15]
	v_mfma_f32_32x32x16_bf16 v[32:47], v[166:169], v[148:151], v[32:47]
	v_mfma_f32_32x32x16_bf16 v[0:15], v[170:173], v[136:139], v[0:15]
	v_mfma_f32_32x32x16_bf16 v[32:47], v[170:173], v[152:155], v[32:47]
	v_mfma_f32_32x32x16_bf16 v[0:15], v[174:177], v[140:143], v[0:15]
	v_mfma_f32_32x32x16_bf16 v[32:47], v[174:177], v[156:159], v[32:47]
	s_setprio 0
	s_barrier
	s_add_u32 m0, s14, 0x8000
	ds_read_b128 v[224:227], v212 offset:8192
	global_load_lds_dwordx4 v240, s[24:25]
	s_add_u32 m0, s14, 0x8400
	ds_read_b128 v[228:231], v213 offset:8192
	global_load_lds_dwordx4 v241, s[24:25]
	ds_read_b128 v[232:235], v214 offset:8192
	ds_read_b128 v[236:239], v215 offset:8192
	s_barrier
	s_waitcnt lgkmcnt(0)
	s_setprio 1
	v_mfma_f32_32x32x16_bf16 v[16:31], v[224:227], v[128:131], v[16:31]
	v_mfma_f32_32x32x16_bf16 v[48:63], v[224:227], v[144:147], v[48:63]
	v_mfma_f32_32x32x16_bf16 v[16:31], v[228:231], v[132:135], v[16:31]
	v_mfma_f32_32x32x16_bf16 v[48:63], v[228:231], v[148:151], v[48:63]
	v_mfma_f32_32x32x16_bf16 v[16:31], v[232:235], v[136:139], v[16:31]
	v_mfma_f32_32x32x16_bf16 v[48:63], v[232:235], v[152:155], v[48:63]
	v_mfma_f32_32x32x16_bf16 v[16:31], v[236:239], v[140:143], v[16:31]
	v_mfma_f32_32x32x16_bf16 v[48:63], v[236:239], v[156:159], v[48:63]
	s_setprio 0
	s_barrier
	s_add_u32 m0, s14, 0x0
	ds_read_b128 v[128:131], v204 offset:8192
	ds_read_b128 v[132:135], v205 offset:8192
	global_load_lds_dwordx4 v220, s[22:23]
	s_add_u32 m0, s14, 0x400
	ds_read_b128 v[136:139], v206 offset:8192
	ds_read_b128 v[140:143], v207 offset:8192
	global_load_lds_dwordx4 v221, s[22:23]
	ds_read_b128 v[144:147], v204 offset:12288
	ds_read_b128 v[148:151], v205 offset:12288
	ds_read_b128 v[152:155], v206 offset:12288
	ds_read_b128 v[156:159], v207 offset:12288
	s_barrier
	s_waitcnt lgkmcnt(0)
	s_setprio 1
	v_mfma_f32_32x32x16_bf16 v[64:79], v[162:165], v[128:131], v[64:79]
	v_mfma_f32_32x32x16_bf16 v[96:111], v[162:165], v[144:147], v[96:111]
	v_mfma_f32_32x32x16_bf16 v[64:79], v[166:169], v[132:135], v[64:79]
	v_mfma_f32_32x32x16_bf16 v[96:111], v[166:169], v[148:151], v[96:111]
	v_mfma_f32_32x32x16_bf16 v[64:79], v[170:173], v[136:139], v[64:79]
	v_mfma_f32_32x32x16_bf16 v[96:111], v[170:173], v[152:155], v[96:111]
	v_mfma_f32_32x32x16_bf16 v[64:79], v[174:177], v[140:143], v[64:79]
	v_mfma_f32_32x32x16_bf16 v[96:111], v[174:177], v[156:159], v[96:111]
	s_setprio 0
	s_barrier
	s_add_u32 m0, s14, 0xa000
	s_nop 0
	global_load_lds_dwordx4 v242, s[24:25]
	s_add_u32 m0, s14, 0xa400
	s_nop 0
	global_load_lds_dwordx4 v243, s[24:25]
	s_waitcnt vmcnt(6)
	s_barrier
	s_setprio 1
	v_mfma_f32_32x32x16_bf16 v[80:95], v[224:227], v[128:131], v[80:95]
	v_mfma_f32_32x32x16_bf16 v[112:127], v[224:227], v[144:147], v[112:127]
	v_mfma_f32_32x32x16_bf16 v[80:95], v[228:231], v[132:135], v[80:95]
	v_mfma_f32_32x32x16_bf16 v[112:127], v[228:231], v[148:151], v[112:127]
	v_mfma_f32_32x32x16_bf16 v[80:95], v[232:235], v[136:139], v[80:95]
	v_mfma_f32_32x32x16_bf16 v[112:127], v[232:235], v[152:155], v[112:127]
	v_mfma_f32_32x32x16_bf16 v[80:95], v[236:239], v[140:143], v[80:95]
	v_mfma_f32_32x32x16_bf16 v[112:127], v[236:239], v[156:159], v[112:127]
	s_setprio 0
	s_barrier
	s_add_u32 m0, s14, 0x2000
	ds_read_b128 v[162:165], v216
	ds_read_b128 v[166:169], v217
	ds_read_b128 v[170:173], v218
	ds_read_b128 v[174:177], v219
	global_load_lds_dwordx4 v222, s[22:23]
	s_add_u32 m0, s14, 0x2400
	ds_read_b128 v[128:131], v208
	ds_read_b128 v[132:135], v209
	ds_read_b128 v[136:139], v210
	ds_read_b128 v[140:143], v211
	global_load_lds_dwordx4 v223, s[22:23]
	ds_read_b128 v[144:147], v208 offset:4096
	ds_read_b128 v[148:151], v209 offset:4096
	ds_read_b128 v[152:155], v210 offset:4096
	ds_read_b128 v[156:159], v211 offset:4096
	s_add_u32 s22, s22, 0x80
	s_addc_u32 s23, s23, 0
	s_add_u32 s24, s24, 0x80
	s_addc_u32 s25, s25, 0
	s_add_u32 s26, s26, 1
	s_cmp_eq_u32 s26, 8
	s_cbranch_scc0 .Lgl5_cadv_done
	s_mov_b32 s26, 0
	s_add_u32 s27, s27, s30
	s_cmp_lt_u32 s27, 0x20
	s_cbranch_scc1 .Lgl5_cadv_new
	s_sub_u32 s22, s22, 0x400
	s_subb_u32 s23, s23, 0
	s_sub_u32 s24, s24, 0x400
	s_subb_u32 s25, s25, 0
	s_branch .Lgl5_cadv_done

; #define RAWBAR() { asm volatile("s_waitcnt vmcnt(0) lgkmcnt(0)" ::: "memory"); __builtin_amdgcn_s_barrier(); }
;     ...
;   if (V != 1) GLDS(0, 0);
;   RAWBAR();
;   for (int kt = 0; kt < nk; kt += 2) {
;     if (V != 1) GLDS(kt + 1, 1);
;     if (V != 2) COMPUTE(0);
;     RAWBAR();
;     if (V != 1) if (kt + 2 < nk) GLDS(kt + 2, 0);
;     if (V != 2) COMPUTE(1);
;     RAWBAR();
.Lgl5_cadv_done:
	s_waitcnt lgkmcnt(8)
	s_barrier
	s_waitcnt lgkmcnt(0)
	s_setprio 1
	v_mfma_f32_32x32x16_bf16 v[0:15], v[162:165], v[128:131], v[0:15]
	v_mfma_f32_32x32x16_bf16 v[32:47], v[162:165], v[144:147], v[32:47]
	v_mfma_f32_32x32x16_bf16 v[0:15], v[166:169], v[132:135], v[0:15]
	v_mfma_f32_32x32x16_bf16 v[32:47], v[166:169], v[148:151], v[32:47]
	v_mfma_f32_32x32x16_bf16 v[0:15], v[170:173], v[136:139], v[0:15]
	v_mfma_f32_32x32x16_bf16 v[32:47], v[170:173], v[152:155], v[32:47]
	v_mfma_f32_32x32x16_bf16 v[0:15], v[174:177], v[140:143], v[0:15]
	v_mfma_f32_32x32x16_bf16 v[32:47], v[174:177], v[156:159], v[32:47]
	s_setprio 0
	s_barrier
	s_add_u32 m0, s14, 0x18000
	ds_read_b128 v[224:227], v216 offset:8192
	global_load_lds_dwordx4 v240, s[24:25]
	s_add_u32 m0, s14, 0x18400
	ds_read_b128 v[228:231], v217 offset:8192
	global_load_lds_dwordx4 v241, s[24:25]
	ds_read_b128 v[232:235], v218 offset:8192
	ds_read_b128 v[236:239], v219 offset:8192
	s_barrier
	s_waitcnt lgkmcnt(0)
	s_setprio 1
	v_mfma_f32_32x32x16_bf16 v[16:31], v[224:227], v[128:131], v[16:31]
	v_mfma_f32_32x32x16_bf16 v[48:63], v[224:227], v[144:147], v[48:63]
	v_mfma_f32_32x32x16_bf16 v[16:31], v[228:231], v[132:135], v[16:31]
	v_mfma_f32_32x32x16_bf16 v[48:63], v[228:231], v[148:151], v[48:63]
	v_mfma_f32_32x32x16_bf16 v[16:31], v[232:235], v[136:139], v[16:31]
	v_mfma_f32_32x32x16_bf16 v[48:63], v[232:235], v[152:155], v[48:63]
	v_mfma_f32_32x32x16_bf16 v[16:31], v[236:239], v[140:143], v[16:31]
	v_mfma_f32_32x32x16_bf16 v[48:63], v[236:239], v[156:159], v[48:63]
	s_setprio 0
	s_barrier
	s_add_u32 m0, s14, 0x10000
	ds_read_b128 v[128:131], v208 offset:8192
	ds_read_b128 v[132:135], v209 offset:8192
	global_load_lds_dwordx4 v220, s[22:23]
	s_add_u32 m0, s14, 0x10400
	ds_read_b128 v[136:139], v210 offset:8192
	ds_read_b128 v[140:143], v211 offset:8192
	global_load_lds_dwordx4 v221, s[22:23]
	ds_read_b128 v[144:147], v208 offset:12288
	ds_read_b128 v[148:151], v209 offset:12288
	ds_read_b128 v[152:155], v210 offset:12288
	ds_read_b128 v[156:159], v211 offset:12288
	s_barrier
	s_waitcnt lgkmcnt(0)
	s_setprio 1
	v_mfma_f32_32x32x16_bf16 v[64:79], v[162:165], v[128:131], v[64:79]
	v_mfma_f32_32x32x16_bf16 v[96:111], v[162:165], v[144:147], v[96:111]
	v_mfma_f32_32x32x16_bf16 v[64:79], v[166:169], v[132:135], v[64:79]
	v_mfma_f32_32x32x16_bf16 v[96:111], v[166:169], v[148:151], v[96:111]
	v_mfma_f32_32x32x16_bf16 v[64:79], v[170:173], v[136:139], v[64:79]
	v_mfma_f32_32x32x16_bf16 v[96:111], v[170:173], v[152:155], v[96:111]
	v_mfma_f32_32x32x16_bf16 v[64:79], v[174:177], v[140:143], v[64:79]
	v_mfma_f32_32x32x16_bf16 v[96:111], v[174:177], v[156:159], v[96:111]
	s_setprio 0
	s_barrier
	s_add_u32 m0, s14, 0x1a000
	s_nop 0
	global_load_lds_dwordx4 v242, s[24:25]
	s_add_u32 m0, s14, 0x1a400
	s_nop 0
	global_load_lds_dwordx4 v243, s[24:25]
	s_waitcnt vmcnt(6)
	s_barrier
	s_setprio 1
	v_mfma_f32_32x32x16_bf16 v[80:95], v[224:227], v[128:131], v[80:95]
	v_mfma_f32_32x32x16_bf16 v[112:127], v[224:227], v[144:147], v[112:127]
	v_mfma_f32_32x32x16_bf16 v[80:95], v[228:231], v[132:135], v[80:95]
	v_mfma_f32_32x32x16_bf16 v[112:127], v[228:231], v[148:151], v[112:127]
	v_mfma_f32_32x32x16_bf16 v[80:95], v[232:235], v[136:139], v[80:95]
	v_mfma_f32_32x32x16_bf16 v[112:127], v[232:235], v[152:155], v[112:127]
	v_mfma_f32_32x32x16_bf16 v[80:95], v[236:239], v[140:143], v[80:95]
	v_mfma_f32_32x32x16_bf16 v[112:127], v[236:239], v[156:159], v[112:127]
	s_setprio 0
	s_barrier
	s_sub_u32 s31, s31, 1
	s_cmp_lg_u32 s31, 0
	s_cbranch_scc1 .Lgl_pair

; DI float bf2f(unsigned h) { return __uint_as_float(h << 16); }
; DI int crow(int r, int hf) { return (r & 3) + 8 * (r >> 2) + 4 * hf; }
; #define RAWBAR() { asm volatile("s_waitcnt vmcnt(0) lgkmcnt(0)" ::: "memory"); __builtin_amdgcn_s_barrier(); }
;     ...
;   for (int kt = 0; kt < nk; kt += 2) {
;     if (V != 1) GLDS(kt + 1, 1);
;     if (V != 2) COMPUTE(0);
;     RAWBAR();
;     if (V != 1) if (kt + 2 < nk) GLDS(kt + 2, 0);
;     if (V != 2) COMPUTE(1);
;     RAWBAR();
; DI void glu_phase(const Params& p, int j, char* smem) {
;     ...
;     gemm_tile(yt + (size_t)m0 * LDYT, LDYT, 8, nullptr, 0, 0, Wt + (size_t)n0 * LDGLU, LDGLU, smem, [&](f32x16(&acc)[2][2], int moff) {
;       const int m0_ = m0 + moff;
;       int l32_ = l32, hf_ = hf; asm volatile("" : "+v"(l32_), "+v"(hf_));
; #pragma unroll
;       for (int i = 0; i < 2; ++i)
; #pragma unroll
;         for (int jn = 0; jn < 2; ++jn)
; #pragma unroll
;           for (int r = 0; r < 16; ++r) {
;             const int row = m0_ + wm * 64 + i * 32 + crow(r, hf_), col = n0 + wn * 64 + jn * 32 + l32_;
;             const float gt = acc[i][jn][r] + gb[col];
;             const float y = bf2f(yt[(size_t)row * LDYT + col]);
;             o[(size_t)row * LDH + 512 + col] = f2bf(y / (1.f + __expf(-gt)));
;           }
.Lgl7_cadv_done:
	s_waitcnt lgkmcnt(8)
	s_barrier
	s_waitcnt lgkmcnt(0)
	s_setprio 1
	v_mfma_f32_32x32x16_bf16 v[0:15], v[162:165], v[128:131], v[0:15]
	v_mfma_f32_32x32x16_bf16 v[32:47], v[162:165], v[144:147], v[32:47]
	v_mfma_f32_32x32x16_bf16 v[0:15], v[166:169], v[132:135], v[0:15]
	v_mfma_f32_32x32x16_bf16 v[32:47], v[166:169], v[148:151], v[32:47]
	v_mfma_f32_32x32x16_bf16 v[0:15], v[170:173], v[136:139], v[0:15]
	v_mfma_f32_32x32x16_bf16 v[32:47], v[170:173], v[152:155], v[32:47]
	v_mfma_f32_32x32x16_bf16 v[0:15], v[174:177], v[140:143], v[0:15]
	v_mfma_f32_32x32x16_bf16 v[32:47], v[174:177], v[156:159], v[32:47]
	s_setprio 0
	s_barrier
	ds_read_b128 v[224:227], v216 offset:8192
	ds_read_b128 v[228:231], v217 offset:8192
	ds_read_b128 v[232:235], v218 offset:8192
	ds_read_b128 v[236:239], v219 offset:8192
	s_barrier
	s_waitcnt lgkmcnt(0)
	s_setprio 1
	v_mfma_f32_32x32x16_bf16 v[16:31], v[224:227], v[128:131], v[16:31]
	v_mfma_f32_32x32x16_bf16 v[48:63], v[224:227], v[144:147], v[48:63]
	v_mfma_f32_32x32x16_bf16 v[16:31], v[228:231], v[132:135], v[16:31]
	v_mfma_f32_32x32x16_bf16 v[48:63], v[228:231], v[148:151], v[48:63]
	v_mfma_f32_32x32x16_bf16 v[16:31], v[232:235], v[136:139], v[16:31]
	v_mfma_f32_32x32x16_bf16 v[48:63], v[232:235], v[152:155], v[48:63]
	v_mfma_f32_32x32x16_bf16 v[16:31], v[236:239], v[140:143], v[16:31]
	v_mfma_f32_32x32x16_bf16 v[48:63], v[236:239], v[156:159], v[48:63]
	s_setprio 0
	s_barrier
	s_add_u32 m0, s14, 0x10000
	ds_read_b128 v[128:131], v208 offset:8192
	ds_read_b128 v[132:135], v209 offset:8192
	global_load_lds_dwordx4 v220, s[22:23]
	s_add_u32 m0, s14, 0x10400
	ds_read_b128 v[136:139], v210 offset:8192
	ds_read_b128 v[140:143], v211 offset:8192
	global_load_lds_dwordx4 v221, s[22:23]
	ds_read_b128 v[144:147], v208 offset:12288
	ds_read_b128 v[148:151], v209 offset:12288
	ds_read_b128 v[152:155], v210 offset:12288
	ds_read_b128 v[156:159], v211 offset:12288
	s_barrier
	s_waitcnt lgkmcnt(0)
	s_setprio 1
	v_mfma_f32_32x32x16_bf16 v[64:79], v[162:165], v[128:131], v[64:79]
	v_mfma_f32_32x32x16_bf16 v[96:111], v[162:165], v[144:147], v[96:111]
	v_mfma_f32_32x32x16_bf16 v[64:79], v[166:169], v[132:135], v[64:79]
	v_mfma_f32_32x32x16_bf16 v[96:111], v[166:169], v[148:151], v[96:111]
	v_mfma_f32_32x32x16_bf16 v[64:79], v[170:173], v[136:139], v[64:79]
	v_mfma_f32_32x32x16_bf16 v[96:111], v[170:173], v[152:155], v[96:111]
	v_mfma_f32_32x32x16_bf16 v[64:79], v[174:177], v[140:143], v[64:79]
	v_mfma_f32_32x32x16_bf16 v[96:111], v[174:177], v[156:159], v[96:111]
	s_setprio 0
	s_barrier
	s_waitcnt vmcnt(2)
	s_barrier
	s_setprio 1
	v_mfma_f32_32x32x16_bf16 v[80:95], v[224:227], v[128:131], v[80:95]
	v_mfma_f32_32x32x16_bf16 v[112:127], v[224:227], v[144:147], v[112:127]
	v_mfma_f32_32x32x16_bf16 v[80:95], v[228:231], v[132:135], v[80:95]
	v_mfma_f32_32x32x16_bf16 v[112:127], v[228:231], v[148:151], v[112:127]
	v_mfma_f32_32x32x16_bf16 v[80:95], v[232:235], v[136:139], v[80:95]
	v_mfma_f32_32x32x16_bf16 v[112:127], v[232:235], v[152:155], v[112:127]
	v_mfma_f32_32x32x16_bf16 v[80:95], v[236:239], v[140:143], v[80:95]
	v_mfma_f32_32x32x16_bf16 v[112:127], v[236:239], v[156:159], v[112:127]
	s_setprio 0
	s_barrier
	s_lshr_b32 s12, s15, 2
	s_and_b32 s13, s15, 3
	s_lshr_b32 s20, s28, 1
	s_add_u32 s20, s20, s5
	s_lshl_b32 s20, s20, 8
	s_lshl_b32 s12, s12, 7
	s_add_u32 s20, s20, s12
	s_and_b32 s29, s28, 1
	s_lshl_b32 s29, s29, 8
	s_lshl_b32 s13, s13, 6
	s_add_u32 s29, s29, s13
	s_lshl_b32 s12, s29, 2
	s_add_u32 s12, s10, s12
	s_addc_u32 s13, s11, 0
	global_load_dwordx4 v[128:131], v196, s[12:13]
	global_load_dwordx4 v[132:135], v196, s[12:13] offset:32
	global_load_dwordx4 v[136:139], v196, s[12:13] offset:64
	global_load_dwordx4 v[140:143], v196, s[12:13] offset:96
	global_load_dwordx4 v[144:147], v196, s[12:13] offset:128
	global_load_dwordx4 v[148:151], v196, s[12:13] offset:160
	global_load_dwordx4 v[152:155], v196, s[12:13] offset:192
	global_load_dwordx4 v[156:159], v196, s[12:13] offset:224
	s_mul_i32 s12, s20, 0x480
	s_lshl_b32 s13, s29, 1
	s_add_u32 s12, s12, s13
	s_add_u32 s12, s6, s12
	s_addc_u32 s13, s7, 0
	s_mul_i32 s100, s20, 0x880
	s_lshl_b32 s101, s29, 1
	s_add_u32 s100, s100, s101
	s_add_u32 s100, s0, s100
	s_addc_u32 s101, s1, 0
	s_add_u32 s100, s100, 0x17404500
	s_addc_u32 s101, s101, 0
	global_load_dwordx2 v[162:163], v197, s[12:13]
	global_load_dwordx2 v[164:165], v197, s[12:13] offset:16
	global_load_dwordx2 v[166:167], v197, s[12:13] offset:32
	global_load_dwordx2 v[168:169], v197, s[12:13] offset:48
	global_load_dwordx2 v[170:171], v197, s[12:13] offset:64
	global_load_dwordx2 v[172:173], v197, s[12:13] offset:80
	global_load_dwordx2 v[174:175], v197, s[12:13] offset:96
	global_load_dwordx2 v[176:177], v197, s[12:13] offset:112
	s_add_u32 s12, s12, 0x9000
	s_addc_u32 s13, s13, 0
	global_load_dwordx2 v[224:225], v197, s[12:13]
	global_load_dwordx2 v[226:227], v197, s[12:13] offset:16
	global_load_dwordx2 v[228:229], v197, s[12:13] offset:32
	global_load_dwordx2 v[230:231], v197, s[12:13] offset:48
	global_load_dwordx2 v[232:233], v197, s[12:13] offset:64
	global_load_dwordx2 v[234:235], v197, s[12:13] offset:80
	global_load_dwordx2 v[236:237], v197, s[12:13] offset:96
	global_load_dwordx2 v[238:239], v197, s[12:13] offset:112
	s_add_u32 s12, s12, 0x9000
	s_addc_u32 s13, s13, 0
	s_waitcnt vmcnt(8)
; DI float bf2f(unsigned h) { return __uint_as_float(h << 16); }
; DI int crow(int r, int hf) { return (r & 3) + 8 * (r >> 2) + 4 * hf; }
; DI void glu_phase(const Params& p, int j, char* smem) {
;     ...
;           for (int r = 0; r < 16; ++r) {
;             const int row = m0_ + wm * 64 + i * 32 + crow(r, hf_), col = n0 + wn * 64 + jn * 32 + l32_;
;             const float gt = acc[i][jn][r] + gb[col];
;             const float y = bf2f(yt[(size_t)row * LDYT + col]);
;             o[(size_t)row * LDH + 512 + col] = f2bf(y / (1.f + __expf(-gt)));
	v_add_f32_e32 v0, v0, v128
	v_mul_f32_e32 v0, 0xbfb8aa3b, v0
	v_exp_f32_e32 v0, v0
	s_nop 0
	v_add_f32_e32 v0, 1.0, v0
	v_rcp_f32_e32 v0, v0
	v_lshlrev_b32_e32 v246, 16, v162
	v_mul_f32_e32 v0, v246, v0
	v_add_f32_e32 v1, v1, v129
	v_mul_f32_e32 v1, 0xbfb8aa3b, v1
	v_exp_f32_e32 v1, v1
	s_nop 0
	v_add_f32_e32 v1, 1.0, v1
	v_rcp_f32_e32 v1, v1
	v_and_b32_e32 v246, 0xffff0000, v162
	v_mul_f32_e32 v1, v246, v1
	v_add_f32_e32 v2, v2, v130
	v_mul_f32_e32 v2, 0xbfb8aa3b, v2
	v_exp_f32_e32 v2, v2
	s_nop 0
	v_add_f32_e32 v2, 1.0, v2
	v_rcp_f32_e32 v2, v2
	v_lshlrev_b32_e32 v246, 16, v163
	v_mul_f32_e32 v2, v246, v2
	v_add_f32_e32 v3, v3, v131
	v_mul_f32_e32 v3, 0xbfb8aa3b, v3
	v_exp_f32_e32 v3, v3
	s_nop 0
	v_add_f32_e32 v3, 1.0, v3
	v_rcp_f32_e32 v3, v3
	v_and_b32_e32 v246, 0xffff0000, v163
	v_mul_f32_e32 v3, v246, v3
	v_add_f32_e32 v4, v4, v132
	v_mul_f32_e32 v4, 0xbfb8aa3b, v4
	v_exp_f32_e32 v4, v4
	s_nop 0
	v_add_f32_e32 v4, 1.0, v4
	v_rcp_f32_e32 v4, v4
	v_lshlrev_b32_e32 v246, 16, v164
	v_mul_f32_e32 v4, v246, v4
	v_add_f32_e32 v5, v5, v133
	v_mul_f32_e32 v5, 0xbfb8aa3b, v5
	v_exp_f32_e32 v5, v5
	s_nop 0
	v_add_f32_e32 v5, 1.0, v5
	v_rcp_f32_e32 v5, v5
	v_and_b32_e32 v246, 0xffff0000, v164
	v_mul_f32_e32 v5, v246, v5
	v_add_f32_e32 v6, v6, v134
	v_mul_f32_e32 v6, 0xbfb8aa3b, v6
	v_exp_f32_e32 v6, v6
	s_nop 0
	v_add_f32_e32 v6, 1.0, v6
	v_rcp_f32_e32 v6, v6
	v_lshlrev_b32_e32 v246, 16, v165
	v_mul_f32_e32 v6, v246, v6
	v_add_f32_e32 v7, v7, v135
	v_mul_f32_e32 v7, 0xbfb8aa3b, v7
	v_exp_f32_e32 v7, v7
	s_nop 0
	v_add_f32_e32 v7, 1.0, v7
	v_rcp_f32_e32 v7, v7
	v_and_b32_e32 v246, 0xffff0000, v165
	v_mul_f32_e32 v7, v246, v7
	v_add_f32_e32 v8, v8, v136
	v_mul_f32_e32 v8, 0xbfb8aa3b, v8
	v_exp_f32_e32 v8, v8
	s_nop 0
	v_add_f32_e32 v8, 1.0, v8
	v_rcp_f32_e32 v8, v8
	v_lshlrev_b32_e32 v246, 16, v166
	v_mul_f32_e32 v8, v246, v8
	v_add_f32_e32 v9, v9, v137
	v_mul_f32_e32 v9, 0xbfb8aa3b, v9
	v_exp_f32_e32 v9, v9
	s_nop 0
	v_add_f32_e32 v9, 1.0, v9
	v_rcp_f32_e32 v9, v9
	v_and_b32_e32 v246, 0xffff0000, v166
	v_mul_f32_e32 v9, v246, v9
	v_add_f32_e32 v10, v10, v138
	v_mul_f32_e32 v10, 0xbfb8aa3b, v10
	v_exp_f32_e32 v10, v10
	s_nop 0
	v_add_f32_e32 v10, 1.0, v10
	v_rcp_f32_e32 v10, v10
	v_lshlrev_b32_e32 v246, 16, v167
	v_mul_f32_e32 v10, v246, v10
	v_add_f32_e32 v11, v11, v139
	v_mul_f32_e32 v11, 0xbfb8aa3b, v11
	v_exp_f32_e32 v11, v11
	s_nop 0
	v_add_f32_e32 v11, 1.0, v11
	v_rcp_f32_e32 v11, v11
	v_and_b32_e32 v246, 0xffff0000, v167
	v_mul_f32_e32 v11, v246, v11
	v_add_f32_e32 v12, v12, v140
	v_mul_f32_e32 v12, 0xbfb8aa3b, v12
	v_exp_f32_e32 v12, v12
	s_nop 0
	v_add_f32_e32 v12, 1.0, v12
	v_rcp_f32_e32 v12, v12
	v_lshlrev_b32_e32 v246, 16, v168
	v_mul_f32_e32 v12, v246, v12
	v_add_f32_e32 v13, v13, v141
	v_mul_f32_e32 v13, 0xbfb8aa3b, v13
	v_exp_f32_e32 v13, v13
	s_nop 0
	v_add_f32_e32 v13, 1.0, v13
	v_rcp_f32_e32 v13, v13
	v_and_b32_e32 v246, 0xffff0000, v168
	v_mul_f32_e32 v13, v246, v13
	v_add_f32_e32 v14, v14, v142
	v_mul_f32_e32 v14, 0xbfb8aa3b, v14
	v_exp_f32_e32 v14, v14
	s_nop 0
	v_add_f32_e32 v14, 1.0, v14
	v_rcp_f32_e32 v14, v14
	v_lshlrev_b32_e32 v246, 16, v169
	v_mul_f32_e32 v14, v246, v14
	v_add_f32_e32 v15, v15, v143
	v_mul_f32_e32 v15, 0xbfb8aa3b, v15
	v_exp_f32_e32 v15, v15
	s_nop 0
	v_add_f32_e32 v15, 1.0, v15
	v_rcp_f32_e32 v15, v15
	v_and_b32_e32 v246, 0xffff0000, v169
	v_mul_f32_e32 v15, v246, v15
	v_add_f32_e32 v16, v16, v144
	v_mul_f32_e32 v16, 0xbfb8aa3b, v16
	v_exp_f32_e32 v16, v16
	s_nop 0
	v_add_f32_e32 v16, 1.0, v16
	v_rcp_f32_e32 v16, v16
	v_lshlrev_b32_e32 v246, 16, v170
	v_mul_f32_e32 v16, v246, v16
	v_add_f32_e32 v17, v17, v145
	v_mul_f32_e32 v17, 0xbfb8aa3b, v17
	v_exp_f32_e32 v17, v17
	s_nop 0
	v_add_f32_e32 v17, 1.0, v17
	v_rcp_f32_e32 v17, v17
	v_and_b32_e32 v246, 0xffff0000, v170
	v_mul_f32_e32 v17, v246, v17
	v_add_f32_e32 v18, v18, v146
	v_mul_f32_e32 v18, 0xbfb8aa3b, v18
	v_exp_f32_e32 v18, v18
	s_nop 0
	v_add_f32_e32 v18, 1.0, v18
	v_rcp_f32_e32 v18, v18
	v_lshlrev_b32_e32 v246, 16, v171
	v_mul_f32_e32 v18, v246, v18
	v_add_f32_e32 v19, v19, v147
	v_mul_f32_e32 v19, 0xbfb8aa3b, v19
	v_exp_f32_e32 v19, v19
	s_nop 0
	v_add_f32_e32 v19, 1.0, v19
	v_rcp_f32_e32 v19, v19
	v_and_b32_e32 v246, 0xffff0000, v171
	v_mul_f32_e32 v19, v246, v19
	v_add_f32_e32 v20, v20, v148
	v_mul_f32_e32 v20, 0xbfb8aa3b, v20
	v_exp_f32_e32 v20, v20
	s_nop 0
	v_add_f32_e32 v20, 1.0, v20
	v_rcp_f32_e32 v20, v20
	v_lshlrev_b32_e32 v246, 16, v172
	v_mul_f32_e32 v20, v246, v20
	v_add_f32_e32 v21, v21, v149
	v_mul_f32_e32 v21, 0xbfb8aa3b, v21
	v_exp_f32_e32 v21, v21
	s_nop 0
	v_add_f32_e32 v21, 1.0, v21
	v_rcp_f32_e32 v21, v21
	v_and_b32_e32 v246, 0xffff0000, v172
	v_mul_f32_e32 v21, v246, v21
	v_add_f32_e32 v22, v22, v150
	v_mul_f32_e32 v22, 0xbfb8aa3b, v22
	v_exp_f32_e32 v22, v22
	s_nop 0
	v_add_f32_e32 v22, 1.0, v22
	v_rcp_f32_e32 v22, v22
	v_lshlrev_b32_e32 v246, 16, v173
	v_mul_f32_e32 v22, v246, v22
	v_add_f32_e32 v23, v23, v151
	v_mul_f32_e32 v23, 0xbfb8aa3b, v23
	v_exp_f32_e32 v23, v23
	s_nop 0
	v_add_f32_e32 v23, 1.0, v23
	v_rcp_f32_e32 v23, v23
	v_and_b32_e32 v246, 0xffff0000, v173
	v_mul_f32_e32 v23, v246, v23
	v_add_f32_e32 v24, v24, v152
	v_mul_f32_e32 v24, 0xbfb8aa3b, v24
	v_exp_f32_e32 v24, v24
	s_nop 0
	v_add_f32_e32 v24, 1.0, v24
	v_rcp_f32_e32 v24, v24
	v_lshlrev_b32_e32 v246, 16, v174
	v_mul_f32_e32 v24, v246, v24
	v_add_f32_e32 v25, v25, v153
	v_mul_f32_e32 v25, 0xbfb8aa3b, v25
	v_exp_f32_e32 v25, v25
	s_nop 0
	v_add_f32_e32 v25, 1.0, v25
	v_rcp_f32_e32 v25, v25
	v_and_b32_e32 v246, 0xffff0000, v174
	v_mul_f32_e32 v25, v246, v25
	v_add_f32_e32 v26, v26, v154
	v_mul_f32_e32 v26, 0xbfb8aa3b, v26
	v_exp_f32_e32 v26, v26
; DI float bf2f(unsigned h) { return __uint_as_float(h << 16); }
; DI int crow(int r, int hf) { return (r & 3) + 8 * (r >> 2) + 4 * hf; }
; DI void glu_phase(const Params& p, int j, char* smem) {
;     ...
;           for (int r = 0; r < 16; ++r) {
;             const int row = m0_ + wm * 64 + i * 32 + crow(r, hf_), col = n0 + wn * 64 + jn * 32 + l32_;
;             const float gt = acc[i][jn][r] + gb[col];
;             const float y = bf2f(yt[(size_t)row * LDYT + col]);
;             o[(size_t)row * LDH + 512 + col] = f2bf(y / (1.f + __expf(-gt)));
	s_nop 0
	v_add_f32_e32 v26, 1.0, v26
	v_rcp_f32_e32 v26, v26
	v_lshlrev_b32_e32 v246, 16, v175
	v_mul_f32_e32 v26, v246, v26
	v_add_f32_e32 v27, v27, v155
	v_mul_f32_e32 v27, 0xbfb8aa3b, v27
	v_exp_f32_e32 v27, v27
	s_nop 0
	v_add_f32_e32 v27, 1.0, v27
	v_rcp_f32_e32 v27, v27
	v_and_b32_e32 v246, 0xffff0000, v175
	v_mul_f32_e32 v27, v246, v27
	v_add_f32_e32 v28, v28, v156
	v_mul_f32_e32 v28, 0xbfb8aa3b, v28
	v_exp_f32_e32 v28, v28
	s_nop 0
	v_add_f32_e32 v28, 1.0, v28
	v_rcp_f32_e32 v28, v28
	v_lshlrev_b32_e32 v246, 16, v176
	v_mul_f32_e32 v28, v246, v28
	v_add_f32_e32 v29, v29, v157
	v_mul_f32_e32 v29, 0xbfb8aa3b, v29
	v_exp_f32_e32 v29, v29
	s_nop 0
	v_add_f32_e32 v29, 1.0, v29
	v_rcp_f32_e32 v29, v29
	v_and_b32_e32 v246, 0xffff0000, v176
	v_mul_f32_e32 v29, v246, v29
	v_add_f32_e32 v30, v30, v158
	v_mul_f32_e32 v30, 0xbfb8aa3b, v30
	v_exp_f32_e32 v30, v30
	s_nop 0
	v_add_f32_e32 v30, 1.0, v30
	v_rcp_f32_e32 v30, v30
	v_lshlrev_b32_e32 v246, 16, v177
	v_mul_f32_e32 v30, v246, v30
	v_add_f32_e32 v31, v31, v159
	v_mul_f32_e32 v31, 0xbfb8aa3b, v31
	v_exp_f32_e32 v31, v31
	s_nop 0
	v_add_f32_e32 v31, 1.0, v31
	v_rcp_f32_e32 v31, v31
	v_and_b32_e32 v246, 0xffff0000, v177
	v_mul_f32_e32 v31, v246, v31
	global_load_dwordx2 v[162:163], v197, s[12:13]
	global_load_dwordx2 v[164:165], v197, s[12:13] offset:16
	global_load_dwordx2 v[166:167], v197, s[12:13] offset:32
	global_load_dwordx2 v[168:169], v197, s[12:13] offset:48
	global_load_dwordx2 v[170:171], v197, s[12:13] offset:64
	global_load_dwordx2 v[172:173], v197, s[12:13] offset:80
	global_load_dwordx2 v[174:175], v197, s[12:13] offset:96
	global_load_dwordx2 v[176:177], v197, s[12:13] offset:112
	s_add_u32 s12, s12, 0x9000
	s_addc_u32 s13, s13, 0
	v_cvt_pk_bf16_f32 v240, v0, v1
	v_cvt_pk_bf16_f32 v241, v2, v3
	ds_write_b64 v178, v[240:241]
	v_cvt_pk_bf16_f32 v242, v4, v5
	v_cvt_pk_bf16_f32 v243, v6, v7
	ds_write_b64 v179, v[242:243]
	v_cvt_pk_bf16_f32 v244, v8, v9
	v_cvt_pk_bf16_f32 v245, v10, v11
	ds_write_b64 v180, v[244:245]
	v_cvt_pk_bf16_f32 v240, v12, v13
	v_cvt_pk_bf16_f32 v241, v14, v15
	ds_write_b64 v181, v[240:241]
	v_cvt_pk_bf16_f32 v242, v16, v17
	v_cvt_pk_bf16_f32 v243, v18, v19
	ds_write_b64 v188, v[242:243]
	v_cvt_pk_bf16_f32 v244, v20, v21
	v_cvt_pk_bf16_f32 v245, v22, v23
	ds_write_b64 v189, v[244:245]
	v_cvt_pk_bf16_f32 v240, v24, v25
	v_cvt_pk_bf16_f32 v241, v26, v27
	ds_write_b64 v190, v[240:241]
	v_cvt_pk_bf16_f32 v242, v28, v29
	v_cvt_pk_bf16_f32 v243, v30, v31
	ds_write_b64 v191, v[242:243]
	ds_read_b128 v[0:3], v194
	ds_read_b128 v[4:7], v194 offset:1024
	ds_read_b128 v[8:11], v194 offset:2048
	ds_read_b128 v[12:15], v194 offset:3072
	s_waitcnt vmcnt(8)
	v_add_f32_e32 v32, v32, v128
	v_mul_f32_e32 v32, 0xbfb8aa3b, v32
	v_exp_f32_e32 v32, v32
	s_nop 0
	v_add_f32_e32 v32, 1.0, v32
	v_rcp_f32_e32 v32, v32
	v_lshlrev_b32_e32 v246, 16, v224
	v_mul_f32_e32 v32, v246, v32
	v_add_f32_e32 v33, v33, v129
	v_mul_f32_e32 v33, 0xbfb8aa3b, v33
	v_exp_f32_e32 v33, v33
	s_nop 0
	v_add_f32_e32 v33, 1.0, v33
	v_rcp_f32_e32 v33, v33
	v_and_b32_e32 v246, 0xffff0000, v224
	v_mul_f32_e32 v33, v246, v33
	v_add_f32_e32 v34, v34, v130
	v_mul_f32_e32 v34, 0xbfb8aa3b, v34
	v_exp_f32_e32 v34, v34
	s_nop 0
	v_add_f32_e32 v34, 1.0, v34
	v_rcp_f32_e32 v34, v34
	v_lshlrev_b32_e32 v246, 16, v225
	v_mul_f32_e32 v34, v246, v34
	v_add_f32_e32 v35, v35, v131
	v_mul_f32_e32 v35, 0xbfb8aa3b, v35
	v_exp_f32_e32 v35, v35
	s_nop 0
	v_add_f32_e32 v35, 1.0, v35
	v_rcp_f32_e32 v35, v35
	v_and_b32_e32 v246, 0xffff0000, v225
	v_mul_f32_e32 v35, v246, v35
	v_add_f32_e32 v36, v36, v132
	v_mul_f32_e32 v36, 0xbfb8aa3b, v36
	v_exp_f32_e32 v36, v36
	s_nop 0
	v_add_f32_e32 v36, 1.0, v36
	v_rcp_f32_e32 v36, v36
	v_lshlrev_b32_e32 v246, 16, v226
	v_mul_f32_e32 v36, v246, v36
	v_add_f32_e32 v37, v37, v133
	v_mul_f32_e32 v37, 0xbfb8aa3b, v37
	v_exp_f32_e32 v37, v37
	s_nop 0
	v_add_f32_e32 v37, 1.0, v37
	v_rcp_f32_e32 v37, v37
	v_and_b32_e32 v246, 0xffff0000, v226
	v_mul_f32_e32 v37, v246, v37
	v_add_f32_e32 v38, v38, v134
	v_mul_f32_e32 v38, 0xbfb8aa3b, v38
	v_exp_f32_e32 v38, v38
	s_nop 0
	v_add_f32_e32 v38, 1.0, v38
	v_rcp_f32_e32 v38, v38
	v_lshlrev_b32_e32 v246, 16, v227
	v_mul_f32_e32 v38, v246, v38
	v_add_f32_e32 v39, v39, v135
	v_mul_f32_e32 v39, 0xbfb8aa3b, v39
	v_exp_f32_e32 v39, v39
	s_nop 0
	v_add_f32_e32 v39, 1.0, v39
	v_rcp_f32_e32 v39, v39
	v_and_b32_e32 v246, 0xffff0000, v227
	v_mul_f32_e32 v39, v246, v39
	v_add_f32_e32 v40, v40, v136
	v_mul_f32_e32 v40, 0xbfb8aa3b, v40
	v_exp_f32_e32 v40, v40
	s_nop 0
	v_add_f32_e32 v40, 1.0, v40
	v_rcp_f32_e32 v40, v40
	v_lshlrev_b32_e32 v246, 16, v228
	v_mul_f32_e32 v40, v246, v40
	v_add_f32_e32 v41, v41, v137
	v_mul_f32_e32 v41, 0xbfb8aa3b, v41
	v_exp_f32_e32 v41, v41
	s_nop 0
	v_add_f32_e32 v41, 1.0, v41
	v_rcp_f32_e32 v41, v41
	v_and_b32_e32 v246, 0xffff0000, v228
	v_mul_f32_e32 v41, v246, v41
	v_add_f32_e32 v42, v42, v138
	v_mul_f32_e32 v42, 0xbfb8aa3b, v42
	v_exp_f32_e32 v42, v42
	s_nop 0
	v_add_f32_e32 v42, 1.0, v42
	v_rcp_f32_e32 v42, v42
	v_lshlrev_b32_e32 v246, 16, v229
	v_mul_f32_e32 v42, v246, v42
	v_add_f32_e32 v43, v43, v139
	v_mul_f32_e32 v43, 0xbfb8aa3b, v43
	v_exp_f32_e32 v43, v43
	s_nop 0
	v_add_f32_e32 v43, 1.0, v43
	v_rcp_f32_e32 v43, v43
	v_and_b32_e32 v246, 0xffff0000, v229
	v_mul_f32_e32 v43, v246, v43
	v_add_f32_e32 v44, v44, v140
	v_mul_f32_e32 v44, 0xbfb8aa3b, v44
	v_exp_f32_e32 v44, v44
	s_nop 0
	v_add_f32_e32 v44, 1.0, v44
	v_rcp_f32_e32 v44, v44
	v_lshlrev_b32_e32 v246, 16, v230
	v_mul_f32_e32 v44, v246, v44
	v_add_f32_e32 v45, v45, v141
	v_mul_f32_e32 v45, 0xbfb8aa3b, v45
	v_exp_f32_e32 v45, v45
	s_nop 0
	v_add_f32_e32 v45, 1.0, v45
; DI float bf2f(unsigned h) { return __uint_as_float(h << 16); }
; DI int crow(int r, int hf) { return (r & 3) + 8 * (r >> 2) + 4 * hf; }
; DI void glu_phase(const Params& p, int j, char* smem) {
;     ...
;           for (int r = 0; r < 16; ++r) {
;             const int row = m0_ + wm * 64 + i * 32 + crow(r, hf_), col = n0 + wn * 64 + jn * 32 + l32_;
;             const float gt = acc[i][jn][r] + gb[col];
;             const float y = bf2f(yt[(size_t)row * LDYT + col]);
;             o[(size_t)row * LDH + 512 + col] = f2bf(y / (1.f + __expf(-gt)));
	v_rcp_f32_e32 v45, v45
	v_and_b32_e32 v246, 0xffff0000, v230
	v_mul_f32_e32 v45, v246, v45
	v_add_f32_e32 v46, v46, v142
	v_mul_f32_e32 v46, 0xbfb8aa3b, v46
	v_exp_f32_e32 v46, v46
	s_nop 0
	v_add_f32_e32 v46, 1.0, v46
	v_rcp_f32_e32 v46, v46
	v_lshlrev_b32_e32 v246, 16, v231
	v_mul_f32_e32 v46, v246, v46
	v_add_f32_e32 v47, v47, v143
	v_mul_f32_e32 v47, 0xbfb8aa3b, v47
	v_exp_f32_e32 v47, v47
	s_nop 0
	v_add_f32_e32 v47, 1.0, v47
	v_rcp_f32_e32 v47, v47
	v_and_b32_e32 v246, 0xffff0000, v231
	v_mul_f32_e32 v47, v246, v47
	v_add_f32_e32 v48, v48, v144
	v_mul_f32_e32 v48, 0xbfb8aa3b, v48
	v_exp_f32_e32 v48, v48
	s_nop 0
	v_add_f32_e32 v48, 1.0, v48
	v_rcp_f32_e32 v48, v48
	v_lshlrev_b32_e32 v246, 16, v232
	v_mul_f32_e32 v48, v246, v48
	v_add_f32_e32 v49, v49, v145
	v_mul_f32_e32 v49, 0xbfb8aa3b, v49
	v_exp_f32_e32 v49, v49
	s_nop 0
	v_add_f32_e32 v49, 1.0, v49
	v_rcp_f32_e32 v49, v49
	v_and_b32_e32 v246, 0xffff0000, v232
	v_mul_f32_e32 v49, v246, v49
	v_add_f32_e32 v50, v50, v146
	v_mul_f32_e32 v50, 0xbfb8aa3b, v50
	v_exp_f32_e32 v50, v50
	s_nop 0
	v_add_f32_e32 v50, 1.0, v50
	v_rcp_f32_e32 v50, v50
	v_lshlrev_b32_e32 v246, 16, v233
	v_mul_f32_e32 v50, v246, v50
	v_add_f32_e32 v51, v51, v147
	v_mul_f32_e32 v51, 0xbfb8aa3b, v51
	v_exp_f32_e32 v51, v51
	s_nop 0
	v_add_f32_e32 v51, 1.0, v51
	v_rcp_f32_e32 v51, v51
	v_and_b32_e32 v246, 0xffff0000, v233
	v_mul_f32_e32 v51, v246, v51
	v_add_f32_e32 v52, v52, v148
	v_mul_f32_e32 v52, 0xbfb8aa3b, v52
	v_exp_f32_e32 v52, v52
	s_nop 0
	v_add_f32_e32 v52, 1.0, v52
	v_rcp_f32_e32 v52, v52
	v_lshlrev_b32_e32 v246, 16, v234
	v_mul_f32_e32 v52, v246, v52
	v_add_f32_e32 v53, v53, v149
	v_mul_f32_e32 v53, 0xbfb8aa3b, v53
	v_exp_f32_e32 v53, v53
	s_nop 0
	v_add_f32_e32 v53, 1.0, v53
	v_rcp_f32_e32 v53, v53
	v_and_b32_e32 v246, 0xffff0000, v234
	v_mul_f32_e32 v53, v246, v53
	v_add_f32_e32 v54, v54, v150
	v_mul_f32_e32 v54, 0xbfb8aa3b, v54
	v_exp_f32_e32 v54, v54
	s_nop 0
	v_add_f32_e32 v54, 1.0, v54
	v_rcp_f32_e32 v54, v54
	v_lshlrev_b32_e32 v246, 16, v235
	v_mul_f32_e32 v54, v246, v54
	v_add_f32_e32 v55, v55, v151
	v_mul_f32_e32 v55, 0xbfb8aa3b, v55
	v_exp_f32_e32 v55, v55
	s_nop 0
	v_add_f32_e32 v55, 1.0, v55
	v_rcp_f32_e32 v55, v55
	v_and_b32_e32 v246, 0xffff0000, v235
	v_mul_f32_e32 v55, v246, v55
	v_add_f32_e32 v56, v56, v152
	v_mul_f32_e32 v56, 0xbfb8aa3b, v56
	v_exp_f32_e32 v56, v56
	s_nop 0
	v_add_f32_e32 v56, 1.0, v56
	v_rcp_f32_e32 v56, v56
	v_lshlrev_b32_e32 v246, 16, v236
	v_mul_f32_e32 v56, v246, v56
	v_add_f32_e32 v57, v57, v153
	v_mul_f32_e32 v57, 0xbfb8aa3b, v57
	v_exp_f32_e32 v57, v57
	s_nop 0
	v_add_f32_e32 v57, 1.0, v57
	v_rcp_f32_e32 v57, v57
	v_and_b32_e32 v246, 0xffff0000, v236
	v_mul_f32_e32 v57, v246, v57
	v_add_f32_e32 v58, v58, v154
	v_mul_f32_e32 v58, 0xbfb8aa3b, v58
	v_exp_f32_e32 v58, v58
	s_nop 0
	v_add_f32_e32 v58, 1.0, v58
	v_rcp_f32_e32 v58, v58
	v_lshlrev_b32_e32 v246, 16, v237
	v_mul_f32_e32 v58, v246, v58
	v_add_f32_e32 v59, v59, v155
	v_mul_f32_e32 v59, 0xbfb8aa3b, v59
	v_exp_f32_e32 v59, v59
	s_nop 0
	v_add_f32_e32 v59, 1.0, v59
	v_rcp_f32_e32 v59, v59
	v_and_b32_e32 v246, 0xffff0000, v237
	v_mul_f32_e32 v59, v246, v59
	v_add_f32_e32 v60, v60, v156
	v_mul_f32_e32 v60, 0xbfb8aa3b, v60
	v_exp_f32_e32 v60, v60
	s_nop 0
	v_add_f32_e32 v60, 1.0, v60
	v_rcp_f32_e32 v60, v60
	v_lshlrev_b32_e32 v246, 16, v238
	v_mul_f32_e32 v60, v246, v60
	v_add_f32_e32 v61, v61, v157
	v_mul_f32_e32 v61, 0xbfb8aa3b, v61
	v_exp_f32_e32 v61, v61
	s_nop 0
	v_add_f32_e32 v61, 1.0, v61
	v_rcp_f32_e32 v61, v61
	v_and_b32_e32 v246, 0xffff0000, v238
	v_mul_f32_e32 v61, v246, v61
	v_add_f32_e32 v62, v62, v158
	v_mul_f32_e32 v62, 0xbfb8aa3b, v62
	v_exp_f32_e32 v62, v62
	s_nop 0
	v_add_f32_e32 v62, 1.0, v62
	v_rcp_f32_e32 v62, v62
	v_lshlrev_b32_e32 v246, 16, v239
	v_mul_f32_e32 v62, v246, v62
	v_add_f32_e32 v63, v63, v159
	v_mul_f32_e32 v63, 0xbfb8aa3b, v63
	v_exp_f32_e32 v63, v63
	s_nop 0
	v_add_f32_e32 v63, 1.0, v63
	v_rcp_f32_e32 v63, v63
	v_and_b32_e32 v246, 0xffff0000, v239
	v_mul_f32_e32 v63, v246, v63
	global_load_dwordx2 v[224:225], v197, s[12:13]
	global_load_dwordx2 v[226:227], v197, s[12:13] offset:16
	global_load_dwordx2 v[228:229], v197, s[12:13] offset:32
	global_load_dwordx2 v[230:231], v197, s[12:13] offset:48
	global_load_dwordx2 v[232:233], v197, s[12:13] offset:64
	global_load_dwordx2 v[234:235], v197, s[12:13] offset:80
	global_load_dwordx2 v[236:237], v197, s[12:13] offset:96
	global_load_dwordx2 v[238:239], v197, s[12:13] offset:112
	s_add_u32 s12, s12, 0x9000
	s_addc_u32 s13, s13, 0
	v_cvt_pk_bf16_f32 v244, v32, v33
	v_cvt_pk_bf16_f32 v245, v34, v35
	ds_write_b64 v178, v[244:245]
	v_cvt_pk_bf16_f32 v240, v36, v37
	v_cvt_pk_bf16_f32 v241, v38, v39
	ds_write_b64 v179, v[240:241]
	v_cvt_pk_bf16_f32 v242, v40, v41
	v_cvt_pk_bf16_f32 v243, v42, v43
	ds_write_b64 v180, v[242:243]
	v_cvt_pk_bf16_f32 v244, v44, v45
	v_cvt_pk_bf16_f32 v245, v46, v47
	ds_write_b64 v181, v[244:245]
	v_cvt_pk_bf16_f32 v240, v48, v49
	v_cvt_pk_bf16_f32 v241, v50, v51
	ds_write_b64 v188, v[240:241]
	v_cvt_pk_bf16_f32 v242, v52, v53
	v_cvt_pk_bf16_f32 v243, v54, v55
	ds_write_b64 v189, v[242:243]
	v_cvt_pk_bf16_f32 v244, v56, v57
	v_cvt_pk_bf16_f32 v245, v58, v59
	ds_write_b64 v190, v[244:245]
	v_cvt_pk_bf16_f32 v240, v60, v61
	v_cvt_pk_bf16_f32 v241, v62, v63
	ds_write_b64 v191, v[240:241]
	ds_read_b128 v[32:35], v194
	ds_read_b128 v[36:39], v194 offset:1024
	ds_read_b128 v[40:43], v194 offset:2048
	ds_read_b128 v[44:47], v194 offset:3072
	s_waitcnt lgkmcnt(12)
; DI float bf2f(unsigned h) { return __uint_as_float(h << 16); }
; DI int crow(int r, int hf) { return (r & 3) + 8 * (r >> 2) + 4 * hf; }
; DI void glu_phase(const Params& p, int j, char* smem) {
;     ...
;           for (int r = 0; r < 16; ++r) {
;             const int row = m0_ + wm * 64 + i * 32 + crow(r, hf_), col = n0 + wn * 64 + jn * 32 + l32_;
;             const float gt = acc[i][jn][r] + gb[col];
;             const float y = bf2f(yt[(size_t)row * LDYT + col]);
;             o[(size_t)row * LDH + 512 + col] = f2bf(y / (1.f + __expf(-gt)));
	global_store_dwordx4 v195, v[0:3], s[100:101] nt
	s_add_u32 s100, s100, 0x4400
	s_addc_u32 s101, s101, 0
	global_store_dwordx4 v195, v[4:7], s[100:101] nt
	s_add_u32 s100, s100, 0x4400
	s_addc_u32 s101, s101, 0
	global_store_dwordx4 v195, v[8:11], s[100:101] nt
	s_add_u32 s100, s100, 0x4400
	s_addc_u32 s101, s101, 0
	global_store_dwordx4 v195, v[12:15], s[100:101] nt
	s_add_u32 s100, s100, 0x4400
	s_addc_u32 s101, s101, 0
	s_waitcnt vmcnt(12)
	v_add_f32_e32 v64, v64, v128
	v_mul_f32_e32 v64, 0xbfb8aa3b, v64
	v_exp_f32_e32 v64, v64
	s_nop 0
	v_add_f32_e32 v64, 1.0, v64
	v_rcp_f32_e32 v64, v64
	v_lshlrev_b32_e32 v246, 16, v162
	v_mul_f32_e32 v64, v246, v64
	v_add_f32_e32 v65, v65, v129
	v_mul_f32_e32 v65, 0xbfb8aa3b, v65
	v_exp_f32_e32 v65, v65
	s_nop 0
	v_add_f32_e32 v65, 1.0, v65
	v_rcp_f32_e32 v65, v65
	v_and_b32_e32 v246, 0xffff0000, v162
	v_mul_f32_e32 v65, v246, v65
	v_add_f32_e32 v66, v66, v130
	v_mul_f32_e32 v66, 0xbfb8aa3b, v66
	v_exp_f32_e32 v66, v66
	s_nop 0
	v_add_f32_e32 v66, 1.0, v66
	v_rcp_f32_e32 v66, v66
	v_lshlrev_b32_e32 v246, 16, v163
	v_mul_f32_e32 v66, v246, v66
	v_add_f32_e32 v67, v67, v131
	v_mul_f32_e32 v67, 0xbfb8aa3b, v67
	v_exp_f32_e32 v67, v67
	s_nop 0
	v_add_f32_e32 v67, 1.0, v67
	v_rcp_f32_e32 v67, v67
	v_and_b32_e32 v246, 0xffff0000, v163
	v_mul_f32_e32 v67, v246, v67
	v_add_f32_e32 v68, v68, v132
	v_mul_f32_e32 v68, 0xbfb8aa3b, v68
	v_exp_f32_e32 v68, v68
	s_nop 0
	v_add_f32_e32 v68, 1.0, v68
	v_rcp_f32_e32 v68, v68
	v_lshlrev_b32_e32 v246, 16, v164
	v_mul_f32_e32 v68, v246, v68
	v_add_f32_e32 v69, v69, v133
	v_mul_f32_e32 v69, 0xbfb8aa3b, v69
	v_exp_f32_e32 v69, v69
	s_nop 0
	v_add_f32_e32 v69, 1.0, v69
	v_rcp_f32_e32 v69, v69
	v_and_b32_e32 v246, 0xffff0000, v164
	v_mul_f32_e32 v69, v246, v69
	v_add_f32_e32 v70, v70, v134
	v_mul_f32_e32 v70, 0xbfb8aa3b, v70
	v_exp_f32_e32 v70, v70
	s_nop 0
	v_add_f32_e32 v70, 1.0, v70
	v_rcp_f32_e32 v70, v70
	v_lshlrev_b32_e32 v246, 16, v165
	v_mul_f32_e32 v70, v246, v70
	v_add_f32_e32 v71, v71, v135
	v_mul_f32_e32 v71, 0xbfb8aa3b, v71
	v_exp_f32_e32 v71, v71
	s_nop 0
	v_add_f32_e32 v71, 1.0, v71
	v_rcp_f32_e32 v71, v71
	v_and_b32_e32 v246, 0xffff0000, v165
	v_mul_f32_e32 v71, v246, v71
	v_add_f32_e32 v72, v72, v136
	v_mul_f32_e32 v72, 0xbfb8aa3b, v72
	v_exp_f32_e32 v72, v72
	s_nop 0
	v_add_f32_e32 v72, 1.0, v72
	v_rcp_f32_e32 v72, v72
	v_lshlrev_b32_e32 v246, 16, v166
	v_mul_f32_e32 v72, v246, v72
	v_add_f32_e32 v73, v73, v137
	v_mul_f32_e32 v73, 0xbfb8aa3b, v73
	v_exp_f32_e32 v73, v73
	s_nop 0
	v_add_f32_e32 v73, 1.0, v73
	v_rcp_f32_e32 v73, v73
	v_and_b32_e32 v246, 0xffff0000, v166
	v_mul_f32_e32 v73, v246, v73
	v_add_f32_e32 v74, v74, v138
	v_mul_f32_e32 v74, 0xbfb8aa3b, v74
	v_exp_f32_e32 v74, v74
	s_nop 0
	v_add_f32_e32 v74, 1.0, v74
	v_rcp_f32_e32 v74, v74
	v_lshlrev_b32_e32 v246, 16, v167
	v_mul_f32_e32 v74, v246, v74
	v_add_f32_e32 v75, v75, v139
	v_mul_f32_e32 v75, 0xbfb8aa3b, v75
	v_exp_f32_e32 v75, v75
	s_nop 0
	v_add_f32_e32 v75, 1.0, v75
	v_rcp_f32_e32 v75, v75
	v_and_b32_e32 v246, 0xffff0000, v167
	v_mul_f32_e32 v75, v246, v75
	v_add_f32_e32 v76, v76, v140
	v_mul_f32_e32 v76, 0xbfb8aa3b, v76
	v_exp_f32_e32 v76, v76
	s_nop 0
	v_add_f32_e32 v76, 1.0, v76
	v_rcp_f32_e32 v76, v76
	v_lshlrev_b32_e32 v246, 16, v168
	v_mul_f32_e32 v76, v246, v76
	v_add_f32_e32 v77, v77, v141
	v_mul_f32_e32 v77, 0xbfb8aa3b, v77
	v_exp_f32_e32 v77, v77
	s_nop 0
	v_add_f32_e32 v77, 1.0, v77
	v_rcp_f32_e32 v77, v77
	v_and_b32_e32 v246, 0xffff0000, v168
	v_mul_f32_e32 v77, v246, v77
	v_add_f32_e32 v78, v78, v142
	v_mul_f32_e32 v78, 0xbfb8aa3b, v78
	v_exp_f32_e32 v78, v78
	s_nop 0
	v_add_f32_e32 v78, 1.0, v78
	v_rcp_f32_e32 v78, v78
	v_lshlrev_b32_e32 v246, 16, v169
	v_mul_f32_e32 v78, v246, v78
	v_add_f32_e32 v79, v79, v143
	v_mul_f32_e32 v79, 0xbfb8aa3b, v79
	v_exp_f32_e32 v79, v79
	s_nop 0
	v_add_f32_e32 v79, 1.0, v79
	v_rcp_f32_e32 v79, v79
	v_and_b32_e32 v246, 0xffff0000, v169
	v_mul_f32_e32 v79, v246, v79
	v_add_f32_e32 v80, v80, v144
	v_mul_f32_e32 v80, 0xbfb8aa3b, v80
	v_exp_f32_e32 v80, v80
	s_nop 0
	v_add_f32_e32 v80, 1.0, v80
	v_rcp_f32_e32 v80, v80
	v_lshlrev_b32_e32 v246, 16, v170
	v_mul_f32_e32 v80, v246, v80
	v_add_f32_e32 v81, v81, v145
	v_mul_f32_e32 v81, 0xbfb8aa3b, v81
	v_exp_f32_e32 v81, v81
	s_nop 0
	v_add_f32_e32 v81, 1.0, v81
	v_rcp_f32_e32 v81, v81
	v_and_b32_e32 v246, 0xffff0000, v170
	v_mul_f32_e32 v81, v246, v81
	v_add_f32_e32 v82, v82, v146
	v_mul_f32_e32 v82, 0xbfb8aa3b, v82
	v_exp_f32_e32 v82, v82
	s_nop 0
	v_add_f32_e32 v82, 1.0, v82
	v_rcp_f32_e32 v82, v82
	v_lshlrev_b32_e32 v246, 16, v171
	v_mul_f32_e32 v82, v246, v82
	v_add_f32_e32 v83, v83, v147
	v_mul_f32_e32 v83, 0xbfb8aa3b, v83
	v_exp_f32_e32 v83, v83
	s_nop 0
	v_add_f32_e32 v83, 1.0, v83
	v_rcp_f32_e32 v83, v83
	v_and_b32_e32 v246, 0xffff0000, v171
	v_mul_f32_e32 v83, v246, v83
	v_add_f32_e32 v84, v84, v148
	v_mul_f32_e32 v84, 0xbfb8aa3b, v84
	v_exp_f32_e32 v84, v84
	s_nop 0
	v_add_f32_e32 v84, 1.0, v84
	v_rcp_f32_e32 v84, v84
	v_lshlrev_b32_e32 v246, 16, v172
	v_mul_f32_e32 v84, v246, v84
	v_add_f32_e32 v85, v85, v149
	v_mul_f32_e32 v85, 0xbfb8aa3b, v85
	v_exp_f32_e32 v85, v85
	s_nop 0
	v_add_f32_e32 v85, 1.0, v85
	v_rcp_f32_e32 v85, v85
	v_and_b32_e32 v246, 0xffff0000, v172
	v_mul_f32_e32 v85, v246, v85
	v_add_f32_e32 v86, v86, v150
	v_mul_f32_e32 v86, 0xbfb8aa3b, v86
	v_exp_f32_e32 v86, v86
	s_nop 0
	v_add_f32_e32 v86, 1.0, v86
	v_rcp_f32_e32 v86, v86
	v_lshlrev_b32_e32 v246, 16, v173
	v_mul_f32_e32 v86, v246, v86
	v_add_f32_e32 v87, v87, v151
	v_mul_f32_e32 v87, 0xbfb8aa3b, v87
	v_exp_f32_e32 v87, v87
	s_nop 0
	v_add_f32_e32 v87, 1.0, v87
	v_rcp_f32_e32 v87, v87
	v_and_b32_e32 v246, 0xffff0000, v173
; DI float bf2f(unsigned h) { return __uint_as_float(h << 16); }
; DI int crow(int r, int hf) { return (r & 3) + 8 * (r >> 2) + 4 * hf; }
; DI void glu_phase(const Params& p, int j, char* smem) {
;     ...
;           for (int r = 0; r < 16; ++r) {
;             const int row = m0_ + wm * 64 + i * 32 + crow(r, hf_), col = n0 + wn * 64 + jn * 32 + l32_;
;             const float gt = acc[i][jn][r] + gb[col];
;             const float y = bf2f(yt[(size_t)row * LDYT + col]);
;             o[(size_t)row * LDH + 512 + col] = f2bf(y / (1.f + __expf(-gt)));
	v_mul_f32_e32 v87, v246, v87
	v_add_f32_e32 v88, v88, v152
	v_mul_f32_e32 v88, 0xbfb8aa3b, v88
	v_exp_f32_e32 v88, v88
	s_nop 0
	v_add_f32_e32 v88, 1.0, v88
	v_rcp_f32_e32 v88, v88
	v_lshlrev_b32_e32 v246, 16, v174
	v_mul_f32_e32 v88, v246, v88
	v_add_f32_e32 v89, v89, v153
	v_mul_f32_e32 v89, 0xbfb8aa3b, v89
	v_exp_f32_e32 v89, v89
	s_nop 0
	v_add_f32_e32 v89, 1.0, v89
	v_rcp_f32_e32 v89, v89
	v_and_b32_e32 v246, 0xffff0000, v174
	v_mul_f32_e32 v89, v246, v89
	v_add_f32_e32 v90, v90, v154
	v_mul_f32_e32 v90, 0xbfb8aa3b, v90
	v_exp_f32_e32 v90, v90
	s_nop 0
	v_add_f32_e32 v90, 1.0, v90
	v_rcp_f32_e32 v90, v90
	v_lshlrev_b32_e32 v246, 16, v175
	v_mul_f32_e32 v90, v246, v90
	v_add_f32_e32 v91, v91, v155
	v_mul_f32_e32 v91, 0xbfb8aa3b, v91
	v_exp_f32_e32 v91, v91
	s_nop 0
	v_add_f32_e32 v91, 1.0, v91
	v_rcp_f32_e32 v91, v91
	v_and_b32_e32 v246, 0xffff0000, v175
	v_mul_f32_e32 v91, v246, v91
	v_add_f32_e32 v92, v92, v156
	v_mul_f32_e32 v92, 0xbfb8aa3b, v92
	v_exp_f32_e32 v92, v92
	s_nop 0
	v_add_f32_e32 v92, 1.0, v92
	v_rcp_f32_e32 v92, v92
	v_lshlrev_b32_e32 v246, 16, v176
	v_mul_f32_e32 v92, v246, v92
	v_add_f32_e32 v93, v93, v157
	v_mul_f32_e32 v93, 0xbfb8aa3b, v93
	v_exp_f32_e32 v93, v93
	s_nop 0
	v_add_f32_e32 v93, 1.0, v93
	v_rcp_f32_e32 v93, v93
	v_and_b32_e32 v246, 0xffff0000, v176
	v_mul_f32_e32 v93, v246, v93
	v_add_f32_e32 v94, v94, v158
	v_mul_f32_e32 v94, 0xbfb8aa3b, v94
	v_exp_f32_e32 v94, v94
	s_nop 0
	v_add_f32_e32 v94, 1.0, v94
	v_rcp_f32_e32 v94, v94
	v_lshlrev_b32_e32 v246, 16, v177
	v_mul_f32_e32 v94, v246, v94
	v_add_f32_e32 v95, v95, v159
	v_mul_f32_e32 v95, 0xbfb8aa3b, v95
	v_exp_f32_e32 v95, v95
	s_nop 0
	v_add_f32_e32 v95, 1.0, v95
	v_rcp_f32_e32 v95, v95
	v_and_b32_e32 v246, 0xffff0000, v177
	v_mul_f32_e32 v95, v246, v95
	v_cvt_pk_bf16_f32 v242, v64, v65
	v_cvt_pk_bf16_f32 v243, v66, v67
	ds_write_b64 v178, v[242:243]
	v_cvt_pk_bf16_f32 v244, v68, v69
	v_cvt_pk_bf16_f32 v245, v70, v71
	ds_write_b64 v179, v[244:245]
	v_cvt_pk_bf16_f32 v240, v72, v73
	v_cvt_pk_bf16_f32 v241, v74, v75
	ds_write_b64 v180, v[240:241]
	v_cvt_pk_bf16_f32 v242, v76, v77
	v_cvt_pk_bf16_f32 v243, v78, v79
	ds_write_b64 v181, v[242:243]
	v_cvt_pk_bf16_f32 v244, v80, v81
	v_cvt_pk_bf16_f32 v245, v82, v83
	ds_write_b64 v188, v[244:245]
	v_cvt_pk_bf16_f32 v240, v84, v85
	v_cvt_pk_bf16_f32 v241, v86, v87
	ds_write_b64 v189, v[240:241]
	v_cvt_pk_bf16_f32 v242, v88, v89
	v_cvt_pk_bf16_f32 v243, v90, v91
	ds_write_b64 v190, v[242:243]
	v_cvt_pk_bf16_f32 v244, v92, v93
	v_cvt_pk_bf16_f32 v245, v94, v95
	ds_write_b64 v191, v[244:245]
	ds_read_b128 v[64:67], v194
	ds_read_b128 v[68:71], v194 offset:1024
	ds_read_b128 v[72:75], v194 offset:2048
	ds_read_b128 v[76:79], v194 offset:3072
	s_waitcnt lgkmcnt(12)
	global_store_dwordx4 v195, v[32:35], s[100:101] nt
	s_add_u32 s100, s100, 0x4400
	s_addc_u32 s101, s101, 0
	global_store_dwordx4 v195, v[36:39], s[100:101] nt
	s_add_u32 s100, s100, 0x4400
	s_addc_u32 s101, s101, 0
	global_store_dwordx4 v195, v[40:43], s[100:101] nt
	s_add_u32 s100, s100, 0x4400
	s_addc_u32 s101, s101, 0
	global_store_dwordx4 v195, v[44:47], s[100:101] nt
	s_add_u32 s100, s100, 0x4400
	s_addc_u32 s101, s101, 0
	s_waitcnt vmcnt(8)
	v_add_f32_e32 v96, v96, v128
	v_mul_f32_e32 v96, 0xbfb8aa3b, v96
	v_exp_f32_e32 v96, v96
	s_nop 0
	v_add_f32_e32 v96, 1.0, v96
	v_rcp_f32_e32 v96, v96
	v_lshlrev_b32_e32 v246, 16, v224
	v_mul_f32_e32 v96, v246, v96
	v_add_f32_e32 v97, v97, v129
	v_mul_f32_e32 v97, 0xbfb8aa3b, v97
	v_exp_f32_e32 v97, v97
	s_nop 0
	v_add_f32_e32 v97, 1.0, v97
	v_rcp_f32_e32 v97, v97
	v_and_b32_e32 v246, 0xffff0000, v224
	v_mul_f32_e32 v97, v246, v97
	v_add_f32_e32 v98, v98, v130
	v_mul_f32_e32 v98, 0xbfb8aa3b, v98
	v_exp_f32_e32 v98, v98
	s_nop 0
	v_add_f32_e32 v98, 1.0, v98
	v_rcp_f32_e32 v98, v98
	v_lshlrev_b32_e32 v246, 16, v225
	v_mul_f32_e32 v98, v246, v98
	v_add_f32_e32 v99, v99, v131
	v_mul_f32_e32 v99, 0xbfb8aa3b, v99
	v_exp_f32_e32 v99, v99
	s_nop 0
	v_add_f32_e32 v99, 1.0, v99
	v_rcp_f32_e32 v99, v99
	v_and_b32_e32 v246, 0xffff0000, v225
	v_mul_f32_e32 v99, v246, v99
	v_add_f32_e32 v100, v100, v132
	v_mul_f32_e32 v100, 0xbfb8aa3b, v100
	v_exp_f32_e32 v100, v100
	s_nop 0
	v_add_f32_e32 v100, 1.0, v100
	v_rcp_f32_e32 v100, v100
	v_lshlrev_b32_e32 v246, 16, v226
	v_mul_f32_e32 v100, v246, v100
	v_add_f32_e32 v101, v101, v133
	v_mul_f32_e32 v101, 0xbfb8aa3b, v101
	v_exp_f32_e32 v101, v101
	s_nop 0
	v_add_f32_e32 v101, 1.0, v101
	v_rcp_f32_e32 v101, v101
	v_and_b32_e32 v246, 0xffff0000, v226
	v_mul_f32_e32 v101, v246, v101
	v_add_f32_e32 v102, v102, v134
	v_mul_f32_e32 v102, 0xbfb8aa3b, v102
	v_exp_f32_e32 v102, v102
	s_nop 0
	v_add_f32_e32 v102, 1.0, v102
	v_rcp_f32_e32 v102, v102
	v_lshlrev_b32_e32 v246, 16, v227
	v_mul_f32_e32 v102, v246, v102
	v_add_f32_e32 v103, v103, v135
	v_mul_f32_e32 v103, 0xbfb8aa3b, v103
	v_exp_f32_e32 v103, v103
	s_nop 0
	v_add_f32_e32 v103, 1.0, v103
	v_rcp_f32_e32 v103, v103
	v_and_b32_e32 v246, 0xffff0000, v227
	v_mul_f32_e32 v103, v246, v103
	v_add_f32_e32 v104, v104, v136
	v_mul_f32_e32 v104, 0xbfb8aa3b, v104
	v_exp_f32_e32 v104, v104
	s_nop 0
	v_add_f32_e32 v104, 1.0, v104
	v_rcp_f32_e32 v104, v104
	v_lshlrev_b32_e32 v246, 16, v228
	v_mul_f32_e32 v104, v246, v104
	v_add_f32_e32 v105, v105, v137
	v_mul_f32_e32 v105, 0xbfb8aa3b, v105
	v_exp_f32_e32 v105, v105
	s_nop 0
	v_add_f32_e32 v105, 1.0, v105
	v_rcp_f32_e32 v105, v105
	v_and_b32_e32 v246, 0xffff0000, v228
	v_mul_f32_e32 v105, v246, v105
	v_add_f32_e32 v106, v106, v138
	v_mul_f32_e32 v106, 0xbfb8aa3b, v106
	v_exp_f32_e32 v106, v106
	s_nop 0
	v_add_f32_e32 v106, 1.0, v106
	v_rcp_f32_e32 v106, v106
	v_lshlrev_b32_e32 v246, 16, v229
; DI float bf2f(unsigned h) { return __uint_as_float(h << 16); }
; DI int crow(int r, int hf) { return (r & 3) + 8 * (r >> 2) + 4 * hf; }
; DI void glu_phase(const Params& p, int j, char* smem) {
;     ...
;   for (int lt = blockIdx.x >> 3; lt < 16 * nN; lt += gridDim.x >> 3) {
;     int mt, nt; tile_map(lt, 16, nN, 16, 2, mt, nt);
;     const int m0 = mt * 256, n0 = nt * 256;
;     ...
; #pragma unroll
;       for (int i = 0; i < 2; ++i)
; #pragma unroll
;         for (int jn = 0; jn < 2; ++jn)
; #pragma unroll
;           for (int r = 0; r < 16; ++r) {
;             const int row = m0_ + wm * 64 + i * 32 + crow(r, hf_), col = n0 + wn * 64 + jn * 32 + l32_;
;             const float gt = acc[i][jn][r] + gb[col];
;             const float y = bf2f(yt[(size_t)row * LDYT + col]);
;             o[(size_t)row * LDH + 512 + col] = f2bf(y / (1.f + __expf(-gt)));
	v_mul_f32_e32 v106, v246, v106
	v_add_f32_e32 v107, v107, v139
	v_mul_f32_e32 v107, 0xbfb8aa3b, v107
	v_exp_f32_e32 v107, v107
	s_nop 0
	v_add_f32_e32 v107, 1.0, v107
	v_rcp_f32_e32 v107, v107
	v_and_b32_e32 v246, 0xffff0000, v229
	v_mul_f32_e32 v107, v246, v107
	v_add_f32_e32 v108, v108, v140
	v_mul_f32_e32 v108, 0xbfb8aa3b, v108
	v_exp_f32_e32 v108, v108
	s_nop 0
	v_add_f32_e32 v108, 1.0, v108
	v_rcp_f32_e32 v108, v108
	v_lshlrev_b32_e32 v246, 16, v230
	v_mul_f32_e32 v108, v246, v108
	v_add_f32_e32 v109, v109, v141
	v_mul_f32_e32 v109, 0xbfb8aa3b, v109
	v_exp_f32_e32 v109, v109
	s_nop 0
	v_add_f32_e32 v109, 1.0, v109
	v_rcp_f32_e32 v109, v109
	v_and_b32_e32 v246, 0xffff0000, v230
	v_mul_f32_e32 v109, v246, v109
	v_add_f32_e32 v110, v110, v142
	v_mul_f32_e32 v110, 0xbfb8aa3b, v110
	v_exp_f32_e32 v110, v110
	s_nop 0
	v_add_f32_e32 v110, 1.0, v110
	v_rcp_f32_e32 v110, v110
	v_lshlrev_b32_e32 v246, 16, v231
	v_mul_f32_e32 v110, v246, v110
	v_add_f32_e32 v111, v111, v143
	v_mul_f32_e32 v111, 0xbfb8aa3b, v111
	v_exp_f32_e32 v111, v111
	s_nop 0
	v_add_f32_e32 v111, 1.0, v111
	v_rcp_f32_e32 v111, v111
	v_and_b32_e32 v246, 0xffff0000, v231
	v_mul_f32_e32 v111, v246, v111
	v_add_f32_e32 v112, v112, v144
	v_mul_f32_e32 v112, 0xbfb8aa3b, v112
	v_exp_f32_e32 v112, v112
	s_nop 0
	v_add_f32_e32 v112, 1.0, v112
	v_rcp_f32_e32 v112, v112
	v_lshlrev_b32_e32 v246, 16, v232
	v_mul_f32_e32 v112, v246, v112
	v_add_f32_e32 v113, v113, v145
	v_mul_f32_e32 v113, 0xbfb8aa3b, v113
	v_exp_f32_e32 v113, v113
	s_nop 0
	v_add_f32_e32 v113, 1.0, v113
	v_rcp_f32_e32 v113, v113
	v_and_b32_e32 v246, 0xffff0000, v232
	v_mul_f32_e32 v113, v246, v113
	v_add_f32_e32 v114, v114, v146
	v_mul_f32_e32 v114, 0xbfb8aa3b, v114
	v_exp_f32_e32 v114, v114
	s_nop 0
	v_add_f32_e32 v114, 1.0, v114
	v_rcp_f32_e32 v114, v114
	v_lshlrev_b32_e32 v246, 16, v233
	v_mul_f32_e32 v114, v246, v114
	v_add_f32_e32 v115, v115, v147
	v_mul_f32_e32 v115, 0xbfb8aa3b, v115
	v_exp_f32_e32 v115, v115
	s_nop 0
	v_add_f32_e32 v115, 1.0, v115
	v_rcp_f32_e32 v115, v115
	v_and_b32_e32 v246, 0xffff0000, v233
	v_mul_f32_e32 v115, v246, v115
	v_add_f32_e32 v116, v116, v148
	v_mul_f32_e32 v116, 0xbfb8aa3b, v116
	v_exp_f32_e32 v116, v116
	s_nop 0
	v_add_f32_e32 v116, 1.0, v116
	v_rcp_f32_e32 v116, v116
	v_lshlrev_b32_e32 v246, 16, v234
	v_mul_f32_e32 v116, v246, v116
	v_add_f32_e32 v117, v117, v149
	v_mul_f32_e32 v117, 0xbfb8aa3b, v117
	v_exp_f32_e32 v117, v117
	s_nop 0
	v_add_f32_e32 v117, 1.0, v117
	v_rcp_f32_e32 v117, v117
	v_and_b32_e32 v246, 0xffff0000, v234
	v_mul_f32_e32 v117, v246, v117
	v_add_f32_e32 v118, v118, v150
	v_mul_f32_e32 v118, 0xbfb8aa3b, v118
	v_exp_f32_e32 v118, v118
	s_nop 0
	v_add_f32_e32 v118, 1.0, v118
	v_rcp_f32_e32 v118, v118
	v_lshlrev_b32_e32 v246, 16, v235
	v_mul_f32_e32 v118, v246, v118
	v_add_f32_e32 v119, v119, v151
	v_mul_f32_e32 v119, 0xbfb8aa3b, v119
	v_exp_f32_e32 v119, v119
	s_nop 0
	v_add_f32_e32 v119, 1.0, v119
	v_rcp_f32_e32 v119, v119
	v_and_b32_e32 v246, 0xffff0000, v235
	v_mul_f32_e32 v119, v246, v119
	v_add_f32_e32 v120, v120, v152
	v_mul_f32_e32 v120, 0xbfb8aa3b, v120
	v_exp_f32_e32 v120, v120
	s_nop 0
	v_add_f32_e32 v120, 1.0, v120
	v_rcp_f32_e32 v120, v120
	v_lshlrev_b32_e32 v246, 16, v236
	v_mul_f32_e32 v120, v246, v120
	v_add_f32_e32 v121, v121, v153
	v_mul_f32_e32 v121, 0xbfb8aa3b, v121
	v_exp_f32_e32 v121, v121
	s_nop 0
	v_add_f32_e32 v121, 1.0, v121
	v_rcp_f32_e32 v121, v121
	v_and_b32_e32 v246, 0xffff0000, v236
	v_mul_f32_e32 v121, v246, v121
	v_add_f32_e32 v122, v122, v154
	v_mul_f32_e32 v122, 0xbfb8aa3b, v122
	v_exp_f32_e32 v122, v122
	s_nop 0
	v_add_f32_e32 v122, 1.0, v122
	v_rcp_f32_e32 v122, v122
	v_lshlrev_b32_e32 v246, 16, v237
	v_mul_f32_e32 v122, v246, v122
	v_add_f32_e32 v123, v123, v155
	v_mul_f32_e32 v123, 0xbfb8aa3b, v123
	v_exp_f32_e32 v123, v123
	s_nop 0
	v_add_f32_e32 v123, 1.0, v123
	v_rcp_f32_e32 v123, v123
	v_and_b32_e32 v246, 0xffff0000, v237
	v_mul_f32_e32 v123, v246, v123
	v_add_f32_e32 v124, v124, v156
	v_mul_f32_e32 v124, 0xbfb8aa3b, v124
	v_exp_f32_e32 v124, v124
	s_nop 0
	v_add_f32_e32 v124, 1.0, v124
	v_rcp_f32_e32 v124, v124
	v_lshlrev_b32_e32 v246, 16, v238
	v_mul_f32_e32 v124, v246, v124
	v_add_f32_e32 v125, v125, v157
	v_mul_f32_e32 v125, 0xbfb8aa3b, v125
	v_exp_f32_e32 v125, v125
	s_nop 0
	v_add_f32_e32 v125, 1.0, v125
	v_rcp_f32_e32 v125, v125
	v_and_b32_e32 v246, 0xffff0000, v238
	v_mul_f32_e32 v125, v246, v125
	v_add_f32_e32 v126, v126, v158
	v_mul_f32_e32 v126, 0xbfb8aa3b, v126
	v_exp_f32_e32 v126, v126
	s_nop 0
	v_add_f32_e32 v126, 1.0, v126
	v_rcp_f32_e32 v126, v126
	v_lshlrev_b32_e32 v246, 16, v239
	v_mul_f32_e32 v126, v246, v126
	v_add_f32_e32 v127, v127, v159
	v_mul_f32_e32 v127, 0xbfb8aa3b, v127
	v_exp_f32_e32 v127, v127
	s_nop 0
	v_add_f32_e32 v127, 1.0, v127
	v_rcp_f32_e32 v127, v127
	v_and_b32_e32 v246, 0xffff0000, v239
	v_mul_f32_e32 v127, v246, v127
	v_cvt_pk_bf16_f32 v240, v96, v97
	v_cvt_pk_bf16_f32 v241, v98, v99
	ds_write_b64 v178, v[240:241]
	v_cvt_pk_bf16_f32 v242, v100, v101
	v_cvt_pk_bf16_f32 v243, v102, v103
	ds_write_b64 v179, v[242:243]
	v_cvt_pk_bf16_f32 v244, v104, v105
	v_cvt_pk_bf16_f32 v245, v106, v107
	ds_write_b64 v180, v[244:245]
	v_cvt_pk_bf16_f32 v240, v108, v109
	v_cvt_pk_bf16_f32 v241, v110, v111
	ds_write_b64 v181, v[240:241]
	v_cvt_pk_bf16_f32 v242, v112, v113
	v_cvt_pk_bf16_f32 v243, v114, v115
	ds_write_b64 v188, v[242:243]
	v_cvt_pk_bf16_f32 v244, v116, v117
	v_cvt_pk_bf16_f32 v245, v118, v119
	ds_write_b64 v189, v[244:245]
	v_cvt_pk_bf16_f32 v240, v120, v121
	v_cvt_pk_bf16_f32 v241, v122, v123
	ds_write_b64 v190, v[240:241]
	v_cvt_pk_bf16_f32 v242, v124, v125
	v_cvt_pk_bf16_f32 v243, v126, v127
	ds_write_b64 v191, v[242:243]
	ds_read_b128 v[96:99], v194
	ds_read_b128 v[100:103], v194 offset:1024
	ds_read_b128 v[104:107], v194 offset:2048
	ds_read_b128 v[108:111], v194 offset:3072
	s_waitcnt lgkmcnt(12)
	global_store_dwordx4 v195, v[64:67], s[100:101] nt
	s_add_u32 s100, s100, 0x4400
	s_addc_u32 s101, s101, 0
	global_store_dwordx4 v195, v[68:71], s[100:101] nt
	s_add_u32 s100, s100, 0x4400
	s_addc_u32 s101, s101, 0
	global_store_dwordx4 v195, v[72:75], s[100:101] nt
	s_add_u32 s100, s100, 0x4400
	s_addc_u32 s101, s101, 0
	global_store_dwordx4 v195, v[76:79], s[100:101] nt
	s_add_u32 s100, s100, 0x4400
	s_addc_u32 s101, s101, 0
	s_waitcnt lgkmcnt(0)
	global_store_dwordx4 v195, v[96:99], s[100:101] nt
	s_add_u32 s100, s100, 0x4400
	s_addc_u32 s101, s101, 0
	global_store_dwordx4 v195, v[100:103], s[100:101] nt
	s_add_u32 s100, s100, 0x4400
	s_addc_u32 s101, s101, 0
	global_store_dwordx4 v195, v[104:107], s[100:101] nt
	s_add_u32 s100, s100, 0x4400
	s_addc_u32 s101, s101, 0
	global_store_dwordx4 v195, v[108:111], s[100:101] nt
	s_waitcnt lgkmcnt(0)
	s_add_u32 s28, s28, s30
	s_cmp_lt_u32 s28, 0x20
	s_cbranch_scc1 .Lgl_tile
	s_waitcnt vmcnt(0) lgkmcnt(0)
	s_cmp_lt_u32 s15, 4
	s_cbranch_scc0 .Lgl_pp_trail
	s_barrier
.Lgl_pp_trail:
.LBB0_721:
	s_mov_b64 s[0:1], 0

; DI int opqv(int x) { asm volatile("" : "+v"(x)); return x; }
; DI char* opq(char* p) { asm volatile("" : "+s"(p)); return p; }
;     ...
;   const int drow = lane >> 3, dslot = lane & 7, x7 = (l32 >> 1) & 7;
; DI void rec_in_phase(const Params& p, int j, char* smem) {
;   const int tid = opqv(threadIdx.x), lane = tid & 63, w = tid >> 6, wm = w >> 2, wn = w & 3, l32 = lane & 31, hf = lane >> 5;
;   char* ws = opq(p.ws);
;   const u16* A = (const u16*)(ws + OFF_HY);
;   const u16* Wt = (const u16*)(ws + OFF_W_RECIN) + (size_t)j * 2560 * LDW1;
;   u16* zr = (u16*)(ws + OFF_ZR); u16* ug = (u16*)(ws + OFF_UG);
;   const float2* rt128 = (const float2*)(ws + OFF_RT128);
;   const int nN = 10;
;   for (int lt = blockIdx.x >> 3; lt < 16 * nN; lt += gridDim.x >> 3) {
;     int mt, nt; tile_map(lt, 16, nN, 16, 2, mt, nt);
;     const int m0 = mt * 256, n0 = nt * 256;
;     gemm_tile(A + (size_t)m0 * LDH, LDH, 16, nullptr, 0, 0, Wt + (size_t)n0 * LDW1, LDW1, smem, [&](f32x16(&acc)[2][2], int moff) {
.LBB0_779:
	s_and_b64 vcc, exec, s[0:1]
	s_cbranch_vccz .LBB0_846
	v_readlane_b32 s0, v252, 5
	v_readlane_b32 s1, v252, 6
	s_andn2_b64 vcc, exec, s[0:1]
	v_readlane_b32 s0, v254, 25
	v_readlane_b32 s1, v254, 26
	s_ashr_i32 s1, s0, 31
	v_readlane_b32 s4, v251, 13
	v_writelane_b32 v254, s0, 25
	v_mov_b32_e32 v0, v182
	v_readlane_b32 s5, v251, 14
	v_writelane_b32 v254, s1, 26
	s_mov_b32 s40, 0x3fb8aa3b
	s_mov_b32 s41, 0xc2ce8ed0
	s_mov_b32 s50, 0x42b17218
	s_mov_b64 s[52:53], 0x1d84180
	s_mov_b64 s[54:55], 0x1d84200
	s_cbranch_vccnz .LBB0_819
	v_readlane_b32 s28, v253, 48
	v_readlane_b32 s30, v253, 50
	s_cmp_ge_u32 s28, 0xa0
	s_cbranch_scc1 .LBB0_819
	s_add_u32 s0, s4, 0x8c04100
	s_addc_u32 s1, s5, 0
	v_readlane_b32 s6, v254, 25
	v_readlane_b32 s31, v251, 0
	s_mul_i32 s6, s6, 0x550000
	s_add_u32 s6, s4, s6
	s_addc_u32 s7, s5, 0
	s_add_u32 s6, s6, 0x1d84100
	s_addc_u32 s7, s7, 0
	s_and_b32 s31, s31, 7
	s_lshl_b32 s31, s31, 4
	s_lshr_b32 s8, s28, 1
	s_add_u32 s31, s31, s8
	s_mul_i32 s8, s31, 0x88000
	s_add_u32 s34, s0, s8
	s_addc_u32 s35, s1, 0
	v_lshrrev_b32_e32 v228, 6, v182
	v_and_b32_e32 v229, 63, v182
	v_readfirstlane_b32 s15, v228
	v_and_b32_e32 v230, 31, v229
	v_lshrrev_b32_e32 v231, 5, v229
	v_lshrrev_b32_e32 v232, 3, v229
	v_and_b32_e32 v233, 7, v229
	s_lshr_b32 s8, s15, 2
	s_lshl_b32 s8, s8, 7
	s_and_b32 s9, s15, 3
	s_lshl_b32 s9, s9, 4
	s_add_u32 s10, s8, s9
	v_lshrrev_b32_e32 v234, 1, v232
	v_xor_b32_e32 v234, v233, v234
	v_lshlrev_b32_e32 v234, 4, v234
	s_add_u32 s11, s10, 0
	v_add_u32_e32 v235, s11, v232
	s_movk_i32 s11, 0x880
	v_mad_u32_u24 v220, v235, s11, v234
	v_lshrrev_b32_e32 v234, 1, v232
	v_add_u32_e32 v234, 4, v234
	v_xor_b32_e32 v234, v233, v234
	v_lshlrev_b32_e32 v234, 4, v234
	s_add_u32 s11, s10, 8
	v_add_u32_e32 v235, s11, v232
	s_movk_i32 s11, 0x880
	v_mad_u32_u24 v221, v235, s11, v234
	v_lshrrev_b32_e32 v234, 1, v232
	v_xor_b32_e32 v234, v233, v234
	v_lshlrev_b32_e32 v234, 4, v234
	s_add_u32 s11, s10, 64
	v_add_u32_e32 v235, s11, v232
	s_movk_i32 s11, 0x880
	v_mad_u32_u24 v222, v235, s11, v234
	v_lshrrev_b32_e32 v234, 1, v232
	v_add_u32_e32 v234, 4, v234
	v_xor_b32_e32 v234, v233, v234
	v_lshlrev_b32_e32 v234, 4, v234
	s_add_u32 s11, s10, 72
	v_add_u32_e32 v235, s11, v232
	s_movk_i32 s11, 0x880
	v_mad_u32_u24 v223, v235, s11, v234
	v_and_b32_e32 v244, 63, v182
	v_lshrrev_b32_e32 v245, 3, v244
	v_and_b32_e32 v246, 7, v244
	s_lshr_b32 s8, s15, 2
	s_lshl_b32 s8, s8, 1
	s_bfe_u32 s9, s15, 0x10001
	s_add_u32 s8, s8, s9
	s_lshl_b32 s8, s8, 6
	s_and_b32 s9, s15, 1
	s_lshl_b32 s9, s9, 4
	s_add_u32 s8, s8, s9
	v_lshrrev_b32_e32 v247, 1, v245
	v_xor_b32_e32 v247, v246, v247
	v_lshlrev_b32_e32 v247, 4, v247
	s_add_u32 s9, s8, 0
	v_add_u32_e32 v244, s9, v245
	s_movk_i32 s9, 0x880
	v_mad_u32_u24 v240, v244, s9, v247
	v_lshrrev_b32_e32 v247, 1, v245
	v_add_u32_e32 v247, 4, v247
	v_xor_b32_e32 v247, v246, v247
	v_lshlrev_b32_e32 v247, 4, v247
	s_add_u32 s9, s8, 8
	v_add_u32_e32 v244, s9, v245
	s_movk_i32 s9, 0x880
	v_mad_u32_u24 v241, v244, s9, v247
	v_lshrrev_b32_e32 v247, 1, v245
	v_xor_b32_e32 v247, v246, v247
	v_lshlrev_b32_e32 v247, 4, v247
	s_add_u32 s9, s8, 32
	v_add_u32_e32 v244, s9, v245
	s_movk_i32 s9, 0x880
	v_mad_u32_u24 v242, v244, s9, v247
	v_lshrrev_b32_e32 v247, 1, v245
	v_add_u32_e32 v247, 4, v247
	v_xor_b32_e32 v247, v246, v247
	v_lshlrev_b32_e32 v247, 4, v247
	s_add_u32 s9, s8, 40
	v_add_u32_e32 v244, s9, v245
	s_movk_i32 s9, 0x880
	v_mad_u32_u24 v243, v244, s9, v247
	v_lshrrev_b32_e32 v236, 1, v230
	v_and_b32_e32 v236, 7, v236
	s_lshr_b32 s8, s15, 2
	s_and_b32 s9, s15, 3
	s_lshl_b32 s10, s8, 14
	s_add_u32 s10, s10, 32
	s_lshr_b32 s11, s9, 1
	s_lshl_b32 s11, s11, 14
	s_add_u32 s11, s11, 0x8020
	v_lshlrev_b32_e32 v237, 7, v230
	v_add_u32_e32 v238, s11, v237
	s_and_b32 s11, s9, 1
	s_lshl_b32 s11, s11, 12
	v_add_u32_e32 v238, s11, v238
	v_add_u32_e32 v237, s10, v237
	v_add_u32_e32 v239, 0, v231
	v_xor_b32_e32 v239, v239, v236
	v_lshlrev_b32_e32 v239, 4, v239
; DI int opqv(int x) { asm volatile("" : "+v"(x)); return x; }
; DI char* opq(char* p) { asm volatile("" : "+s"(p)); return p; }
; #define RAWBAR() { asm volatile("s_waitcnt vmcnt(0) lgkmcnt(0)" ::: "memory"); __builtin_amdgcn_s_barrier(); }
;     ...
;   const int drow = lane >> 3, dslot = lane & 7, x7 = (l32 >> 1) & 7;
;     ...
;   if (V != 1) GLDS(0, 0);
;   RAWBAR();
; DI void rec_in_phase(const Params& p, int j, char* smem) {
;   const int tid = opqv(threadIdx.x), lane = tid & 63, w = tid >> 6, wm = w >> 2, wn = w & 3, l32 = lane & 31, hf = lane >> 5;
;   char* ws = opq(p.ws);
;   const u16* A = (const u16*)(ws + OFF_HY);
;   const u16* Wt = (const u16*)(ws + OFF_W_RECIN) + (size_t)j * 2560 * LDW1;
;   u16* zr = (u16*)(ws + OFF_ZR); u16* ug = (u16*)(ws + OFF_UG);
;   const float2* rt128 = (const float2*)(ws + OFF_RT128);
;   const int nN = 10;
;   for (int lt = blockIdx.x >> 3; lt < 16 * nN; lt += gridDim.x >> 3) {
;     int mt, nt; tile_map(lt, 16, nN, 16, 2, mt, nt);
;     const int m0 = mt * 256, n0 = nt * 256;
;     gemm_tile(A + (size_t)m0 * LDH, LDH, 16, nullptr, 0, 0, Wt + (size_t)n0 * LDW1, LDW1, smem, [&](f32x16(&acc)[2][2], int moff) {
	v_add_u32_e32 v204, v237, v239
	v_add_u32_e32 v212, v238, v239
	v_add_u32_e32 v208, 0x10000, v204
	v_add_u32_e32 v216, 0x10000, v212
	v_add_u32_e32 v239, 2, v231
	v_xor_b32_e32 v239, v239, v236
	v_lshlrev_b32_e32 v239, 4, v239
	v_add_u32_e32 v205, v237, v239
	v_add_u32_e32 v213, v238, v239
	v_add_u32_e32 v209, 0x10000, v205
	v_add_u32_e32 v217, 0x10000, v213
	v_add_u32_e32 v239, 4, v231
	v_xor_b32_e32 v239, v239, v236
	v_lshlrev_b32_e32 v239, 4, v239
	v_add_u32_e32 v206, v237, v239
	v_add_u32_e32 v214, v238, v239
	v_add_u32_e32 v210, 0x10000, v206
	v_add_u32_e32 v218, 0x10000, v214
	v_add_u32_e32 v239, 6, v231
	v_xor_b32_e32 v239, v239, v236
	v_lshlrev_b32_e32 v239, 4, v239
	v_add_u32_e32 v207, v237, v239
	v_add_u32_e32 v215, v238, v239
	v_add_u32_e32 v211, 0x10000, v207
	v_add_u32_e32 v219, 0x10000, v215
	s_lshl_b32 s10, s15, 12
	s_add_u32 s10, s10, 0x18020
	v_lshlrev_b32_e32 v234, 7, v230
	v_lshlrev_b32_e32 v235, 3, v231
	v_add3_u32 v234, v234, v235, s10
	v_and_b32_e32 v235, 7, v230
	v_mov_b32_e32 v178, v235
	v_xor_b32_e32 v179, 1, v235
	v_xor_b32_e32 v180, 2, v235
	v_xor_b32_e32 v181, 3, v235
	v_xor_b32_e32 v188, 4, v235
	v_xor_b32_e32 v189, 5, v235
	v_xor_b32_e32 v190, 6, v235
	v_xor_b32_e32 v191, 7, v235
	v_lshl_add_u32 v178, v178, 4, v234
	v_lshl_add_u32 v179, v179, 4, v234
	v_lshl_add_u32 v180, v180, 4, v234
	v_lshl_add_u32 v181, v181, 4, v234
	v_lshl_add_u32 v188, v188, 4, v234
	v_lshl_add_u32 v189, v189, 4, v234
	v_lshl_add_u32 v190, v190, 4, v234
	v_lshl_add_u32 v191, v191, 4, v234
	v_xor_b32_e32 v194, v232, v233
	v_lshlrev_b32_e32 v194, 4, v194
	v_lshl_add_u32 v194, v232, 7, v194
	v_add_u32_e32 v194, s10, v194
	s_lshl_b32 s14, s8, 14
	s_lshl_b32 s10, s9, 11
	s_add_u32 s14, s14, s10
	s_add_u32 s14, s14, 32
	s_lshl_b32 s12, s8, 7
	s_mov_b32 s13, s9
	v_lshlrev_b32_e32 v195, 4, v233
	s_movk_i32 s10, 0x1080
	v_mad_u32_u24 v195, v232, s10, v195
	v_lshrrev_b32_e32 v234, 2, v233
	v_lshl_add_u32 v196, v234, 6, v195
	v_lshrrev_b32_e32 v234, 1, v233
	v_and_b32_e32 v235, 1, v233
	v_lshlrev_b32_e32 v235, 4, v235
	v_lshl_add_u32 v197, v234, 20, v235
	v_lshl_add_u32 v197, v232, 5, v197
	v_lshlrev_b32_e32 v160, 9, v230
	v_lshl_add_u32 v160, v231, 5, v160
	s_lshl_b32 s10, s31, 8
	s_add_u32 s10, s10, s12
	s_and_b32 s10, s10, 0x3fff
	s_lshl_b32 s10, s10, 9
	s_and_b32 s11, s13, 1
	s_lshl_b32 s11, s11, 8
	s_add_u32 s10, s10, s11
	s_add_u32 s36, s4, s10
	s_addc_u32 s37, s5, 0
	s_add_u32 s36, s36, 0x634100
	s_addc_u32 s37, s37, 0
	s_mov_b32 s27, s28
	s_mov_b32 s26, 0
	s_lshr_b32 s8, s27, 5
	s_lshl_b32 s8, s8, 1
	s_and_b32 s9, s27, 1
	s_add_u32 s8, s8, s9
	s_mul_i32 s8, s8, 0x88000
	s_add_u32 s24, s6, s8
	s_addc_u32 s25, s7, 0
	s_mov_b64 s[22:23], s[34:35]
	s_add_u32 m0, s14, 0x8000
	s_nop 0
	global_load_lds_dwordx4 v240, s[24:25]
	s_add_u32 m0, s14, 0x8400
	s_nop 0
	global_load_lds_dwordx4 v241, s[24:25]
	s_add_u32 m0, s14, 0x0
	s_nop 0
	global_load_lds_dwordx4 v220, s[22:23]
	s_add_u32 m0, s14, 0x400
	s_nop 0
	global_load_lds_dwordx4 v221, s[22:23]
	s_add_u32 m0, s14, 0xa000
	s_nop 0
	global_load_lds_dwordx4 v242, s[24:25]
	s_add_u32 m0, s14, 0xa400
	s_nop 0
	global_load_lds_dwordx4 v243, s[24:25]
	s_add_u32 m0, s14, 0x2000
	s_nop 0
	global_load_lds_dwordx4 v222, s[22:23]
	s_add_u32 m0, s14, 0x2400
	s_nop 0
	global_load_lds_dwordx4 v223, s[22:23]
	s_add_u32 s22, s22, 0x80
	s_addc_u32 s23, s23, 0
	s_add_u32 s24, s24, 0x80
	s_addc_u32 s25, s25, 0
	s_add_u32 s26, s26, 1
	s_cmp_eq_u32 s26, 16
	s_cbranch_scc0 .Lri1_cadv_done
	s_mov_b32 s26, 0
	s_add_u32 s27, s27, s30
	s_cmp_lt_u32 s27, 0xa0
	s_cbranch_scc1 .Lri1_cadv_new
	s_sub_u32 s22, s22, 0x800
	s_subb_u32 s23, s23, 0
	s_sub_u32 s24, s24, 0x800
	s_subb_u32 s25, s25, 0
	s_branch .Lri1_cadv_done
.Lri1_cadv_new:
	s_lshr_b32 s8, s27, 5
	s_lshl_b32 s8, s8, 1
	s_and_b32 s9, s27, 1
	s_add_u32 s8, s8, s9
	s_mul_i32 s8, s8, 0x88000
	s_add_u32 s24, s6, s8
	s_addc_u32 s25, s7, 0
	s_mov_b64 s[22:23], s[34:35]
.Lri1_cadv_done:
	s_cmp_lt_u32 s15, 4
	s_cbranch_scc1 .Lri_pp_lead
	s_barrier

; #define RAWBAR() { asm volatile("s_waitcnt vmcnt(0) lgkmcnt(0)" ::: "memory"); __builtin_amdgcn_s_barrier(); }
;     ...
;   if (V != 1) GLDS(0, 0);
;   RAWBAR();
;   for (int kt = 0; kt < nk; kt += 2) {
;     if (V != 1) GLDS(kt + 1, 1);
.Lri_tile:
	v_and_b32_e32 v244, 63, v182
	v_lshrrev_b32_e32 v245, 3, v244
	v_and_b32_e32 v246, 7, v244
	s_lshr_b32 s8, s15, 2
	s_lshl_b32 s8, s8, 1
	s_bfe_u32 s9, s15, 0x10001
	s_add_u32 s8, s8, s9
	s_lshl_b32 s8, s8, 6
	s_and_b32 s9, s15, 1
	s_lshl_b32 s9, s9, 4
	s_add_u32 s8, s8, s9
	v_lshrrev_b32_e32 v247, 1, v245
	v_xor_b32_e32 v247, v246, v247
	v_lshlrev_b32_e32 v247, 4, v247
	s_add_u32 s9, s8, 0
	v_add_u32_e32 v244, s9, v245
	s_movk_i32 s9, 0x880
	v_mad_u32_u24 v240, v244, s9, v247
	v_lshrrev_b32_e32 v247, 1, v245
	v_add_u32_e32 v247, 4, v247
	v_xor_b32_e32 v247, v246, v247
	v_lshlrev_b32_e32 v247, 4, v247
	s_add_u32 s9, s8, 8
	v_add_u32_e32 v244, s9, v245
	s_movk_i32 s9, 0x880
	v_mad_u32_u24 v241, v244, s9, v247
	v_lshrrev_b32_e32 v247, 1, v245
	v_xor_b32_e32 v247, v246, v247
	v_lshlrev_b32_e32 v247, 4, v247
	s_add_u32 s9, s8, 32
	v_add_u32_e32 v244, s9, v245
	s_movk_i32 s9, 0x880
	v_mad_u32_u24 v242, v244, s9, v247
	v_lshrrev_b32_e32 v247, 1, v245
	v_add_u32_e32 v247, 4, v247
	v_xor_b32_e32 v247, v246, v247
	v_lshlrev_b32_e32 v247, 4, v247
	s_add_u32 s9, s8, 40
	v_add_u32_e32 v244, s9, v245
	s_movk_i32 s9, 0x880
	v_mad_u32_u24 v243, v244, s9, v247
	s_add_u32 m0, s14, 0x12000
	ds_read_b128 v[162:165], v212
	ds_read_b128 v[166:169], v213
	ds_read_b128 v[170:173], v214
	ds_read_b128 v[174:177], v215
	global_load_lds_dwordx4 v222, s[22:23]
	s_add_u32 m0, s14, 0x12400
	ds_read_b128 v[128:131], v204
	ds_read_b128 v[132:135], v205
	ds_read_b128 v[136:139], v206
	ds_read_b128 v[140:143], v207
	global_load_lds_dwordx4 v223, s[22:23]
	ds_read_b128 v[144:147], v204 offset:4096
	ds_read_b128 v[148:151], v205 offset:4096
	ds_read_b128 v[152:155], v206 offset:4096
	ds_read_b128 v[156:159], v207 offset:4096
	s_add_u32 s22, s22, 0x80
	s_addc_u32 s23, s23, 0
	s_add_u32 s24, s24, 0x80
	s_addc_u32 s25, s25, 0
	s_add_u32 s26, s26, 1
	s_cmp_eq_u32 s26, 16
	s_cbranch_scc0 .Lri2_cadv_done
	s_mov_b32 s26, 0
	s_add_u32 s27, s27, s30
	s_cmp_lt_u32 s27, 0xa0
	s_cbranch_scc1 .Lri2_cadv_new
	s_sub_u32 s22, s22, 0x800
	s_subb_u32 s23, s23, 0
	s_sub_u32 s24, s24, 0x800
	s_subb_u32 s25, s25, 0
	s_branch .Lri2_cadv_done

; #define RAWBAR() { asm volatile("s_waitcnt vmcnt(0) lgkmcnt(0)" ::: "memory"); __builtin_amdgcn_s_barrier(); }
;     ...
;   if (V != 1) GLDS(0, 0);
;   RAWBAR();
;   for (int kt = 0; kt < nk; kt += 2) {
;     if (V != 1) GLDS(kt + 1, 1);
;     if (V != 2) COMPUTE(0);
;     RAWBAR();
;     if (V != 1) if (kt + 2 < nk) GLDS(kt + 2, 0);
;     if (V != 2) COMPUTE(1);
;     RAWBAR();
;   }
.Lri2_cadv_done:
	s_waitcnt lgkmcnt(8)
	s_barrier
	s_waitcnt lgkmcnt(0)
	s_setprio 1
	v_mfma_f32_32x32x16_bf16 v[0:15], v[162:165], v[128:131], 0
	v_mfma_f32_32x32x16_bf16 v[32:47], v[162:165], v[144:147], 0
	v_mfma_f32_32x32x16_bf16 v[0:15], v[166:169], v[132:135], v[0:15]
	v_mfma_f32_32x32x16_bf16 v[32:47], v[166:169], v[148:151], v[32:47]
	v_mfma_f32_32x32x16_bf16 v[0:15], v[170:173], v[136:139], v[0:15]
	v_mfma_f32_32x32x16_bf16 v[32:47], v[170:173], v[152:155], v[32:47]
	v_mfma_f32_32x32x16_bf16 v[0:15], v[174:177], v[140:143], v[0:15]
	v_mfma_f32_32x32x16_bf16 v[32:47], v[174:177], v[156:159], v[32:47]
	s_setprio 0
	s_barrier
	s_add_u32 m0, s14, 0x18080
	ds_read_b128 v[224:227], v212 offset:8192
	global_load_lds_dwordx4 v240, s[24:25] offset:-128
	s_add_u32 m0, s14, 0x18480
	ds_read_b128 v[228:231], v213 offset:8192
	global_load_lds_dwordx4 v241, s[24:25] offset:-128
	s_add_u32 m0, s14, 0x1a080
	ds_read_b128 v[232:235], v214 offset:8192
	global_load_lds_dwordx4 v242, s[24:25] offset:-128
	s_add_u32 m0, s14, 0x1a480
	ds_read_b128 v[236:239], v215 offset:8192
	global_load_lds_dwordx4 v243, s[24:25] offset:-128
	s_add_u32 m0, s14, 0x8000
	s_nop 0
	global_load_lds_dwordx4 v240, s[24:25]
	s_add_u32 m0, s14, 0x8400
	s_nop 0
	global_load_lds_dwordx4 v241, s[24:25]
	s_barrier
	s_waitcnt lgkmcnt(0)
	s_setprio 1
	v_mfma_f32_32x32x16_bf16 v[16:31], v[224:227], v[128:131], 0
	v_mfma_f32_32x32x16_bf16 v[48:63], v[224:227], v[144:147], 0
	v_mfma_f32_32x32x16_bf16 v[16:31], v[228:231], v[132:135], v[16:31]
	v_mfma_f32_32x32x16_bf16 v[48:63], v[228:231], v[148:151], v[48:63]
	v_mfma_f32_32x32x16_bf16 v[16:31], v[232:235], v[136:139], v[16:31]
	v_mfma_f32_32x32x16_bf16 v[48:63], v[232:235], v[152:155], v[48:63]
	v_mfma_f32_32x32x16_bf16 v[16:31], v[236:239], v[140:143], v[16:31]
	v_mfma_f32_32x32x16_bf16 v[48:63], v[236:239], v[156:159], v[48:63]
	s_setprio 0
	s_barrier
	s_add_u32 m0, s14, 0x0
	ds_read_b128 v[128:131], v204 offset:8192
	ds_read_b128 v[132:135], v205 offset:8192
	global_load_lds_dwordx4 v220, s[22:23]
	s_add_u32 m0, s14, 0x400
	ds_read_b128 v[136:139], v206 offset:8192
	ds_read_b128 v[140:143], v207 offset:8192
	global_load_lds_dwordx4 v221, s[22:23]
	ds_read_b128 v[144:147], v204 offset:12288
	ds_read_b128 v[148:151], v205 offset:12288
	ds_read_b128 v[152:155], v206 offset:12288
	ds_read_b128 v[156:159], v207 offset:12288
	s_barrier
	s_waitcnt lgkmcnt(0)
	s_setprio 1
	v_mfma_f32_32x32x16_bf16 v[64:79], v[162:165], v[128:131], 0
	v_mfma_f32_32x32x16_bf16 v[96:111], v[162:165], v[144:147], 0
	v_mfma_f32_32x32x16_bf16 v[64:79], v[166:169], v[132:135], v[64:79]
	v_mfma_f32_32x32x16_bf16 v[96:111], v[166:169], v[148:151], v[96:111]
	v_mfma_f32_32x32x16_bf16 v[64:79], v[170:173], v[136:139], v[64:79]
	v_mfma_f32_32x32x16_bf16 v[96:111], v[170:173], v[152:155], v[96:111]
	v_mfma_f32_32x32x16_bf16 v[64:79], v[174:177], v[140:143], v[64:79]
	v_mfma_f32_32x32x16_bf16 v[96:111], v[174:177], v[156:159], v[96:111]
	s_setprio 0
	s_barrier
	s_add_u32 m0, s14, 0xa000
	s_nop 0
	global_load_lds_dwordx4 v242, s[24:25]
	s_add_u32 m0, s14, 0xa400
	s_nop 0
	global_load_lds_dwordx4 v243, s[24:25]
	s_waitcnt vmcnt(6)
	s_barrier
	s_setprio 1
	v_mfma_f32_32x32x16_bf16 v[80:95], v[224:227], v[128:131], 0
	v_mfma_f32_32x32x16_bf16 v[112:127], v[224:227], v[144:147], 0
	v_mfma_f32_32x32x16_bf16 v[80:95], v[228:231], v[132:135], v[80:95]
	v_mfma_f32_32x32x16_bf16 v[112:127], v[228:231], v[148:151], v[112:127]
	v_mfma_f32_32x32x16_bf16 v[80:95], v[232:235], v[136:139], v[80:95]
	v_mfma_f32_32x32x16_bf16 v[112:127], v[232:235], v[152:155], v[112:127]
	v_mfma_f32_32x32x16_bf16 v[80:95], v[236:239], v[140:143], v[80:95]
	v_mfma_f32_32x32x16_bf16 v[112:127], v[236:239], v[156:159], v[112:127]
	s_setprio 0
	s_barrier
	s_add_u32 m0, s14, 0x2000
	ds_read_b128 v[162:165], v216
	ds_read_b128 v[166:169], v217
	ds_read_b128 v[170:173], v218
	ds_read_b128 v[174:177], v219
	global_load_lds_dwordx4 v222, s[22:23]
	s_add_u32 m0, s14, 0x2400
	ds_read_b128 v[128:131], v208
	ds_read_b128 v[132:135], v209
	ds_read_b128 v[136:139], v210
	ds_read_b128 v[140:143], v211
	global_load_lds_dwordx4 v223, s[22:23]
	ds_read_b128 v[144:147], v208 offset:4096
	ds_read_b128 v[148:151], v209 offset:4096
	ds_read_b128 v[152:155], v210 offset:4096
	ds_read_b128 v[156:159], v211 offset:4096
	s_add_u32 s22, s22, 0x80
	s_addc_u32 s23, s23, 0
	s_add_u32 s24, s24, 0x80
	s_addc_u32 s25, s25, 0
	s_add_u32 s26, s26, 1
	s_cmp_eq_u32 s26, 16
	s_cbranch_scc0 .Lri3_cadv_done
	s_mov_b32 s26, 0
	s_add_u32 s27, s27, s30
	s_cmp_lt_u32 s27, 0xa0
	s_cbranch_scc1 .Lri3_cadv_new
	s_sub_u32 s22, s22, 0x800
	s_subb_u32 s23, s23, 0
	s_sub_u32 s24, s24, 0x800
	s_subb_u32 s25, s25, 0
	s_branch .Lri3_cadv_done

.Lri_pair:
	s_add_u32 m0, s14, 0x12000
	ds_read_b128 v[162:165], v212
	ds_read_b128 v[166:169], v213
	ds_read_b128 v[170:173], v214
	ds_read_b128 v[174:177], v215
	global_load_lds_dwordx4 v222, s[22:23]
	s_add_u32 m0, s14, 0x12400
	ds_read_b128 v[128:131], v204
	ds_read_b128 v[132:135], v205
	ds_read_b128 v[136:139], v206
	ds_read_b128 v[140:143], v207
	global_load_lds_dwordx4 v223, s[22:23]
	ds_read_b128 v[144:147], v204 offset:4096
	ds_read_b128 v[148:151], v205 offset:4096
	ds_read_b128 v[152:155], v206 offset:4096
	ds_read_b128 v[156:159], v207 offset:4096
	s_add_u32 s22, s22, 0x80
	s_addc_u32 s23, s23, 0
	s_add_u32 s24, s24, 0x80
	s_addc_u32 s25, s25, 0
	s_add_u32 s26, s26, 1
	s_cmp_eq_u32 s26, 16
	s_cbranch_scc0 .Lri4_cadv_done
	s_mov_b32 s26, 0
	s_add_u32 s27, s27, s30
	s_cmp_lt_u32 s27, 0xa0
	s_cbranch_scc1 .Lri4_cadv_new
	s_sub_u32 s22, s22, 0x800
	s_subb_u32 s23, s23, 0
	s_sub_u32 s24, s24, 0x800
	s_subb_u32 s25, s25, 0
	s_branch .Lri4_cadv_done

; #define RAWBAR() { asm volatile("s_waitcnt vmcnt(0) lgkmcnt(0)" ::: "memory"); __builtin_amdgcn_s_barrier(); }
;     ...
;   if (V != 1) GLDS(0, 0);
;   RAWBAR();
;   for (int kt = 0; kt < nk; kt += 2) {
;     if (V != 1) GLDS(kt + 1, 1);
;     if (V != 2) COMPUTE(0);
;     RAWBAR();
;     if (V != 1) if (kt + 2 < nk) GLDS(kt + 2, 0);
;     if (V != 2) COMPUTE(1);
;     RAWBAR();
;   }
.Lri4_cadv_done:
	s_waitcnt lgkmcnt(8)
	s_barrier
	s_waitcnt lgkmcnt(0)
	s_setprio 1
	v_mfma_f32_32x32x16_bf16 v[0:15], v[162:165], v[128:131], v[0:15]
	v_mfma_f32_32x32x16_bf16 v[32:47], v[162:165], v[144:147], v[32:47]
	v_mfma_f32_32x32x16_bf16 v[0:15], v[166:169], v[132:135], v[0:15]
	v_mfma_f32_32x32x16_bf16 v[32:47], v[166:169], v[148:151], v[32:47]
	v_mfma_f32_32x32x16_bf16 v[0:15], v[170:173], v[136:139], v[0:15]
	v_mfma_f32_32x32x16_bf16 v[32:47], v[170:173], v[152:155], v[32:47]
	v_mfma_f32_32x32x16_bf16 v[0:15], v[174:177], v[140:143], v[0:15]
	v_mfma_f32_32x32x16_bf16 v[32:47], v[174:177], v[156:159], v[32:47]
	s_setprio 0
	s_barrier
	s_add_u32 m0, s14, 0x8000
	ds_read_b128 v[224:227], v212 offset:8192
	global_load_lds_dwordx4 v240, s[24:25]
	s_add_u32 m0, s14, 0x8400
	ds_read_b128 v[228:231], v213 offset:8192
	global_load_lds_dwordx4 v241, s[24:25]
	ds_read_b128 v[232:235], v214 offset:8192
	ds_read_b128 v[236:239], v215 offset:8192
	s_barrier
	s_waitcnt lgkmcnt(0)
	s_setprio 1
	v_mfma_f32_32x32x16_bf16 v[16:31], v[224:227], v[128:131], v[16:31]
	v_mfma_f32_32x32x16_bf16 v[48:63], v[224:227], v[144:147], v[48:63]
	v_mfma_f32_32x32x16_bf16 v[16:31], v[228:231], v[132:135], v[16:31]
	v_mfma_f32_32x32x16_bf16 v[48:63], v[228:231], v[148:151], v[48:63]
	v_mfma_f32_32x32x16_bf16 v[16:31], v[232:235], v[136:139], v[16:31]
	v_mfma_f32_32x32x16_bf16 v[48:63], v[232:235], v[152:155], v[48:63]
	v_mfma_f32_32x32x16_bf16 v[16:31], v[236:239], v[140:143], v[16:31]
	v_mfma_f32_32x32x16_bf16 v[48:63], v[236:239], v[156:159], v[48:63]
	s_setprio 0
	s_barrier
	s_add_u32 m0, s14, 0x0
	ds_read_b128 v[128:131], v204 offset:8192
	ds_read_b128 v[132:135], v205 offset:8192
	global_load_lds_dwordx4 v220, s[22:23]
	s_add_u32 m0, s14, 0x400
	ds_read_b128 v[136:139], v206 offset:8192
	ds_read_b128 v[140:143], v207 offset:8192
	global_load_lds_dwordx4 v221, s[22:23]
	ds_read_b128 v[144:147], v204 offset:12288
	ds_read_b128 v[148:151], v205 offset:12288
	ds_read_b128 v[152:155], v206 offset:12288
	ds_read_b128 v[156:159], v207 offset:12288
	s_barrier
	s_waitcnt lgkmcnt(0)
	s_setprio 1
	v_mfma_f32_32x32x16_bf16 v[64:79], v[162:165], v[128:131], v[64:79]
	v_mfma_f32_32x32x16_bf16 v[96:111], v[162:165], v[144:147], v[96:111]
	v_mfma_f32_32x32x16_bf16 v[64:79], v[166:169], v[132:135], v[64:79]
	v_mfma_f32_32x32x16_bf16 v[96:111], v[166:169], v[148:151], v[96:111]
	v_mfma_f32_32x32x16_bf16 v[64:79], v[170:173], v[136:139], v[64:79]
	v_mfma_f32_32x32x16_bf16 v[96:111], v[170:173], v[152:155], v[96:111]
	v_mfma_f32_32x32x16_bf16 v[64:79], v[174:177], v[140:143], v[64:79]
	v_mfma_f32_32x32x16_bf16 v[96:111], v[174:177], v[156:159], v[96:111]
	s_setprio 0
	s_barrier
	s_add_u32 m0, s14, 0xa000
	s_nop 0
	global_load_lds_dwordx4 v242, s[24:25]
	s_add_u32 m0, s14, 0xa400
	s_nop 0
	global_load_lds_dwordx4 v243, s[24:25]
	s_waitcnt vmcnt(6)
	s_barrier
	s_setprio 1
	v_mfma_f32_32x32x16_bf16 v[80:95], v[224:227], v[128:131], v[80:95]
	v_mfma_f32_32x32x16_bf16 v[112:127], v[224:227], v[144:147], v[112:127]
	v_mfma_f32_32x32x16_bf16 v[80:95], v[228:231], v[132:135], v[80:95]
	v_mfma_f32_32x32x16_bf16 v[112:127], v[228:231], v[148:151], v[112:127]
	v_mfma_f32_32x32x16_bf16 v[80:95], v[232:235], v[136:139], v[80:95]
	v_mfma_f32_32x32x16_bf16 v[112:127], v[232:235], v[152:155], v[112:127]
	v_mfma_f32_32x32x16_bf16 v[80:95], v[236:239], v[140:143], v[80:95]
	v_mfma_f32_32x32x16_bf16 v[112:127], v[236:239], v[156:159], v[112:127]
	s_setprio 0
	s_barrier
	s_add_u32 m0, s14, 0x2000
	ds_read_b128 v[162:165], v216
	ds_read_b128 v[166:169], v217
	ds_read_b128 v[170:173], v218
	ds_read_b128 v[174:177], v219
	global_load_lds_dwordx4 v222, s[22:23]
	s_add_u32 m0, s14, 0x2400
	ds_read_b128 v[128:131], v208
	ds_read_b128 v[132:135], v209
	ds_read_b128 v[136:139], v210
	ds_read_b128 v[140:143], v211
	global_load_lds_dwordx4 v223, s[22:23]
	ds_read_b128 v[144:147], v208 offset:4096
	ds_read_b128 v[148:151], v209 offset:4096
	ds_read_b128 v[152:155], v210 offset:4096
	ds_read_b128 v[156:159], v211 offset:4096
	s_add_u32 s22, s22, 0x80
	s_addc_u32 s23, s23, 0
	s_add_u32 s24, s24, 0x80
	s_addc_u32 s25, s25, 0
	s_add_u32 s26, s26, 1
	s_cmp_eq_u32 s26, 16
	s_cbranch_scc0 .Lri5_cadv_done
	s_mov_b32 s26, 0
	s_add_u32 s27, s27, s30
	s_cmp_lt_u32 s27, 0xa0
	s_cbranch_scc1 .Lri5_cadv_new
	s_sub_u32 s22, s22, 0x800
	s_subb_u32 s23, s23, 0
	s_sub_u32 s24, s24, 0x800
	s_subb_u32 s25, s25, 0
	s_branch .Lri5_cadv_done

; DI int crow(int r, int hf) { return (r & 3) + 8 * (r >> 2) + 4 * hf; }
; #define RAWBAR() { asm volatile("s_waitcnt vmcnt(0) lgkmcnt(0)" ::: "memory"); __builtin_amdgcn_s_barrier(); }
;     ...
;   for (int kt = 0; kt < nk; kt += 2) {
;     if (V != 1) GLDS(kt + 1, 1);
;     if (V != 2) COMPUTE(0);
;     RAWBAR();
;     if (V != 1) if (kt + 2 < nk) GLDS(kt + 2, 0);
;     if (V != 2) COMPUTE(1);
;     RAWBAR();
;   }
; DI void rec_in_phase(const Params& p, int j, char* smem) {
;     ...
;       const int C64 = n0 + wn * 64;
; #pragma unroll
;       for (int i = 0; i < 2; ++i) {
;         const int rb = m0_ + wm * 64 + i * 32;
;         if (C64 < 1024) {
;           const int fi = ((C64 & 127) >> 1) + l32_, cbase = C64 & ~127;
;           const float sc = (C64 >= 512) ? RET_KSCALE : 1.f;
; #pragma unroll
;           for (int r = 0; r < 16; ++r) {
;             const int t = rb + crow(r, hf_), pos = t & (S_ - 1);
;             const float2 cs = rt128[pos * 64 + fi];
;             const float x1 = acc[i][0][r], x2 = acc[i][1][r];
;             zr[(size_t)t * LDZR + cbase + fi] = f2bf((x1 * cs.x - x2 * cs.y) * sc);
;             zr[(size_t)t * LDZR + cbase + 64 + fi] = f2bf((x2 * cs.x + x1 * cs.y) * sc);
;           }
;         } else if (C64 < 2048) {
; #pragma unroll
;           for (int jn = 0; jn < 2; ++jn)
; #pragma unroll
;             for (int r = 0; r < 16; ++r) zr[(size_t)(rb + crow(r, hf_)) * LDZR + C64 + jn * 32 + l32_] = f2bf(acc[i][jn][r]);
;         } else {
.Lri7_cadv_done:
	s_waitcnt lgkmcnt(8)
	s_barrier
	s_waitcnt lgkmcnt(0)
	s_setprio 1
	v_mfma_f32_32x32x16_bf16 v[0:15], v[162:165], v[128:131], v[0:15]
	v_mfma_f32_32x32x16_bf16 v[32:47], v[162:165], v[144:147], v[32:47]
	v_mfma_f32_32x32x16_bf16 v[0:15], v[166:169], v[132:135], v[0:15]
	v_mfma_f32_32x32x16_bf16 v[32:47], v[166:169], v[148:151], v[32:47]
	v_mfma_f32_32x32x16_bf16 v[0:15], v[170:173], v[136:139], v[0:15]
	v_mfma_f32_32x32x16_bf16 v[32:47], v[170:173], v[152:155], v[32:47]
	v_mfma_f32_32x32x16_bf16 v[0:15], v[174:177], v[140:143], v[0:15]
	v_mfma_f32_32x32x16_bf16 v[32:47], v[174:177], v[156:159], v[32:47]
	s_setprio 0
	s_barrier
	ds_read_b128 v[224:227], v216 offset:8192
	ds_read_b128 v[228:231], v217 offset:8192
	ds_read_b128 v[232:235], v218 offset:8192
	ds_read_b128 v[236:239], v219 offset:8192
	s_barrier
	s_waitcnt lgkmcnt(0)
	s_setprio 1
	v_mfma_f32_32x32x16_bf16 v[16:31], v[224:227], v[128:131], v[16:31]
	v_mfma_f32_32x32x16_bf16 v[48:63], v[224:227], v[144:147], v[48:63]
	v_mfma_f32_32x32x16_bf16 v[16:31], v[228:231], v[132:135], v[16:31]
	v_mfma_f32_32x32x16_bf16 v[48:63], v[228:231], v[148:151], v[48:63]
	v_mfma_f32_32x32x16_bf16 v[16:31], v[232:235], v[136:139], v[16:31]
	v_mfma_f32_32x32x16_bf16 v[48:63], v[232:235], v[152:155], v[48:63]
	v_mfma_f32_32x32x16_bf16 v[16:31], v[236:239], v[140:143], v[16:31]
	v_mfma_f32_32x32x16_bf16 v[48:63], v[236:239], v[156:159], v[48:63]
	s_setprio 0
	s_barrier
	s_add_u32 m0, s14, 0x10000
	ds_read_b128 v[128:131], v208 offset:8192
	ds_read_b128 v[132:135], v209 offset:8192
	global_load_lds_dwordx4 v220, s[22:23]
	s_add_u32 m0, s14, 0x10400
	ds_read_b128 v[136:139], v210 offset:8192
	ds_read_b128 v[140:143], v211 offset:8192
	global_load_lds_dwordx4 v221, s[22:23]
	ds_read_b128 v[144:147], v208 offset:12288
	ds_read_b128 v[148:151], v209 offset:12288
	ds_read_b128 v[152:155], v210 offset:12288
	ds_read_b128 v[156:159], v211 offset:12288
	s_barrier
	s_waitcnt lgkmcnt(0)
	s_setprio 1
	v_mfma_f32_32x32x16_bf16 v[64:79], v[162:165], v[128:131], v[64:79]
	v_mfma_f32_32x32x16_bf16 v[96:111], v[162:165], v[144:147], v[96:111]
	v_mfma_f32_32x32x16_bf16 v[64:79], v[166:169], v[132:135], v[64:79]
	v_mfma_f32_32x32x16_bf16 v[96:111], v[166:169], v[148:151], v[96:111]
	v_mfma_f32_32x32x16_bf16 v[64:79], v[170:173], v[136:139], v[64:79]
	v_mfma_f32_32x32x16_bf16 v[96:111], v[170:173], v[152:155], v[96:111]
	v_mfma_f32_32x32x16_bf16 v[64:79], v[174:177], v[140:143], v[64:79]
	v_mfma_f32_32x32x16_bf16 v[96:111], v[174:177], v[156:159], v[96:111]
	s_setprio 0
	s_barrier
	s_waitcnt vmcnt(2)
	s_barrier
	s_setprio 1
	v_mfma_f32_32x32x16_bf16 v[80:95], v[224:227], v[128:131], v[80:95]
	v_mfma_f32_32x32x16_bf16 v[112:127], v[224:227], v[144:147], v[112:127]
	v_mfma_f32_32x32x16_bf16 v[80:95], v[228:231], v[132:135], v[80:95]
	v_mfma_f32_32x32x16_bf16 v[112:127], v[228:231], v[148:151], v[112:127]
	v_mfma_f32_32x32x16_bf16 v[80:95], v[232:235], v[136:139], v[80:95]
	v_mfma_f32_32x32x16_bf16 v[112:127], v[232:235], v[152:155], v[112:127]
	v_mfma_f32_32x32x16_bf16 v[80:95], v[236:239], v[140:143], v[80:95]
	v_mfma_f32_32x32x16_bf16 v[112:127], v[236:239], v[156:159], v[112:127]
	s_setprio 0
	s_barrier
	s_lshr_b32 s20, s28, 5
	s_lshl_b32 s20, s20, 1
	s_and_b32 s8, s28, 1
	s_add_u32 s20, s20, s8
	s_lshl_b32 s10, s31, 8
	s_add_u32 s10, s10, s12
	s_cmp_lt_u32 s20, 4
	s_cbranch_scc1 .Lri_epi_rope
	s_cmp_lt_u32 s20, 8
	s_cbranch_scc1 .Lri_epi_plain
; DI int crow(int r, int hf) { return (r & 3) + 8 * (r >> 2) + 4 * hf; }
; DI void rec_in_phase(const Params& p, int j, char* smem) {
;     ...
;         } else {
; #pragma unroll
;           for (int jn = 0; jn < 2; ++jn) {
;             const int cl = C64 - 2048 + jn * 32 + l32_, g = cl >> 4, pp = cl & 15;
; #pragma unroll
;             for (int r = 0; r < 16; ++r) ug[((size_t)g * T_ + rb + crow(r, hf_)) * 16 + pp] = f2bf(acc[i][jn][r]);
;           }
;         }
	s_sub_u32 s8, s20, 8
	s_lshl_b32 s8, s8, 4
	s_lshl_b32 s9, s13, 2
	s_add_u32 s8, s8, s9
	s_lshl_b32 s8, s8, 15
	s_add_u32 s8, s8, s10
	s_lshl_b32 s8, s8, 5
	s_add_u32 s38, s4, s8
	s_addc_u32 s39, s5, 0
	s_add_u32 s38, s38, 0x15404100
	s_addc_u32 s39, s39, 0
	v_cvt_pk_bf16_f32 v240, v0, v1
	v_cvt_pk_bf16_f32 v241, v2, v3
	ds_write_b64 v178, v[240:241]
	v_cvt_pk_bf16_f32 v242, v4, v5
	v_cvt_pk_bf16_f32 v243, v6, v7
	ds_write_b64 v179, v[242:243]
	v_cvt_pk_bf16_f32 v244, v8, v9
	v_cvt_pk_bf16_f32 v245, v10, v11
	ds_write_b64 v180, v[244:245]
	v_cvt_pk_bf16_f32 v246, v12, v13
	v_cvt_pk_bf16_f32 v247, v14, v15
	ds_write_b64 v181, v[246:247]
	v_cvt_pk_bf16_f32 v240, v16, v17
	v_cvt_pk_bf16_f32 v241, v18, v19
	ds_write_b64 v188, v[240:241]
	v_cvt_pk_bf16_f32 v242, v20, v21
	v_cvt_pk_bf16_f32 v243, v22, v23
	ds_write_b64 v189, v[242:243]
	v_cvt_pk_bf16_f32 v244, v24, v25
	v_cvt_pk_bf16_f32 v245, v26, v27
	ds_write_b64 v190, v[244:245]
	v_cvt_pk_bf16_f32 v246, v28, v29
	v_cvt_pk_bf16_f32 v247, v30, v31
	ds_write_b64 v191, v[246:247]
	ds_read_b128 v[0:3], v194
	ds_read_b128 v[4:7], v194 offset:1024
	ds_read_b128 v[8:11], v194 offset:2048
	ds_read_b128 v[12:15], v194 offset:3072
	v_cvt_pk_bf16_f32 v240, v32, v33
	v_cvt_pk_bf16_f32 v241, v34, v35
	ds_write_b64 v178, v[240:241]
	v_cvt_pk_bf16_f32 v242, v36, v37
	v_cvt_pk_bf16_f32 v243, v38, v39
	ds_write_b64 v179, v[242:243]
	v_cvt_pk_bf16_f32 v244, v40, v41
	v_cvt_pk_bf16_f32 v245, v42, v43
	ds_write_b64 v180, v[244:245]
	v_cvt_pk_bf16_f32 v246, v44, v45
	v_cvt_pk_bf16_f32 v247, v46, v47
	ds_write_b64 v181, v[246:247]
	v_cvt_pk_bf16_f32 v240, v48, v49
	v_cvt_pk_bf16_f32 v241, v50, v51
	ds_write_b64 v188, v[240:241]
	v_cvt_pk_bf16_f32 v242, v52, v53
	v_cvt_pk_bf16_f32 v243, v54, v55
	ds_write_b64 v189, v[242:243]
	v_cvt_pk_bf16_f32 v244, v56, v57
	v_cvt_pk_bf16_f32 v245, v58, v59
	ds_write_b64 v190, v[244:245]
	v_cvt_pk_bf16_f32 v246, v60, v61
	v_cvt_pk_bf16_f32 v247, v62, v63
	ds_write_b64 v191, v[246:247]
	ds_read_b128 v[32:35], v194
	ds_read_b128 v[36:39], v194 offset:1024
	ds_read_b128 v[40:43], v194 offset:2048
	ds_read_b128 v[44:47], v194 offset:3072
	s_waitcnt lgkmcnt(12)
	global_store_dwordx4 v197, v[0:3], s[38:39] nt
	s_add_u32 s38, s38, 0x100
	s_addc_u32 s39, s39, 0
	global_store_dwordx4 v197, v[4:7], s[38:39] nt
	s_add_u32 s38, s38, 0x100
	s_addc_u32 s39, s39, 0
	global_store_dwordx4 v197, v[8:11], s[38:39] nt
	s_add_u32 s38, s38, 0x100
	s_addc_u32 s39, s39, 0
	global_store_dwordx4 v197, v[12:15], s[38:39] nt
	s_add_u32 s38, s38, 0x100
	s_addc_u32 s39, s39, 0
	v_cvt_pk_bf16_f32 v240, v64, v65
	v_cvt_pk_bf16_f32 v241, v66, v67
	ds_write_b64 v178, v[240:241]
	v_cvt_pk_bf16_f32 v242, v68, v69
	v_cvt_pk_bf16_f32 v243, v70, v71
	ds_write_b64 v179, v[242:243]
	v_cvt_pk_bf16_f32 v244, v72, v73
	v_cvt_pk_bf16_f32 v245, v74, v75
	ds_write_b64 v180, v[244:245]
	v_cvt_pk_bf16_f32 v246, v76, v77
	v_cvt_pk_bf16_f32 v247, v78, v79
	ds_write_b64 v181, v[246:247]
	v_cvt_pk_bf16_f32 v240, v80, v81
	v_cvt_pk_bf16_f32 v241, v82, v83
	ds_write_b64 v188, v[240:241]
	v_cvt_pk_bf16_f32 v242, v84, v85
	v_cvt_pk_bf16_f32 v243, v86, v87
	ds_write_b64 v189, v[242:243]
	v_cvt_pk_bf16_f32 v244, v88, v89
	v_cvt_pk_bf16_f32 v245, v90, v91
	ds_write_b64 v190, v[244:245]
	v_cvt_pk_bf16_f32 v246, v92, v93
	v_cvt_pk_bf16_f32 v247, v94, v95
	ds_write_b64 v191, v[246:247]
	ds_read_b128 v[64:67], v194
	ds_read_b128 v[68:71], v194 offset:1024
	ds_read_b128 v[72:75], v194 offset:2048
	ds_read_b128 v[76:79], v194 offset:3072
	s_waitcnt lgkmcnt(12)
	global_store_dwordx4 v197, v[32:35], s[38:39] nt
	s_add_u32 s38, s38, 0x100
	s_addc_u32 s39, s39, 0
	global_store_dwordx4 v197, v[36:39], s[38:39] nt
	s_add_u32 s38, s38, 0x100
	s_addc_u32 s39, s39, 0
	global_store_dwordx4 v197, v[40:43], s[38:39] nt
	s_add_u32 s38, s38, 0x100
	s_addc_u32 s39, s39, 0
	global_store_dwordx4 v197, v[44:47], s[38:39] nt
	s_add_u32 s38, s38, 0x100
	s_addc_u32 s39, s39, 0
	v_cvt_pk_bf16_f32 v240, v96, v97
	v_cvt_pk_bf16_f32 v241, v98, v99
	ds_write_b64 v178, v[240:241]
	v_cvt_pk_bf16_f32 v242, v100, v101
	v_cvt_pk_bf16_f32 v243, v102, v103
	ds_write_b64 v179, v[242:243]
	v_cvt_pk_bf16_f32 v244, v104, v105
	v_cvt_pk_bf16_f32 v245, v106, v107
	ds_write_b64 v180, v[244:245]
	v_cvt_pk_bf16_f32 v246, v108, v109
	v_cvt_pk_bf16_f32 v247, v110, v111
	ds_write_b64 v181, v[246:247]
	v_cvt_pk_bf16_f32 v240, v112, v113
	v_cvt_pk_bf16_f32 v241, v114, v115
	ds_write_b64 v188, v[240:241]
	v_cvt_pk_bf16_f32 v242, v116, v117
	v_cvt_pk_bf16_f32 v243, v118, v119
	ds_write_b64 v189, v[242:243]
	v_cvt_pk_bf16_f32 v244, v120, v121
	v_cvt_pk_bf16_f32 v245, v122, v123
	ds_write_b64 v190, v[244:245]
	v_cvt_pk_bf16_f32 v246, v124, v125
	v_cvt_pk_bf16_f32 v247, v126, v127
	ds_write_b64 v191, v[246:247]
	ds_read_b128 v[96:99], v194
	ds_read_b128 v[100:103], v194 offset:1024
	ds_read_b128 v[104:107], v194 offset:2048
	ds_read_b128 v[108:111], v194 offset:3072
	s_waitcnt lgkmcnt(12)
	global_store_dwordx4 v197, v[64:67], s[38:39] nt
	s_add_u32 s38, s38, 0x100
	s_addc_u32 s39, s39, 0
	global_store_dwordx4 v197, v[68:71], s[38:39] nt
	s_add_u32 s38, s38, 0x100
	s_addc_u32 s39, s39, 0
	global_store_dwordx4 v197, v[72:75], s[38:39] nt
	s_add_u32 s38, s38, 0x100
	s_addc_u32 s39, s39, 0
	global_store_dwordx4 v197, v[76:79], s[38:39] nt
	s_add_u32 s38, s38, 0x100
	s_addc_u32 s39, s39, 0
	s_waitcnt lgkmcnt(0)
	global_store_dwordx4 v197, v[96:99], s[38:39] nt
	s_add_u32 s38, s38, 0x100
	s_addc_u32 s39, s39, 0
	global_store_dwordx4 v197, v[100:103], s[38:39] nt
	s_add_u32 s38, s38, 0x100
	s_addc_u32 s39, s39, 0
	global_store_dwordx4 v197, v[104:107], s[38:39] nt
	s_add_u32 s38, s38, 0x100
	s_addc_u32 s39, s39, 0
	global_store_dwordx4 v197, v[108:111], s[38:39] nt
	s_branch .Lri_epi_done

; DI int opqv(int x) { asm volatile("" : "+v"(x)); return x; }
; DI char* opq(char* p) { asm volatile("" : "+s"(p)); return p; }
; DI void s5_fill(const Params& p, int j) {
;   const int tid = opqv(threadIdx.x), nb = gridDim.x, bid = blockIdx.x;
;   char* ws = opq(p.ws);
;   const float4* s5z = (const float4*)(ws + OFF_S5Z) + j * 2048; const float2* bbar = (const float2*)(ws + OFF_BBAR) + j * 2048 * 16;
;   const float* ktab = (const float*)(ws + OFF_KTAB) + (size_t)j * 32 * 32 * 256;
;   u16* WE = (u16*)(ws + OFF_WE); u16* WY = (u16*)(ws + OFF_WY);
;   for (int idx = bid * NTHR + tid; idx < 32 * 256 * 512; idx += nb * NTHR) {
;     const int g = idx >> 17, n2 = (idx >> 9) & 255, k = idx & 511, jj = k >> 4, q = k & 15, n = n2 & 63;
;     if (n2 >= 128) { WE[idx] = 0; continue; }
.Lri_epi_done:
	s_waitcnt lgkmcnt(0)
	s_add_u32 s28, s28, s30
	s_cmp_lt_u32 s28, 0xa0
	s_cbranch_scc1 .Lri_tile
	s_waitcnt vmcnt(0) lgkmcnt(0)
	s_cmp_lt_u32 s15, 4
	s_cbranch_scc0 .Lri_pp_trail
	s_barrier
.Lri_pp_trail:
.LBB0_819:
	v_readlane_b32 s4, v251, 9
	v_mov_b32_e32 v9, v182
	v_readlane_b32 s5, v251, 10
	s_load_dword s0, s[4:5], 0x10
	v_readlane_b32 s22, v251, 13
	s_load_dword s4, s[4:5], 0x0
	v_readlane_b32 s23, v251, 14
	s_waitcnt lgkmcnt(0)
	s_lshr_b32 s0, s0, 16
	s_cmp_lg_u32 s0, 0
	s_cselect_b64 s[0:1], -1, 0
	s_cmp_lg_u64 s[0:1], 0
	v_readlane_b32 s0, v254, 25
	s_addc_u32 s34, s4, 0
	v_readlane_b32 s1, v254, 26
	s_lshl_b32 s0, s0, 11
	s_ashr_i32 s1, s0, 31
	s_lshl_b64 s[0:1], s[0:1], 4
	s_add_u32 s0, s22, s0
	s_addc_u32 s1, s23, s1
	s_add_u32 s8, s0, 0xe34100
	v_readlane_b32 s0, v253, 25
	s_addc_u32 s9, s1, 0
	v_and_b32_e32 v8, 15, v9
	v_add_u32_e32 v0, s0, v9
	s_mov_b32 s0, 0x400000
	v_cmp_gt_i32_e32 vcc, s0, v0
	v_ashrrev_i32_e32 v1, 31, v0
	s_and_saveexec_b64 s[10:11], vcc
	s_mov_b32 s35, 0x66666667
	s_cbranch_execz .LBB0_830
	v_readlane_b32 s0, v254, 25
	v_readlane_b32 s1, v254, 26
	s_lshl_b32 s0, s0, 15
	s_ashr_i32 s1, s0, 31
	s_lshl_b64 s[0:1], s[0:1], 3
	s_add_u32 s0, s22, s0
	s_addc_u32 s1, s23, s1
	s_add_u32 s12, s0, 0xe44100
	s_addc_u32 s13, s1, 0
	s_lshl_b32 s14, s34, 9
	v_lshl_add_u64 v[2:3], v[0:1], 1, s[22:23]
	s_mov_b64 s[0:1], 0x7004100
	s_ashr_i32 s15, s14, 31
	v_lshl_add_u64 v[2:3], v[2:3], 0, s[0:1]
	s_lshl_b64 s[24:25], s[14:15], 1
	s_mov_b64 s[26:27], 0
	v_mov_b32_e32 v10, v0
	s_branch .LBB0_822
